# row passes (NORM0 and the POST recompute-h pass) hand-written with two x rows prefetched ahead (3 register buffers), loads of a row issued together
# speedup vs baseline: 1.0097x; 1.0097x over previous
; DI void rows_norm_mod(const P& p, const float* xlat, const float* xctx, int l, const float* gain, int sh_idx, int sc_idx,
;                       h16* dst, int nrows) {
;     ...
;   for (int row = gw; row < nrows; row += nw) {
;     const float* xr = row < TL ? xlat + (size_t)row * 1024 : xctx + (size_t)(row - TL) * 1024;
;     const int mrow = row < TL ? (row >> 12) : 8;
;     const float* mr = mod + ((size_t)l * 9 + mrow) * 6144;
;     f32x4 v[4];
;     float ss = 0.f;
; #pragma unroll
;     for (int i = 0; i < 4; ++i) {
;       v[i] = *(const f32x4*)(xr + lane * 4 + 256 * i);
;       ss += v[i].x * v[i].x + v[i].y * v[i].y + v[i].z * v[i].z + v[i].w * v[i].w;
;     }
;     ss = wave_sum(ss);
;     const float rstd = rsqrtf(ss * (1.f / 1024.f) + EPS);
; #pragma unroll
;     for (int i = 0; i < 4; ++i) {
;       const int c = lane * 4 + 256 * i;
;       f32x4 g = *(const f32x4*)(gain + c), sc = *(const f32x4*)(mr + sc_idx * 1024 + c), sh = *(const f32x4*)(mr + sh_idx * 1024 + c);
;       h16x4 o;
;       o.x = (h16)(v[i].x * rstd * g.x * (1.f + sc.x) + sh.x);
;       o.y = (h16)(v[i].y * rstd * g.y * (1.f + sc.y) + sh.y);
;       o.z = (h16)(v[i].z * rstd * g.z * (1.f + sc.z) + sh.z);
;       o.w = (h16)(v[i].w * rstd * g.w * (1.f + sc.w) + sh.w);
;       *(h16x4*)(dst + (size_t)row * 1024 + c) = o;
;     }
.LBB0_158:
	s_mul_i32 s41, s78, 0x36000
	s_add_u32 s56, s6, s41
	s_addc_u32 s57, s7, 0
	s_add_u32 s58, s48, 0x17cec000
	s_addc_u32 s59, s49, 0
	s_lshl_b32 s41, s78, 12
	s_add_u32 s60, s24, s41
	s_addc_u32 s61, s25, 0
	v_lshrrev_b32_e32 v128, 1, v0
	global_load_dwordx4 v[80:83], v0, s[60:61]
	global_load_dwordx4 v[84:87], v0, s[60:61] offset:1024
	global_load_dwordx4 v[88:91], v0, s[60:61] offset:2048
	global_load_dwordx4 v[92:95], v0, s[60:61] offset:3072
	v_readfirstlane_b32 s40, v22
	s_nop 3
	s_sub_u32 s42, s40, 0x8000
	s_cmp_lt_u32 s40, 0x8000
	s_cselect_b32 s42, s40, s42
	s_cselect_b32 s44, s82, s80
	s_cselect_b32 s45, s83, s81
	s_lshl_b32 s42, s42, 12
	s_add_u32 s44, s44, s42
	s_addc_u32 s45, s45, 0
	global_load_dwordx4 v[2:5], v0, s[44:45]
	global_load_dwordx4 v[6:9], v0, s[44:45] offset:1024
	global_load_dwordx4 v[10:13], v0, s[44:45] offset:2048
	global_load_dwordx4 v[14:17], v0, s[44:45] offset:3072
	s_add_i32 s43, s40, s4
	s_cmp_lt_i32 s43, s36
	s_cbranch_scc0 .Lrnp_pre0
	s_sub_u32 s42, s43, 0x8000
	s_cmp_lt_u32 s43, 0x8000
	s_cselect_b32 s42, s43, s42
	s_cselect_b32 s44, s82, s80
	s_cselect_b32 s45, s83, s81
	s_lshl_b32 s42, s42, 12
	s_add_u32 s44, s44, s42
	s_addc_u32 s45, s45, 0
	global_load_dwordx4 v[32:35], v0, s[44:45]
	global_load_dwordx4 v[36:39], v0, s[44:45] offset:1024
	global_load_dwordx4 v[40:43], v0, s[44:45] offset:2048
	global_load_dwordx4 v[44:47], v0, s[44:45] offset:3072
.Lrnp_pre0:
	s_lshr_b32 s41, s40, 12
	s_cmp_lt_u32 s40, 0x8000
	s_cselect_b32 s41, s41, 8
	s_mul_i32 s41, s41, 0x6000
	s_add_u32 s50, s56, s41
	s_addc_u32 s51, s57, 0
	s_add_u32 s52, s50, 0x1000
	s_addc_u32 s53, s51, 0
	s_lshl_b32 s41, s40, 11
	s_add_u32 s54, s58, s41
	s_addc_u32 s55, s59, 0
	global_load_dwordx4 v[96:99], v0, s[52:53]
	global_load_dwordx4 v[100:103], v0, s[52:53] offset:1024
	global_load_dwordx4 v[104:107], v0, s[52:53] offset:2048
	global_load_dwordx4 v[108:111], v0, s[52:53] offset:3072
	global_load_dwordx4 v[178:181], v0, s[50:51]
	global_load_dwordx4 v[182:185], v0, s[50:51] offset:1024
	global_load_dwordx4 v[186:189], v0, s[50:51] offset:2048
	global_load_dwordx4 v[190:193], v0, s[50:51] offset:3072
	s_add_i32 s46, s40, s4
	s_add_i32 s46, s46, s4
	s_cmp_lt_i32 s46, s36
	s_cbranch_scc0 .Lrnp_tail0
	s_sub_u32 s42, s46, 0x8000
	s_cmp_lt_u32 s46, 0x8000
	s_cselect_b32 s42, s46, s42
	s_cselect_b32 s44, s82, s80
	s_cselect_b32 s45, s83, s81
	s_lshl_b32 s42, s42, 12
	s_add_u32 s44, s44, s42
	s_addc_u32 s45, s45, 0
	global_load_dwordx4 v[162:165], v0, s[44:45]
	global_load_dwordx4 v[166:169], v0, s[44:45] offset:1024
	global_load_dwordx4 v[170:173], v0, s[44:45] offset:2048
	global_load_dwordx4 v[174:177], v0, s[44:45] offset:3072
	s_waitcnt vmcnt(16)
	v_mul_f32_e32 v112, v3, v3
	v_mul_f32_e32 v113, v7, v7
	v_mul_f32_e32 v114, v11, v11
	v_mul_f32_e32 v115, v15, v15
	v_fmac_f32_e32 v112, v2, v2
	v_fmac_f32_e32 v113, v6, v6
	v_fmac_f32_e32 v114, v10, v10
	v_fmac_f32_e32 v115, v14, v14
	v_fmac_f32_e32 v112, v4, v4
	v_fmac_f32_e32 v113, v8, v8
	v_fmac_f32_e32 v114, v12, v12
	v_fmac_f32_e32 v115, v16, v16
	v_fmac_f32_e32 v112, v5, v5
	v_fmac_f32_e32 v113, v9, v9
	v_fmac_f32_e32 v114, v13, v13
	v_fmac_f32_e32 v115, v17, v17
	v_add_f32_e32 v112, v112, v113
	v_add_f32_e32 v112, v112, v114
	v_add_f32_e32 v112, v112, v115
	s_nop 1
	v_add_f32_dpp v112, v112, v112 quad_perm:[1,0,3,2] row_mask:0xf bank_mask:0xf bound_ctrl:1
	s_nop 1
	v_add_f32_dpp v112, v112, v112 quad_perm:[2,3,0,1] row_mask:0xf bank_mask:0xf bound_ctrl:1
	s_nop 1
	v_add_f32_dpp v112, v112, v112 row_half_mirror row_mask:0xf bank_mask:0xf bound_ctrl:1
	s_nop 1
	v_add_f32_dpp v112, v112, v112 row_mirror row_mask:0xf bank_mask:0xf bound_ctrl:1
	s_nop 1
	ds_swizzle_b32 v113, v112 offset:swizzle(SWAP,16)
	s_waitcnt lgkmcnt(0)
	v_add_f32_e32 v112, v112, v113
	v_mov_b32_e32 v113, v112
	s_nop 1
	v_permlane32_swap_b32_e32 v112, v113
	v_add_f32_e32 v112, v112, v113
	v_fmamk_f32 v112, v112, 0x3a800000, v224
	v_rsq_f32_e32 v112, v112
	s_waitcnt vmcnt(4)
	v_mul_f32_e32 v2, v2, v112
	v_mul_f32_e32 v3, v3, v112
	v_mul_f32_e32 v4, v4, v112
	v_mul_f32_e32 v5, v5, v112
	v_mul_f32_e32 v6, v6, v112
	v_mul_f32_e32 v7, v7, v112
	v_mul_f32_e32 v8, v8, v112
	v_mul_f32_e32 v9, v9, v112
	v_mul_f32_e32 v10, v10, v112
	v_mul_f32_e32 v11, v11, v112
	v_mul_f32_e32 v12, v12, v112
	v_mul_f32_e32 v13, v13, v112
	v_mul_f32_e32 v14, v14, v112
	v_mul_f32_e32 v15, v15, v112
	v_mul_f32_e32 v16, v16, v112
	v_mul_f32_e32 v17, v17, v112
	v_mul_f32_e32 v2, v80, v2
	v_mul_f32_e32 v3, v81, v3
	v_mul_f32_e32 v4, v82, v4
	v_mul_f32_e32 v5, v83, v5
	v_mul_f32_e32 v6, v84, v6
	v_mul_f32_e32 v7, v85, v7
	v_mul_f32_e32 v8, v86, v8
	v_mul_f32_e32 v9, v87, v9
	v_mul_f32_e32 v10, v88, v10
	v_mul_f32_e32 v11, v89, v11
	v_mul_f32_e32 v12, v90, v12
	v_mul_f32_e32 v13, v91, v13
	v_mul_f32_e32 v14, v92, v14
	v_mul_f32_e32 v15, v93, v15
	v_mul_f32_e32 v16, v94, v16
	v_mul_f32_e32 v17, v95, v17
	v_add_f32_e32 v96, 1.0, v96
	v_add_f32_e32 v97, 1.0, v97
	v_add_f32_e32 v98, 1.0, v98
	v_add_f32_e32 v99, 1.0, v99
	v_add_f32_e32 v100, 1.0, v100
	v_add_f32_e32 v101, 1.0, v101
	v_add_f32_e32 v102, 1.0, v102
	v_add_f32_e32 v103, 1.0, v103
	v_add_f32_e32 v104, 1.0, v104
	v_add_f32_e32 v105, 1.0, v105
	v_add_f32_e32 v106, 1.0, v106
	v_add_f32_e32 v107, 1.0, v107
	v_add_f32_e32 v108, 1.0, v108
	v_add_f32_e32 v109, 1.0, v109
	v_add_f32_e32 v110, 1.0, v110
	v_add_f32_e32 v111, 1.0, v111
	v_fma_f32 v2, v96, v2, v178
	v_fma_f32 v3, v97, v3, v179
	v_fma_f32 v4, v98, v4, v180
	v_fma_f32 v5, v99, v5, v181
	v_fma_f32 v6, v100, v6, v182
	v_fma_f32 v7, v101, v7, v183
	v_fma_f32 v8, v102, v8, v184
	v_fma_f32 v9, v103, v9, v185
	v_fma_f32 v10, v104, v10, v186
	v_fma_f32 v11, v105, v11, v187
	v_fma_f32 v12, v106, v12, v188
	v_fma_f32 v13, v107, v13, v189
	v_fma_f32 v14, v108, v14, v190
	v_fma_f32 v15, v109, v15, v191
	v_fma_f32 v16, v110, v16, v192
	v_fma_f32 v17, v111, v17, v193
	v_cvt_pk_f16_f32 v114, v2, v3
	v_cvt_pk_f16_f32 v115, v4, v5
	v_cvt_pk_f16_f32 v116, v6, v7
	v_cvt_pk_f16_f32 v117, v8, v9
	v_cvt_pk_f16_f32 v118, v10, v11
	v_cvt_pk_f16_f32 v119, v12, v13
	v_cvt_pk_f16_f32 v120, v14, v15
	v_cvt_pk_f16_f32 v121, v16, v17
	global_store_dwordx2 v128, v[114:115], s[54:55]
	global_store_dwordx2 v128, v[116:117], s[54:55] offset:512
	global_store_dwordx2 v128, v[118:119], s[54:55] offset:1024
	global_store_dwordx2 v128, v[120:121], s[54:55] offset:1536
	s_add_i32 s40, s40, s4
; DI void rows_norm_mod(const P& p, const float* xlat, const float* xctx, int l, const float* gain, int sh_idx, int sc_idx,
;                       h16* dst, int nrows) {
;     ...
;   for (int row = gw; row < nrows; row += nw) {
;     const float* xr = row < TL ? xlat + (size_t)row * 1024 : xctx + (size_t)(row - TL) * 1024;
;     const int mrow = row < TL ? (row >> 12) : 8;
;     const float* mr = mod + ((size_t)l * 9 + mrow) * 6144;
;     f32x4 v[4];
;     float ss = 0.f;
; #pragma unroll
;     for (int i = 0; i < 4; ++i) {
;       v[i] = *(const f32x4*)(xr + lane * 4 + 256 * i);
;       ss += v[i].x * v[i].x + v[i].y * v[i].y + v[i].z * v[i].z + v[i].w * v[i].w;
;     }
;     ss = wave_sum(ss);
;     const float rstd = rsqrtf(ss * (1.f / 1024.f) + EPS);
; #pragma unroll
;     for (int i = 0; i < 4; ++i) {
;       const int c = lane * 4 + 256 * i;
;       f32x4 g = *(const f32x4*)(gain + c), sc = *(const f32x4*)(mr + sc_idx * 1024 + c), sh = *(const f32x4*)(mr + sh_idx * 1024 + c);
;       h16x4 o;
;       o.x = (h16)(v[i].x * rstd * g.x * (1.f + sc.x) + sh.x);
;       o.y = (h16)(v[i].y * rstd * g.y * (1.f + sc.y) + sh.y);
;       o.z = (h16)(v[i].z * rstd * g.z * (1.f + sc.z) + sh.z);
;       o.w = (h16)(v[i].w * rstd * g.w * (1.f + sc.w) + sh.w);
;       *(h16x4*)(dst + (size_t)row * 1024 + c) = o;
;     }
.Lrnp_pre1:
	s_lshr_b32 s41, s40, 12
	s_cmp_lt_u32 s40, 0x8000
	s_cselect_b32 s41, s41, 8
	s_mul_i32 s41, s41, 0x6000
	s_add_u32 s50, s56, s41
	s_addc_u32 s51, s57, 0
	s_add_u32 s52, s50, 0x1000
	s_addc_u32 s53, s51, 0
	s_lshl_b32 s41, s40, 11
	s_add_u32 s54, s58, s41
	s_addc_u32 s55, s59, 0
	global_load_dwordx4 v[96:99], v0, s[52:53]
	global_load_dwordx4 v[100:103], v0, s[52:53] offset:1024
	global_load_dwordx4 v[104:107], v0, s[52:53] offset:2048
	global_load_dwordx4 v[108:111], v0, s[52:53] offset:3072
	global_load_dwordx4 v[178:181], v0, s[50:51]
	global_load_dwordx4 v[182:185], v0, s[50:51] offset:1024
	global_load_dwordx4 v[186:189], v0, s[50:51] offset:2048
	global_load_dwordx4 v[190:193], v0, s[50:51] offset:3072
	s_add_i32 s46, s40, s4
	s_add_i32 s46, s46, s4
	s_cmp_lt_i32 s46, s36
	s_cbranch_scc0 .Lrnp_tail1
	s_sub_u32 s42, s46, 0x8000
	s_cmp_lt_u32 s46, 0x8000
	s_cselect_b32 s42, s46, s42
	s_cselect_b32 s44, s82, s80
	s_cselect_b32 s45, s83, s81
	s_lshl_b32 s42, s42, 12
	s_add_u32 s44, s44, s42
	s_addc_u32 s45, s45, 0
	global_load_dwordx4 v[2:5], v0, s[44:45]
	global_load_dwordx4 v[6:9], v0, s[44:45] offset:1024
	global_load_dwordx4 v[10:13], v0, s[44:45] offset:2048
	global_load_dwordx4 v[14:17], v0, s[44:45] offset:3072
	s_waitcnt vmcnt(16)
	v_mul_f32_e32 v112, v33, v33
	v_mul_f32_e32 v113, v37, v37
	v_mul_f32_e32 v114, v41, v41
	v_mul_f32_e32 v115, v45, v45
	v_fmac_f32_e32 v112, v32, v32
	v_fmac_f32_e32 v113, v36, v36
	v_fmac_f32_e32 v114, v40, v40
	v_fmac_f32_e32 v115, v44, v44
	v_fmac_f32_e32 v112, v34, v34
	v_fmac_f32_e32 v113, v38, v38
	v_fmac_f32_e32 v114, v42, v42
	v_fmac_f32_e32 v115, v46, v46
	v_fmac_f32_e32 v112, v35, v35
	v_fmac_f32_e32 v113, v39, v39
	v_fmac_f32_e32 v114, v43, v43
	v_fmac_f32_e32 v115, v47, v47
	v_add_f32_e32 v112, v112, v113
	v_add_f32_e32 v112, v112, v114
	v_add_f32_e32 v112, v112, v115
	s_nop 1
	v_add_f32_dpp v112, v112, v112 quad_perm:[1,0,3,2] row_mask:0xf bank_mask:0xf bound_ctrl:1
	s_nop 1
	v_add_f32_dpp v112, v112, v112 quad_perm:[2,3,0,1] row_mask:0xf bank_mask:0xf bound_ctrl:1
	s_nop 1
	v_add_f32_dpp v112, v112, v112 row_half_mirror row_mask:0xf bank_mask:0xf bound_ctrl:1
	s_nop 1
	v_add_f32_dpp v112, v112, v112 row_mirror row_mask:0xf bank_mask:0xf bound_ctrl:1
	s_nop 1
	ds_swizzle_b32 v113, v112 offset:swizzle(SWAP,16)
	s_waitcnt lgkmcnt(0)
	v_add_f32_e32 v112, v112, v113
	v_mov_b32_e32 v113, v112
	s_nop 1
	v_permlane32_swap_b32_e32 v112, v113
	v_add_f32_e32 v112, v112, v113
	v_fmamk_f32 v112, v112, 0x3a800000, v224
	v_rsq_f32_e32 v112, v112
	s_waitcnt vmcnt(4)
	v_mul_f32_e32 v32, v32, v112
	v_mul_f32_e32 v33, v33, v112
	v_mul_f32_e32 v34, v34, v112
	v_mul_f32_e32 v35, v35, v112
	v_mul_f32_e32 v36, v36, v112
	v_mul_f32_e32 v37, v37, v112
	v_mul_f32_e32 v38, v38, v112
	v_mul_f32_e32 v39, v39, v112
	v_mul_f32_e32 v40, v40, v112
	v_mul_f32_e32 v41, v41, v112
	v_mul_f32_e32 v42, v42, v112
	v_mul_f32_e32 v43, v43, v112
	v_mul_f32_e32 v44, v44, v112
	v_mul_f32_e32 v45, v45, v112
	v_mul_f32_e32 v46, v46, v112
	v_mul_f32_e32 v47, v47, v112
	v_mul_f32_e32 v32, v80, v32
	v_mul_f32_e32 v33, v81, v33
	v_mul_f32_e32 v34, v82, v34
	v_mul_f32_e32 v35, v83, v35
	v_mul_f32_e32 v36, v84, v36
	v_mul_f32_e32 v37, v85, v37
	v_mul_f32_e32 v38, v86, v38
	v_mul_f32_e32 v39, v87, v39
	v_mul_f32_e32 v40, v88, v40
	v_mul_f32_e32 v41, v89, v41
	v_mul_f32_e32 v42, v90, v42
	v_mul_f32_e32 v43, v91, v43
	v_mul_f32_e32 v44, v92, v44
	v_mul_f32_e32 v45, v93, v45
	v_mul_f32_e32 v46, v94, v46
	v_mul_f32_e32 v47, v95, v47
	v_add_f32_e32 v96, 1.0, v96
	v_add_f32_e32 v97, 1.0, v97
	v_add_f32_e32 v98, 1.0, v98
	v_add_f32_e32 v99, 1.0, v99
	v_add_f32_e32 v100, 1.0, v100
	v_add_f32_e32 v101, 1.0, v101
	v_add_f32_e32 v102, 1.0, v102
	v_add_f32_e32 v103, 1.0, v103
	v_add_f32_e32 v104, 1.0, v104
	v_add_f32_e32 v105, 1.0, v105
	v_add_f32_e32 v106, 1.0, v106
	v_add_f32_e32 v107, 1.0, v107
	v_add_f32_e32 v108, 1.0, v108
	v_add_f32_e32 v109, 1.0, v109
	v_add_f32_e32 v110, 1.0, v110
	v_add_f32_e32 v111, 1.0, v111
	v_fma_f32 v32, v96, v32, v178
	v_fma_f32 v33, v97, v33, v179
	v_fma_f32 v34, v98, v34, v180
	v_fma_f32 v35, v99, v35, v181
	v_fma_f32 v36, v100, v36, v182
	v_fma_f32 v37, v101, v37, v183
	v_fma_f32 v38, v102, v38, v184
	v_fma_f32 v39, v103, v39, v185
	v_fma_f32 v40, v104, v40, v186
	v_fma_f32 v41, v105, v41, v187
	v_fma_f32 v42, v106, v42, v188
	v_fma_f32 v43, v107, v43, v189
	v_fma_f32 v44, v108, v44, v190
	v_fma_f32 v45, v109, v45, v191
	v_fma_f32 v46, v110, v46, v192
	v_fma_f32 v47, v111, v47, v193
	v_cvt_pk_f16_f32 v114, v32, v33
	v_cvt_pk_f16_f32 v115, v34, v35
	v_cvt_pk_f16_f32 v116, v36, v37
	v_cvt_pk_f16_f32 v117, v38, v39
	v_cvt_pk_f16_f32 v118, v40, v41
	v_cvt_pk_f16_f32 v119, v42, v43
	v_cvt_pk_f16_f32 v120, v44, v45
	v_cvt_pk_f16_f32 v121, v46, v47
	global_store_dwordx2 v128, v[114:115], s[54:55]
	global_store_dwordx2 v128, v[116:117], s[54:55] offset:512
	global_store_dwordx2 v128, v[118:119], s[54:55] offset:1024
	global_store_dwordx2 v128, v[120:121], s[54:55] offset:1536
	s_add_i32 s40, s40, s4
; DI void rows_norm_mod(const P& p, const float* xlat, const float* xctx, int l, const float* gain, int sh_idx, int sc_idx,
;                       h16* dst, int nrows) {
;     ...
;   for (int row = gw; row < nrows; row += nw) {
;     const float* xr = row < TL ? xlat + (size_t)row * 1024 : xctx + (size_t)(row - TL) * 1024;
;     const int mrow = row < TL ? (row >> 12) : 8;
;     const float* mr = mod + ((size_t)l * 9 + mrow) * 6144;
;     f32x4 v[4];
;     float ss = 0.f;
; #pragma unroll
;     for (int i = 0; i < 4; ++i) {
;       v[i] = *(const f32x4*)(xr + lane * 4 + 256 * i);
;       ss += v[i].x * v[i].x + v[i].y * v[i].y + v[i].z * v[i].z + v[i].w * v[i].w;
;     }
;     ss = wave_sum(ss);
;     const float rstd = rsqrtf(ss * (1.f / 1024.f) + EPS);
; #pragma unroll
;     for (int i = 0; i < 4; ++i) {
;       const int c = lane * 4 + 256 * i;
;       f32x4 g = *(const f32x4*)(gain + c), sc = *(const f32x4*)(mr + sc_idx * 1024 + c), sh = *(const f32x4*)(mr + sh_idx * 1024 + c);
;       h16x4 o;
;       o.x = (h16)(v[i].x * rstd * g.x * (1.f + sc.x) + sh.x);
;       o.y = (h16)(v[i].y * rstd * g.y * (1.f + sc.y) + sh.y);
;       o.z = (h16)(v[i].z * rstd * g.z * (1.f + sc.z) + sh.z);
;       o.w = (h16)(v[i].w * rstd * g.w * (1.f + sc.w) + sh.w);
;       *(h16x4*)(dst + (size_t)row * 1024 + c) = o;
;     }
.Lrnp_l2:
	s_lshr_b32 s41, s40, 12
	s_cmp_lt_u32 s40, 0x8000
	s_cselect_b32 s41, s41, 8
	s_mul_i32 s41, s41, 0x6000
	s_add_u32 s50, s56, s41
	s_addc_u32 s51, s57, 0
	s_add_u32 s52, s50, 0x1000
	s_addc_u32 s53, s51, 0
	s_lshl_b32 s41, s40, 11
	s_add_u32 s54, s58, s41
	s_addc_u32 s55, s59, 0
	global_load_dwordx4 v[96:99], v0, s[52:53]
	global_load_dwordx4 v[100:103], v0, s[52:53] offset:1024
	global_load_dwordx4 v[104:107], v0, s[52:53] offset:2048
	global_load_dwordx4 v[108:111], v0, s[52:53] offset:3072
	global_load_dwordx4 v[178:181], v0, s[50:51]
	global_load_dwordx4 v[182:185], v0, s[50:51] offset:1024
	global_load_dwordx4 v[186:189], v0, s[50:51] offset:2048
	global_load_dwordx4 v[190:193], v0, s[50:51] offset:3072
	s_add_i32 s46, s40, s4
	s_add_i32 s46, s46, s4
	s_cmp_lt_i32 s46, s36
	s_cbranch_scc0 .Lrnp_tail2
	s_sub_u32 s42, s46, 0x8000
	s_cmp_lt_u32 s46, 0x8000
	s_cselect_b32 s42, s46, s42
	s_cselect_b32 s44, s82, s80
	s_cselect_b32 s45, s83, s81
	s_lshl_b32 s42, s42, 12
	s_add_u32 s44, s44, s42
	s_addc_u32 s45, s45, 0
	global_load_dwordx4 v[32:35], v0, s[44:45]
	global_load_dwordx4 v[36:39], v0, s[44:45] offset:1024
	global_load_dwordx4 v[40:43], v0, s[44:45] offset:2048
	global_load_dwordx4 v[44:47], v0, s[44:45] offset:3072
	s_waitcnt vmcnt(32)
	v_mul_f32_e32 v112, v163, v163
	v_mul_f32_e32 v113, v167, v167
	v_mul_f32_e32 v114, v171, v171
	v_mul_f32_e32 v115, v175, v175
	v_fmac_f32_e32 v112, v162, v162
	v_fmac_f32_e32 v113, v166, v166
	v_fmac_f32_e32 v114, v170, v170
	v_fmac_f32_e32 v115, v174, v174
	v_fmac_f32_e32 v112, v164, v164
	v_fmac_f32_e32 v113, v168, v168
	v_fmac_f32_e32 v114, v172, v172
	v_fmac_f32_e32 v115, v176, v176
	v_fmac_f32_e32 v112, v165, v165
	v_fmac_f32_e32 v113, v169, v169
	v_fmac_f32_e32 v114, v173, v173
	v_fmac_f32_e32 v115, v177, v177
	v_add_f32_e32 v112, v112, v113
	v_add_f32_e32 v112, v112, v114
	v_add_f32_e32 v112, v112, v115
	s_nop 1
	v_add_f32_dpp v112, v112, v112 quad_perm:[1,0,3,2] row_mask:0xf bank_mask:0xf bound_ctrl:1
	s_nop 1
	v_add_f32_dpp v112, v112, v112 quad_perm:[2,3,0,1] row_mask:0xf bank_mask:0xf bound_ctrl:1
	s_nop 1
	v_add_f32_dpp v112, v112, v112 row_half_mirror row_mask:0xf bank_mask:0xf bound_ctrl:1
	s_nop 1
	v_add_f32_dpp v112, v112, v112 row_mirror row_mask:0xf bank_mask:0xf bound_ctrl:1
	s_nop 1
	ds_swizzle_b32 v113, v112 offset:swizzle(SWAP,16)
	s_waitcnt lgkmcnt(0)
	v_add_f32_e32 v112, v112, v113
	v_mov_b32_e32 v113, v112
	s_nop 1
	v_permlane32_swap_b32_e32 v112, v113
	v_add_f32_e32 v112, v112, v113
	v_fmamk_f32 v112, v112, 0x3a800000, v224
	v_rsq_f32_e32 v112, v112
	s_waitcnt vmcnt(4)
	v_mul_f32_e32 v162, v162, v112
	v_mul_f32_e32 v163, v163, v112
	v_mul_f32_e32 v164, v164, v112
	v_mul_f32_e32 v165, v165, v112
	v_mul_f32_e32 v166, v166, v112
	v_mul_f32_e32 v167, v167, v112
	v_mul_f32_e32 v168, v168, v112
	v_mul_f32_e32 v169, v169, v112
	v_mul_f32_e32 v170, v170, v112
	v_mul_f32_e32 v171, v171, v112
	v_mul_f32_e32 v172, v172, v112
	v_mul_f32_e32 v173, v173, v112
	v_mul_f32_e32 v174, v174, v112
	v_mul_f32_e32 v175, v175, v112
	v_mul_f32_e32 v176, v176, v112
	v_mul_f32_e32 v177, v177, v112
	v_mul_f32_e32 v162, v80, v162
	v_mul_f32_e32 v163, v81, v163
	v_mul_f32_e32 v164, v82, v164
	v_mul_f32_e32 v165, v83, v165
	v_mul_f32_e32 v166, v84, v166
	v_mul_f32_e32 v167, v85, v167
	v_mul_f32_e32 v168, v86, v168
	v_mul_f32_e32 v169, v87, v169
	v_mul_f32_e32 v170, v88, v170
	v_mul_f32_e32 v171, v89, v171
	v_mul_f32_e32 v172, v90, v172
	v_mul_f32_e32 v173, v91, v173
	v_mul_f32_e32 v174, v92, v174
	v_mul_f32_e32 v175, v93, v175
	v_mul_f32_e32 v176, v94, v176
	v_mul_f32_e32 v177, v95, v177
	v_add_f32_e32 v96, 1.0, v96
	v_add_f32_e32 v97, 1.0, v97
	v_add_f32_e32 v98, 1.0, v98
	v_add_f32_e32 v99, 1.0, v99
	v_add_f32_e32 v100, 1.0, v100
	v_add_f32_e32 v101, 1.0, v101
	v_add_f32_e32 v102, 1.0, v102
	v_add_f32_e32 v103, 1.0, v103
	v_add_f32_e32 v104, 1.0, v104
	v_add_f32_e32 v105, 1.0, v105
	v_add_f32_e32 v106, 1.0, v106
	v_add_f32_e32 v107, 1.0, v107
	v_add_f32_e32 v108, 1.0, v108
	v_add_f32_e32 v109, 1.0, v109
	v_add_f32_e32 v110, 1.0, v110
	v_add_f32_e32 v111, 1.0, v111
	v_fma_f32 v162, v96, v162, v178
	v_fma_f32 v163, v97, v163, v179
	v_fma_f32 v164, v98, v164, v180
	v_fma_f32 v165, v99, v165, v181
	v_fma_f32 v166, v100, v166, v182
	v_fma_f32 v167, v101, v167, v183
	v_fma_f32 v168, v102, v168, v184
	v_fma_f32 v169, v103, v169, v185
	v_fma_f32 v170, v104, v170, v186
	v_fma_f32 v171, v105, v171, v187
	v_fma_f32 v172, v106, v172, v188
	v_fma_f32 v173, v107, v173, v189
	v_fma_f32 v174, v108, v174, v190
	v_fma_f32 v175, v109, v175, v191
	v_fma_f32 v176, v110, v176, v192
	v_fma_f32 v177, v111, v177, v193
	v_cvt_pk_f16_f32 v114, v162, v163
	v_cvt_pk_f16_f32 v115, v164, v165
	v_cvt_pk_f16_f32 v116, v166, v167
	v_cvt_pk_f16_f32 v117, v168, v169
	v_cvt_pk_f16_f32 v118, v170, v171
	v_cvt_pk_f16_f32 v119, v172, v173
	v_cvt_pk_f16_f32 v120, v174, v175
	v_cvt_pk_f16_f32 v121, v176, v177
	global_store_dwordx2 v128, v[114:115], s[54:55]
	global_store_dwordx2 v128, v[116:117], s[54:55] offset:512
	global_store_dwordx2 v128, v[118:119], s[54:55] offset:1024
	global_store_dwordx2 v128, v[120:121], s[54:55] offset:1536
	s_add_i32 s40, s40, s4
; DI void rows_norm_mod(const P& p, const float* xlat, const float* xctx, int l, const float* gain, int sh_idx, int sc_idx,
;                       h16* dst, int nrows) {
;     ...
;   for (int row = gw; row < nrows; row += nw) {
;     const float* xr = row < TL ? xlat + (size_t)row * 1024 : xctx + (size_t)(row - TL) * 1024;
;     const int mrow = row < TL ? (row >> 12) : 8;
;     const float* mr = mod + ((size_t)l * 9 + mrow) * 6144;
;     f32x4 v[4];
;     float ss = 0.f;
; #pragma unroll
;     for (int i = 0; i < 4; ++i) {
;       v[i] = *(const f32x4*)(xr + lane * 4 + 256 * i);
;       ss += v[i].x * v[i].x + v[i].y * v[i].y + v[i].z * v[i].z + v[i].w * v[i].w;
;     }
;     ss = wave_sum(ss);
;     const float rstd = rsqrtf(ss * (1.f / 1024.f) + EPS);
; #pragma unroll
;     for (int i = 0; i < 4; ++i) {
;       const int c = lane * 4 + 256 * i;
;       f32x4 g = *(const f32x4*)(gain + c), sc = *(const f32x4*)(mr + sc_idx * 1024 + c), sh = *(const f32x4*)(mr + sh_idx * 1024 + c);
;       h16x4 o;
;       o.x = (h16)(v[i].x * rstd * g.x * (1.f + sc.x) + sh.x);
;       o.y = (h16)(v[i].y * rstd * g.y * (1.f + sc.y) + sh.y);
;       o.z = (h16)(v[i].z * rstd * g.z * (1.f + sc.z) + sh.z);
;       o.w = (h16)(v[i].w * rstd * g.w * (1.f + sc.w) + sh.w);
;       *(h16x4*)(dst + (size_t)row * 1024 + c) = o;
;     }
.Lrnp_l0:
	s_lshr_b32 s41, s40, 12
	s_cmp_lt_u32 s40, 0x8000
	s_cselect_b32 s41, s41, 8
	s_mul_i32 s41, s41, 0x6000
	s_add_u32 s50, s56, s41
	s_addc_u32 s51, s57, 0
	s_add_u32 s52, s50, 0x1000
	s_addc_u32 s53, s51, 0
	s_lshl_b32 s41, s40, 11
	s_add_u32 s54, s58, s41
	s_addc_u32 s55, s59, 0
	global_load_dwordx4 v[96:99], v0, s[52:53]
	global_load_dwordx4 v[100:103], v0, s[52:53] offset:1024
	global_load_dwordx4 v[104:107], v0, s[52:53] offset:2048
	global_load_dwordx4 v[108:111], v0, s[52:53] offset:3072
	global_load_dwordx4 v[178:181], v0, s[50:51]
	global_load_dwordx4 v[182:185], v0, s[50:51] offset:1024
	global_load_dwordx4 v[186:189], v0, s[50:51] offset:2048
	global_load_dwordx4 v[190:193], v0, s[50:51] offset:3072
	s_add_i32 s46, s40, s4
	s_add_i32 s46, s46, s4
	s_cmp_lt_i32 s46, s36
	s_cbranch_scc0 .Lrnp_tail0
	s_sub_u32 s42, s46, 0x8000
	s_cmp_lt_u32 s46, 0x8000
	s_cselect_b32 s42, s46, s42
	s_cselect_b32 s44, s82, s80
	s_cselect_b32 s45, s83, s81
	s_lshl_b32 s42, s42, 12
	s_add_u32 s44, s44, s42
	s_addc_u32 s45, s45, 0
	global_load_dwordx4 v[162:165], v0, s[44:45]
	global_load_dwordx4 v[166:169], v0, s[44:45] offset:1024
	global_load_dwordx4 v[170:173], v0, s[44:45] offset:2048
	global_load_dwordx4 v[174:177], v0, s[44:45] offset:3072
	s_waitcnt vmcnt(32)
	v_mul_f32_e32 v112, v3, v3
	v_mul_f32_e32 v113, v7, v7
	v_mul_f32_e32 v114, v11, v11
	v_mul_f32_e32 v115, v15, v15
	v_fmac_f32_e32 v112, v2, v2
	v_fmac_f32_e32 v113, v6, v6
	v_fmac_f32_e32 v114, v10, v10
	v_fmac_f32_e32 v115, v14, v14
	v_fmac_f32_e32 v112, v4, v4
	v_fmac_f32_e32 v113, v8, v8
	v_fmac_f32_e32 v114, v12, v12
	v_fmac_f32_e32 v115, v16, v16
	v_fmac_f32_e32 v112, v5, v5
	v_fmac_f32_e32 v113, v9, v9
	v_fmac_f32_e32 v114, v13, v13
	v_fmac_f32_e32 v115, v17, v17
	v_add_f32_e32 v112, v112, v113
	v_add_f32_e32 v112, v112, v114
	v_add_f32_e32 v112, v112, v115
	s_nop 1
	v_add_f32_dpp v112, v112, v112 quad_perm:[1,0,3,2] row_mask:0xf bank_mask:0xf bound_ctrl:1
	s_nop 1
	v_add_f32_dpp v112, v112, v112 quad_perm:[2,3,0,1] row_mask:0xf bank_mask:0xf bound_ctrl:1
	s_nop 1
	v_add_f32_dpp v112, v112, v112 row_half_mirror row_mask:0xf bank_mask:0xf bound_ctrl:1
	s_nop 1
	v_add_f32_dpp v112, v112, v112 row_mirror row_mask:0xf bank_mask:0xf bound_ctrl:1
	s_nop 1
	ds_swizzle_b32 v113, v112 offset:swizzle(SWAP,16)
	s_waitcnt lgkmcnt(0)
	v_add_f32_e32 v112, v112, v113
	v_mov_b32_e32 v113, v112
	s_nop 1
	v_permlane32_swap_b32_e32 v112, v113
	v_add_f32_e32 v112, v112, v113
	v_fmamk_f32 v112, v112, 0x3a800000, v224
	v_rsq_f32_e32 v112, v112
	s_waitcnt vmcnt(4)
	v_mul_f32_e32 v2, v2, v112
	v_mul_f32_e32 v3, v3, v112
	v_mul_f32_e32 v4, v4, v112
	v_mul_f32_e32 v5, v5, v112
	v_mul_f32_e32 v6, v6, v112
	v_mul_f32_e32 v7, v7, v112
	v_mul_f32_e32 v8, v8, v112
	v_mul_f32_e32 v9, v9, v112
	v_mul_f32_e32 v10, v10, v112
	v_mul_f32_e32 v11, v11, v112
	v_mul_f32_e32 v12, v12, v112
	v_mul_f32_e32 v13, v13, v112
	v_mul_f32_e32 v14, v14, v112
	v_mul_f32_e32 v15, v15, v112
	v_mul_f32_e32 v16, v16, v112
	v_mul_f32_e32 v17, v17, v112
	v_mul_f32_e32 v2, v80, v2
	v_mul_f32_e32 v3, v81, v3
	v_mul_f32_e32 v4, v82, v4
	v_mul_f32_e32 v5, v83, v5
	v_mul_f32_e32 v6, v84, v6
	v_mul_f32_e32 v7, v85, v7
	v_mul_f32_e32 v8, v86, v8
	v_mul_f32_e32 v9, v87, v9
	v_mul_f32_e32 v10, v88, v10
	v_mul_f32_e32 v11, v89, v11
	v_mul_f32_e32 v12, v90, v12
	v_mul_f32_e32 v13, v91, v13
	v_mul_f32_e32 v14, v92, v14
	v_mul_f32_e32 v15, v93, v15
	v_mul_f32_e32 v16, v94, v16
	v_mul_f32_e32 v17, v95, v17
	v_add_f32_e32 v96, 1.0, v96
	v_add_f32_e32 v97, 1.0, v97
	v_add_f32_e32 v98, 1.0, v98
	v_add_f32_e32 v99, 1.0, v99
	v_add_f32_e32 v100, 1.0, v100
	v_add_f32_e32 v101, 1.0, v101
	v_add_f32_e32 v102, 1.0, v102
	v_add_f32_e32 v103, 1.0, v103
	v_add_f32_e32 v104, 1.0, v104
	v_add_f32_e32 v105, 1.0, v105
	v_add_f32_e32 v106, 1.0, v106
	v_add_f32_e32 v107, 1.0, v107
	v_add_f32_e32 v108, 1.0, v108
	v_add_f32_e32 v109, 1.0, v109
	v_add_f32_e32 v110, 1.0, v110
	v_add_f32_e32 v111, 1.0, v111
	v_fma_f32 v2, v96, v2, v178
	v_fma_f32 v3, v97, v3, v179
	v_fma_f32 v4, v98, v4, v180
	v_fma_f32 v5, v99, v5, v181
	v_fma_f32 v6, v100, v6, v182
	v_fma_f32 v7, v101, v7, v183
	v_fma_f32 v8, v102, v8, v184
	v_fma_f32 v9, v103, v9, v185
	v_fma_f32 v10, v104, v10, v186
	v_fma_f32 v11, v105, v11, v187
	v_fma_f32 v12, v106, v12, v188
	v_fma_f32 v13, v107, v13, v189
	v_fma_f32 v14, v108, v14, v190
	v_fma_f32 v15, v109, v15, v191
	v_fma_f32 v16, v110, v16, v192
	v_fma_f32 v17, v111, v17, v193
	v_cvt_pk_f16_f32 v114, v2, v3
	v_cvt_pk_f16_f32 v115, v4, v5
	v_cvt_pk_f16_f32 v116, v6, v7
	v_cvt_pk_f16_f32 v117, v8, v9
	v_cvt_pk_f16_f32 v118, v10, v11
	v_cvt_pk_f16_f32 v119, v12, v13
	v_cvt_pk_f16_f32 v120, v14, v15
	v_cvt_pk_f16_f32 v121, v16, v17
	global_store_dwordx2 v128, v[114:115], s[54:55]
	global_store_dwordx2 v128, v[116:117], s[54:55] offset:512
	global_store_dwordx2 v128, v[118:119], s[54:55] offset:1024
	global_store_dwordx2 v128, v[120:121], s[54:55] offset:1536
	s_add_i32 s40, s40, s4
; DI void rows_norm_mod(const P& p, const float* xlat, const float* xctx, int l, const float* gain, int sh_idx, int sc_idx,
;                       h16* dst, int nrows) {
;     ...
;   for (int row = gw; row < nrows; row += nw) {
;     const float* xr = row < TL ? xlat + (size_t)row * 1024 : xctx + (size_t)(row - TL) * 1024;
;     const int mrow = row < TL ? (row >> 12) : 8;
;     const float* mr = mod + ((size_t)l * 9 + mrow) * 6144;
;     f32x4 v[4];
;     float ss = 0.f;
; #pragma unroll
;     for (int i = 0; i < 4; ++i) {
;       v[i] = *(const f32x4*)(xr + lane * 4 + 256 * i);
;       ss += v[i].x * v[i].x + v[i].y * v[i].y + v[i].z * v[i].z + v[i].w * v[i].w;
;     }
;     ss = wave_sum(ss);
;     const float rstd = rsqrtf(ss * (1.f / 1024.f) + EPS);
; #pragma unroll
;     for (int i = 0; i < 4; ++i) {
;       const int c = lane * 4 + 256 * i;
;       f32x4 g = *(const f32x4*)(gain + c), sc = *(const f32x4*)(mr + sc_idx * 1024 + c), sh = *(const f32x4*)(mr + sh_idx * 1024 + c);
;       h16x4 o;
;       o.x = (h16)(v[i].x * rstd * g.x * (1.f + sc.x) + sh.x);
;       o.y = (h16)(v[i].y * rstd * g.y * (1.f + sc.y) + sh.y);
;       o.z = (h16)(v[i].z * rstd * g.z * (1.f + sc.z) + sh.z);
;       o.w = (h16)(v[i].w * rstd * g.w * (1.f + sc.w) + sh.w);
;       *(h16x4*)(dst + (size_t)row * 1024 + c) = o;
;     }
.Lrnp_l1:
	s_lshr_b32 s41, s40, 12
	s_cmp_lt_u32 s40, 0x8000
	s_cselect_b32 s41, s41, 8
	s_mul_i32 s41, s41, 0x6000
	s_add_u32 s50, s56, s41
	s_addc_u32 s51, s57, 0
	s_add_u32 s52, s50, 0x1000
	s_addc_u32 s53, s51, 0
	s_lshl_b32 s41, s40, 11
	s_add_u32 s54, s58, s41
	s_addc_u32 s55, s59, 0
	global_load_dwordx4 v[96:99], v0, s[52:53]
	global_load_dwordx4 v[100:103], v0, s[52:53] offset:1024
	global_load_dwordx4 v[104:107], v0, s[52:53] offset:2048
	global_load_dwordx4 v[108:111], v0, s[52:53] offset:3072
	global_load_dwordx4 v[178:181], v0, s[50:51]
	global_load_dwordx4 v[182:185], v0, s[50:51] offset:1024
	global_load_dwordx4 v[186:189], v0, s[50:51] offset:2048
	global_load_dwordx4 v[190:193], v0, s[50:51] offset:3072
	s_add_i32 s46, s40, s4
	s_add_i32 s46, s46, s4
	s_cmp_lt_i32 s46, s36
	s_cbranch_scc0 .Lrnp_tail1
	s_sub_u32 s42, s46, 0x8000
	s_cmp_lt_u32 s46, 0x8000
	s_cselect_b32 s42, s46, s42
	s_cselect_b32 s44, s82, s80
	s_cselect_b32 s45, s83, s81
	s_lshl_b32 s42, s42, 12
	s_add_u32 s44, s44, s42
	s_addc_u32 s45, s45, 0
	global_load_dwordx4 v[2:5], v0, s[44:45]
	global_load_dwordx4 v[6:9], v0, s[44:45] offset:1024
	global_load_dwordx4 v[10:13], v0, s[44:45] offset:2048
	global_load_dwordx4 v[14:17], v0, s[44:45] offset:3072
	s_waitcnt vmcnt(32)
	v_mul_f32_e32 v112, v33, v33
	v_mul_f32_e32 v113, v37, v37
	v_mul_f32_e32 v114, v41, v41
	v_mul_f32_e32 v115, v45, v45
	v_fmac_f32_e32 v112, v32, v32
	v_fmac_f32_e32 v113, v36, v36
	v_fmac_f32_e32 v114, v40, v40
	v_fmac_f32_e32 v115, v44, v44
	v_fmac_f32_e32 v112, v34, v34
	v_fmac_f32_e32 v113, v38, v38
	v_fmac_f32_e32 v114, v42, v42
	v_fmac_f32_e32 v115, v46, v46
	v_fmac_f32_e32 v112, v35, v35
	v_fmac_f32_e32 v113, v39, v39
	v_fmac_f32_e32 v114, v43, v43
	v_fmac_f32_e32 v115, v47, v47
	v_add_f32_e32 v112, v112, v113
	v_add_f32_e32 v112, v112, v114
	v_add_f32_e32 v112, v112, v115
	s_nop 1
	v_add_f32_dpp v112, v112, v112 quad_perm:[1,0,3,2] row_mask:0xf bank_mask:0xf bound_ctrl:1
	s_nop 1
	v_add_f32_dpp v112, v112, v112 quad_perm:[2,3,0,1] row_mask:0xf bank_mask:0xf bound_ctrl:1
	s_nop 1
	v_add_f32_dpp v112, v112, v112 row_half_mirror row_mask:0xf bank_mask:0xf bound_ctrl:1
	s_nop 1
	v_add_f32_dpp v112, v112, v112 row_mirror row_mask:0xf bank_mask:0xf bound_ctrl:1
	s_nop 1
	ds_swizzle_b32 v113, v112 offset:swizzle(SWAP,16)
	s_waitcnt lgkmcnt(0)
	v_add_f32_e32 v112, v112, v113
	v_mov_b32_e32 v113, v112
	s_nop 1
	v_permlane32_swap_b32_e32 v112, v113
	v_add_f32_e32 v112, v112, v113
	v_fmamk_f32 v112, v112, 0x3a800000, v224
	v_rsq_f32_e32 v112, v112
	s_waitcnt vmcnt(4)
	v_mul_f32_e32 v32, v32, v112
	v_mul_f32_e32 v33, v33, v112
	v_mul_f32_e32 v34, v34, v112
	v_mul_f32_e32 v35, v35, v112
	v_mul_f32_e32 v36, v36, v112
	v_mul_f32_e32 v37, v37, v112
	v_mul_f32_e32 v38, v38, v112
	v_mul_f32_e32 v39, v39, v112
	v_mul_f32_e32 v40, v40, v112
	v_mul_f32_e32 v41, v41, v112
	v_mul_f32_e32 v42, v42, v112
	v_mul_f32_e32 v43, v43, v112
	v_mul_f32_e32 v44, v44, v112
	v_mul_f32_e32 v45, v45, v112
	v_mul_f32_e32 v46, v46, v112
	v_mul_f32_e32 v47, v47, v112
	v_mul_f32_e32 v32, v80, v32
	v_mul_f32_e32 v33, v81, v33
	v_mul_f32_e32 v34, v82, v34
	v_mul_f32_e32 v35, v83, v35
	v_mul_f32_e32 v36, v84, v36
	v_mul_f32_e32 v37, v85, v37
	v_mul_f32_e32 v38, v86, v38
	v_mul_f32_e32 v39, v87, v39
	v_mul_f32_e32 v40, v88, v40
	v_mul_f32_e32 v41, v89, v41
	v_mul_f32_e32 v42, v90, v42
	v_mul_f32_e32 v43, v91, v43
	v_mul_f32_e32 v44, v92, v44
	v_mul_f32_e32 v45, v93, v45
	v_mul_f32_e32 v46, v94, v46
	v_mul_f32_e32 v47, v95, v47
	v_add_f32_e32 v96, 1.0, v96
	v_add_f32_e32 v97, 1.0, v97
	v_add_f32_e32 v98, 1.0, v98
	v_add_f32_e32 v99, 1.0, v99
	v_add_f32_e32 v100, 1.0, v100
	v_add_f32_e32 v101, 1.0, v101
	v_add_f32_e32 v102, 1.0, v102
	v_add_f32_e32 v103, 1.0, v103
	v_add_f32_e32 v104, 1.0, v104
	v_add_f32_e32 v105, 1.0, v105
	v_add_f32_e32 v106, 1.0, v106
	v_add_f32_e32 v107, 1.0, v107
	v_add_f32_e32 v108, 1.0, v108
	v_add_f32_e32 v109, 1.0, v109
	v_add_f32_e32 v110, 1.0, v110
	v_add_f32_e32 v111, 1.0, v111
	v_fma_f32 v32, v96, v32, v178
	v_fma_f32 v33, v97, v33, v179
	v_fma_f32 v34, v98, v34, v180
	v_fma_f32 v35, v99, v35, v181
	v_fma_f32 v36, v100, v36, v182
	v_fma_f32 v37, v101, v37, v183
	v_fma_f32 v38, v102, v38, v184
	v_fma_f32 v39, v103, v39, v185
	v_fma_f32 v40, v104, v40, v186
	v_fma_f32 v41, v105, v41, v187
	v_fma_f32 v42, v106, v42, v188
	v_fma_f32 v43, v107, v43, v189
	v_fma_f32 v44, v108, v44, v190
	v_fma_f32 v45, v109, v45, v191
	v_fma_f32 v46, v110, v46, v192
	v_fma_f32 v47, v111, v47, v193
	v_cvt_pk_f16_f32 v114, v32, v33
	v_cvt_pk_f16_f32 v115, v34, v35
	v_cvt_pk_f16_f32 v116, v36, v37
	v_cvt_pk_f16_f32 v117, v38, v39
	v_cvt_pk_f16_f32 v118, v40, v41
	v_cvt_pk_f16_f32 v119, v42, v43
	v_cvt_pk_f16_f32 v120, v44, v45
	v_cvt_pk_f16_f32 v121, v46, v47
	global_store_dwordx2 v128, v[114:115], s[54:55]
	global_store_dwordx2 v128, v[116:117], s[54:55] offset:512
	global_store_dwordx2 v128, v[118:119], s[54:55] offset:1024
	global_store_dwordx2 v128, v[120:121], s[54:55] offset:1536
	s_add_i32 s40, s40, s4
	s_branch .Lrnp_l2
; DI void rows_norm_mod(const P& p, const float* xlat, const float* xctx, int l, const float* gain, int sh_idx, int sc_idx,
;                       h16* dst, int nrows) {
;     ...
;   for (int row = gw; row < nrows; row += nw) {
;     const float* xr = row < TL ? xlat + (size_t)row * 1024 : xctx + (size_t)(row - TL) * 1024;
;     const int mrow = row < TL ? (row >> 12) : 8;
;     const float* mr = mod + ((size_t)l * 9 + mrow) * 6144;
;     f32x4 v[4];
;     float ss = 0.f;
; #pragma unroll
;     for (int i = 0; i < 4; ++i) {
;       v[i] = *(const f32x4*)(xr + lane * 4 + 256 * i);
;       ss += v[i].x * v[i].x + v[i].y * v[i].y + v[i].z * v[i].z + v[i].w * v[i].w;
;     }
;     ss = wave_sum(ss);
;     const float rstd = rsqrtf(ss * (1.f / 1024.f) + EPS);
; #pragma unroll
;     for (int i = 0; i < 4; ++i) {
;       const int c = lane * 4 + 256 * i;
;       f32x4 g = *(const f32x4*)(gain + c), sc = *(const f32x4*)(mr + sc_idx * 1024 + c), sh = *(const f32x4*)(mr + sh_idx * 1024 + c);
;       h16x4 o;
;       o.x = (h16)(v[i].x * rstd * g.x * (1.f + sc.x) + sh.x);
;       o.y = (h16)(v[i].y * rstd * g.y * (1.f + sc.y) + sh.y);
;       o.z = (h16)(v[i].z * rstd * g.z * (1.f + sc.z) + sh.z);
;       o.w = (h16)(v[i].w * rstd * g.w * (1.f + sc.w) + sh.w);
;       *(h16x4*)(dst + (size_t)row * 1024 + c) = o;
;     }
.Lrnp_tail0:
	s_waitcnt vmcnt(8)
	v_mul_f32_e32 v112, v3, v3
	v_mul_f32_e32 v113, v7, v7
	v_mul_f32_e32 v114, v11, v11
	v_mul_f32_e32 v115, v15, v15
	v_fmac_f32_e32 v112, v2, v2
	v_fmac_f32_e32 v113, v6, v6
	v_fmac_f32_e32 v114, v10, v10
	v_fmac_f32_e32 v115, v14, v14
	v_fmac_f32_e32 v112, v4, v4
	v_fmac_f32_e32 v113, v8, v8
	v_fmac_f32_e32 v114, v12, v12
	v_fmac_f32_e32 v115, v16, v16
	v_fmac_f32_e32 v112, v5, v5
	v_fmac_f32_e32 v113, v9, v9
	v_fmac_f32_e32 v114, v13, v13
	v_fmac_f32_e32 v115, v17, v17
	v_add_f32_e32 v112, v112, v113
	v_add_f32_e32 v112, v112, v114
	v_add_f32_e32 v112, v112, v115
	s_nop 1
	v_add_f32_dpp v112, v112, v112 quad_perm:[1,0,3,2] row_mask:0xf bank_mask:0xf bound_ctrl:1
	s_nop 1
	v_add_f32_dpp v112, v112, v112 quad_perm:[2,3,0,1] row_mask:0xf bank_mask:0xf bound_ctrl:1
	s_nop 1
	v_add_f32_dpp v112, v112, v112 row_half_mirror row_mask:0xf bank_mask:0xf bound_ctrl:1
	s_nop 1
	v_add_f32_dpp v112, v112, v112 row_mirror row_mask:0xf bank_mask:0xf bound_ctrl:1
	s_nop 1
	ds_swizzle_b32 v113, v112 offset:swizzle(SWAP,16)
	s_waitcnt lgkmcnt(0)
	v_add_f32_e32 v112, v112, v113
	v_mov_b32_e32 v113, v112
	s_nop 1
	v_permlane32_swap_b32_e32 v112, v113
	v_add_f32_e32 v112, v112, v113
	v_fmamk_f32 v112, v112, 0x3a800000, v224
	v_rsq_f32_e32 v112, v112
	s_waitcnt vmcnt(0)
	v_mul_f32_e32 v2, v2, v112
	v_mul_f32_e32 v3, v3, v112
	v_mul_f32_e32 v4, v4, v112
	v_mul_f32_e32 v5, v5, v112
	v_mul_f32_e32 v6, v6, v112
	v_mul_f32_e32 v7, v7, v112
	v_mul_f32_e32 v8, v8, v112
	v_mul_f32_e32 v9, v9, v112
	v_mul_f32_e32 v10, v10, v112
	v_mul_f32_e32 v11, v11, v112
	v_mul_f32_e32 v12, v12, v112
	v_mul_f32_e32 v13, v13, v112
	v_mul_f32_e32 v14, v14, v112
	v_mul_f32_e32 v15, v15, v112
	v_mul_f32_e32 v16, v16, v112
	v_mul_f32_e32 v17, v17, v112
	v_mul_f32_e32 v2, v80, v2
	v_mul_f32_e32 v3, v81, v3
	v_mul_f32_e32 v4, v82, v4
	v_mul_f32_e32 v5, v83, v5
	v_mul_f32_e32 v6, v84, v6
	v_mul_f32_e32 v7, v85, v7
	v_mul_f32_e32 v8, v86, v8
	v_mul_f32_e32 v9, v87, v9
	v_mul_f32_e32 v10, v88, v10
	v_mul_f32_e32 v11, v89, v11
	v_mul_f32_e32 v12, v90, v12
	v_mul_f32_e32 v13, v91, v13
	v_mul_f32_e32 v14, v92, v14
	v_mul_f32_e32 v15, v93, v15
	v_mul_f32_e32 v16, v94, v16
	v_mul_f32_e32 v17, v95, v17
	v_add_f32_e32 v96, 1.0, v96
	v_add_f32_e32 v97, 1.0, v97
	v_add_f32_e32 v98, 1.0, v98
	v_add_f32_e32 v99, 1.0, v99
	v_add_f32_e32 v100, 1.0, v100
	v_add_f32_e32 v101, 1.0, v101
	v_add_f32_e32 v102, 1.0, v102
	v_add_f32_e32 v103, 1.0, v103
	v_add_f32_e32 v104, 1.0, v104
	v_add_f32_e32 v105, 1.0, v105
	v_add_f32_e32 v106, 1.0, v106
	v_add_f32_e32 v107, 1.0, v107
	v_add_f32_e32 v108, 1.0, v108
	v_add_f32_e32 v109, 1.0, v109
	v_add_f32_e32 v110, 1.0, v110
	v_add_f32_e32 v111, 1.0, v111
	v_fma_f32 v2, v96, v2, v178
	v_fma_f32 v3, v97, v3, v179
	v_fma_f32 v4, v98, v4, v180
	v_fma_f32 v5, v99, v5, v181
	v_fma_f32 v6, v100, v6, v182
	v_fma_f32 v7, v101, v7, v183
	v_fma_f32 v8, v102, v8, v184
	v_fma_f32 v9, v103, v9, v185
	v_fma_f32 v10, v104, v10, v186
	v_fma_f32 v11, v105, v11, v187
	v_fma_f32 v12, v106, v12, v188
	v_fma_f32 v13, v107, v13, v189
	v_fma_f32 v14, v108, v14, v190
	v_fma_f32 v15, v109, v15, v191
	v_fma_f32 v16, v110, v16, v192
	v_fma_f32 v17, v111, v17, v193
	v_cvt_pk_f16_f32 v114, v2, v3
	v_cvt_pk_f16_f32 v115, v4, v5
	v_cvt_pk_f16_f32 v116, v6, v7
	v_cvt_pk_f16_f32 v117, v8, v9
	v_cvt_pk_f16_f32 v118, v10, v11
	v_cvt_pk_f16_f32 v119, v12, v13
	v_cvt_pk_f16_f32 v120, v14, v15
	v_cvt_pk_f16_f32 v121, v16, v17
	global_store_dwordx2 v128, v[114:115], s[54:55]
	global_store_dwordx2 v128, v[116:117], s[54:55] offset:512
	global_store_dwordx2 v128, v[118:119], s[54:55] offset:1024
	global_store_dwordx2 v128, v[120:121], s[54:55] offset:1536
	s_add_i32 s40, s40, s4
	s_cmp_lt_i32 s40, s36
	s_cbranch_scc0 .Lrnp_exit
	s_lshr_b32 s41, s40, 12
	s_cmp_lt_u32 s40, 0x8000
	s_cselect_b32 s41, s41, 8
	s_mul_i32 s41, s41, 0x6000
	s_add_u32 s50, s56, s41
	s_addc_u32 s51, s57, 0
	s_add_u32 s52, s50, 0x1000
	s_addc_u32 s53, s51, 0
	s_lshl_b32 s41, s40, 11
	s_add_u32 s54, s58, s41
	s_addc_u32 s55, s59, 0
	global_load_dwordx4 v[96:99], v0, s[52:53]
	global_load_dwordx4 v[100:103], v0, s[52:53] offset:1024
	global_load_dwordx4 v[104:107], v0, s[52:53] offset:2048
	global_load_dwordx4 v[108:111], v0, s[52:53] offset:3072
	global_load_dwordx4 v[178:181], v0, s[50:51]
	global_load_dwordx4 v[182:185], v0, s[50:51] offset:1024
	global_load_dwordx4 v[186:189], v0, s[50:51] offset:2048
	global_load_dwordx4 v[190:193], v0, s[50:51] offset:3072
	s_waitcnt vmcnt(8)
	v_mul_f32_e32 v112, v33, v33
	v_mul_f32_e32 v113, v37, v37
	v_mul_f32_e32 v114, v41, v41
	v_mul_f32_e32 v115, v45, v45
	v_fmac_f32_e32 v112, v32, v32
	v_fmac_f32_e32 v113, v36, v36
	v_fmac_f32_e32 v114, v40, v40
	v_fmac_f32_e32 v115, v44, v44
	v_fmac_f32_e32 v112, v34, v34
	v_fmac_f32_e32 v113, v38, v38
	v_fmac_f32_e32 v114, v42, v42
	v_fmac_f32_e32 v115, v46, v46
	v_fmac_f32_e32 v112, v35, v35
	v_fmac_f32_e32 v113, v39, v39
	v_fmac_f32_e32 v114, v43, v43
	v_fmac_f32_e32 v115, v47, v47
	v_add_f32_e32 v112, v112, v113
	v_add_f32_e32 v112, v112, v114
	v_add_f32_e32 v112, v112, v115
	s_nop 1
	v_add_f32_dpp v112, v112, v112 quad_perm:[1,0,3,2] row_mask:0xf bank_mask:0xf bound_ctrl:1
	s_nop 1
	v_add_f32_dpp v112, v112, v112 quad_perm:[2,3,0,1] row_mask:0xf bank_mask:0xf bound_ctrl:1
	s_nop 1
	v_add_f32_dpp v112, v112, v112 row_half_mirror row_mask:0xf bank_mask:0xf bound_ctrl:1
	s_nop 1
	v_add_f32_dpp v112, v112, v112 row_mirror row_mask:0xf bank_mask:0xf bound_ctrl:1
	s_nop 1
	ds_swizzle_b32 v113, v112 offset:swizzle(SWAP,16)
	s_waitcnt lgkmcnt(0)
; DI void rows_norm_mod(const P& p, const float* xlat, const float* xctx, int l, const float* gain, int sh_idx, int sc_idx,
;                       h16* dst, int nrows) {
;     ...
;   for (int row = gw; row < nrows; row += nw) {
;     const float* xr = row < TL ? xlat + (size_t)row * 1024 : xctx + (size_t)(row - TL) * 1024;
;     const int mrow = row < TL ? (row >> 12) : 8;
;     const float* mr = mod + ((size_t)l * 9 + mrow) * 6144;
;     f32x4 v[4];
;     float ss = 0.f;
; #pragma unroll
;     for (int i = 0; i < 4; ++i) {
;       v[i] = *(const f32x4*)(xr + lane * 4 + 256 * i);
;       ss += v[i].x * v[i].x + v[i].y * v[i].y + v[i].z * v[i].z + v[i].w * v[i].w;
;     }
;     ss = wave_sum(ss);
;     const float rstd = rsqrtf(ss * (1.f / 1024.f) + EPS);
; #pragma unroll
;     for (int i = 0; i < 4; ++i) {
;       const int c = lane * 4 + 256 * i;
;       f32x4 g = *(const f32x4*)(gain + c), sc = *(const f32x4*)(mr + sc_idx * 1024 + c), sh = *(const f32x4*)(mr + sh_idx * 1024 + c);
;       h16x4 o;
;       o.x = (h16)(v[i].x * rstd * g.x * (1.f + sc.x) + sh.x);
;       o.y = (h16)(v[i].y * rstd * g.y * (1.f + sc.y) + sh.y);
;       o.z = (h16)(v[i].z * rstd * g.z * (1.f + sc.z) + sh.z);
;       o.w = (h16)(v[i].w * rstd * g.w * (1.f + sc.w) + sh.w);
;       *(h16x4*)(dst + (size_t)row * 1024 + c) = o;
;     }
	v_add_f32_e32 v112, v112, v113
	v_mov_b32_e32 v113, v112
	s_nop 1
	v_permlane32_swap_b32_e32 v112, v113
	v_add_f32_e32 v112, v112, v113
	v_fmamk_f32 v112, v112, 0x3a800000, v224
	v_rsq_f32_e32 v112, v112
	s_waitcnt vmcnt(0)
	v_mul_f32_e32 v32, v32, v112
	v_mul_f32_e32 v33, v33, v112
	v_mul_f32_e32 v34, v34, v112
	v_mul_f32_e32 v35, v35, v112
	v_mul_f32_e32 v36, v36, v112
	v_mul_f32_e32 v37, v37, v112
	v_mul_f32_e32 v38, v38, v112
	v_mul_f32_e32 v39, v39, v112
	v_mul_f32_e32 v40, v40, v112
	v_mul_f32_e32 v41, v41, v112
	v_mul_f32_e32 v42, v42, v112
	v_mul_f32_e32 v43, v43, v112
	v_mul_f32_e32 v44, v44, v112
	v_mul_f32_e32 v45, v45, v112
	v_mul_f32_e32 v46, v46, v112
	v_mul_f32_e32 v47, v47, v112
	v_mul_f32_e32 v32, v80, v32
	v_mul_f32_e32 v33, v81, v33
	v_mul_f32_e32 v34, v82, v34
	v_mul_f32_e32 v35, v83, v35
	v_mul_f32_e32 v36, v84, v36
	v_mul_f32_e32 v37, v85, v37
	v_mul_f32_e32 v38, v86, v38
	v_mul_f32_e32 v39, v87, v39
	v_mul_f32_e32 v40, v88, v40
	v_mul_f32_e32 v41, v89, v41
	v_mul_f32_e32 v42, v90, v42
	v_mul_f32_e32 v43, v91, v43
	v_mul_f32_e32 v44, v92, v44
	v_mul_f32_e32 v45, v93, v45
	v_mul_f32_e32 v46, v94, v46
	v_mul_f32_e32 v47, v95, v47
	v_add_f32_e32 v96, 1.0, v96
	v_add_f32_e32 v97, 1.0, v97
	v_add_f32_e32 v98, 1.0, v98
	v_add_f32_e32 v99, 1.0, v99
	v_add_f32_e32 v100, 1.0, v100
	v_add_f32_e32 v101, 1.0, v101
	v_add_f32_e32 v102, 1.0, v102
	v_add_f32_e32 v103, 1.0, v103
	v_add_f32_e32 v104, 1.0, v104
	v_add_f32_e32 v105, 1.0, v105
	v_add_f32_e32 v106, 1.0, v106
	v_add_f32_e32 v107, 1.0, v107
	v_add_f32_e32 v108, 1.0, v108
	v_add_f32_e32 v109, 1.0, v109
	v_add_f32_e32 v110, 1.0, v110
	v_add_f32_e32 v111, 1.0, v111
	v_fma_f32 v32, v96, v32, v178
	v_fma_f32 v33, v97, v33, v179
	v_fma_f32 v34, v98, v34, v180
	v_fma_f32 v35, v99, v35, v181
	v_fma_f32 v36, v100, v36, v182
	v_fma_f32 v37, v101, v37, v183
	v_fma_f32 v38, v102, v38, v184
	v_fma_f32 v39, v103, v39, v185
	v_fma_f32 v40, v104, v40, v186
	v_fma_f32 v41, v105, v41, v187
	v_fma_f32 v42, v106, v42, v188
	v_fma_f32 v43, v107, v43, v189
	v_fma_f32 v44, v108, v44, v190
	v_fma_f32 v45, v109, v45, v191
	v_fma_f32 v46, v110, v46, v192
	v_fma_f32 v47, v111, v47, v193
	v_cvt_pk_f16_f32 v114, v32, v33
	v_cvt_pk_f16_f32 v115, v34, v35
	v_cvt_pk_f16_f32 v116, v36, v37
	v_cvt_pk_f16_f32 v117, v38, v39
	v_cvt_pk_f16_f32 v118, v40, v41
	v_cvt_pk_f16_f32 v119, v42, v43
	v_cvt_pk_f16_f32 v120, v44, v45
	v_cvt_pk_f16_f32 v121, v46, v47
	global_store_dwordx2 v128, v[114:115], s[54:55]
	global_store_dwordx2 v128, v[116:117], s[54:55] offset:512
	global_store_dwordx2 v128, v[118:119], s[54:55] offset:1024
	global_store_dwordx2 v128, v[120:121], s[54:55] offset:1536
	s_add_i32 s40, s40, s4
	s_branch .Lrnp_exit
.Lrnp_tail1:
	s_waitcnt vmcnt(8)
	v_mul_f32_e32 v112, v33, v33
	v_mul_f32_e32 v113, v37, v37
	v_mul_f32_e32 v114, v41, v41
	v_mul_f32_e32 v115, v45, v45
	v_fmac_f32_e32 v112, v32, v32
	v_fmac_f32_e32 v113, v36, v36
	v_fmac_f32_e32 v114, v40, v40
	v_fmac_f32_e32 v115, v44, v44
	v_fmac_f32_e32 v112, v34, v34
	v_fmac_f32_e32 v113, v38, v38
	v_fmac_f32_e32 v114, v42, v42
	v_fmac_f32_e32 v115, v46, v46
	v_fmac_f32_e32 v112, v35, v35
	v_fmac_f32_e32 v113, v39, v39
	v_fmac_f32_e32 v114, v43, v43
	v_fmac_f32_e32 v115, v47, v47
	v_add_f32_e32 v112, v112, v113
	v_add_f32_e32 v112, v112, v114
	v_add_f32_e32 v112, v112, v115
	s_nop 1
	v_add_f32_dpp v112, v112, v112 quad_perm:[1,0,3,2] row_mask:0xf bank_mask:0xf bound_ctrl:1
	s_nop 1
	v_add_f32_dpp v112, v112, v112 quad_perm:[2,3,0,1] row_mask:0xf bank_mask:0xf bound_ctrl:1
	s_nop 1
	v_add_f32_dpp v112, v112, v112 row_half_mirror row_mask:0xf bank_mask:0xf bound_ctrl:1
	s_nop 1
	v_add_f32_dpp v112, v112, v112 row_mirror row_mask:0xf bank_mask:0xf bound_ctrl:1
	s_nop 1
	ds_swizzle_b32 v113, v112 offset:swizzle(SWAP,16)
	s_waitcnt lgkmcnt(0)
	v_add_f32_e32 v112, v112, v113
	v_mov_b32_e32 v113, v112
	s_nop 1
	v_permlane32_swap_b32_e32 v112, v113
	v_add_f32_e32 v112, v112, v113
	v_fmamk_f32 v112, v112, 0x3a800000, v224
	v_rsq_f32_e32 v112, v112
	s_waitcnt vmcnt(0)
	v_mul_f32_e32 v32, v32, v112
	v_mul_f32_e32 v33, v33, v112
	v_mul_f32_e32 v34, v34, v112
	v_mul_f32_e32 v35, v35, v112
	v_mul_f32_e32 v36, v36, v112
	v_mul_f32_e32 v37, v37, v112
	v_mul_f32_e32 v38, v38, v112
	v_mul_f32_e32 v39, v39, v112
	v_mul_f32_e32 v40, v40, v112
	v_mul_f32_e32 v41, v41, v112
	v_mul_f32_e32 v42, v42, v112
	v_mul_f32_e32 v43, v43, v112
	v_mul_f32_e32 v44, v44, v112
	v_mul_f32_e32 v45, v45, v112
	v_mul_f32_e32 v46, v46, v112
	v_mul_f32_e32 v47, v47, v112
	v_mul_f32_e32 v32, v80, v32
	v_mul_f32_e32 v33, v81, v33
	v_mul_f32_e32 v34, v82, v34
	v_mul_f32_e32 v35, v83, v35
	v_mul_f32_e32 v36, v84, v36
	v_mul_f32_e32 v37, v85, v37
	v_mul_f32_e32 v38, v86, v38
	v_mul_f32_e32 v39, v87, v39
	v_mul_f32_e32 v40, v88, v40
	v_mul_f32_e32 v41, v89, v41
	v_mul_f32_e32 v42, v90, v42
	v_mul_f32_e32 v43, v91, v43
	v_mul_f32_e32 v44, v92, v44
	v_mul_f32_e32 v45, v93, v45
	v_mul_f32_e32 v46, v94, v46
	v_mul_f32_e32 v47, v95, v47
	v_add_f32_e32 v96, 1.0, v96
	v_add_f32_e32 v97, 1.0, v97
	v_add_f32_e32 v98, 1.0, v98
	v_add_f32_e32 v99, 1.0, v99
	v_add_f32_e32 v100, 1.0, v100
	v_add_f32_e32 v101, 1.0, v101
	v_add_f32_e32 v102, 1.0, v102
	v_add_f32_e32 v103, 1.0, v103
	v_add_f32_e32 v104, 1.0, v104
	v_add_f32_e32 v105, 1.0, v105
	v_add_f32_e32 v106, 1.0, v106
	v_add_f32_e32 v107, 1.0, v107
	v_add_f32_e32 v108, 1.0, v108
	v_add_f32_e32 v109, 1.0, v109
	v_add_f32_e32 v110, 1.0, v110
	v_add_f32_e32 v111, 1.0, v111
	v_fma_f32 v32, v96, v32, v178
	v_fma_f32 v33, v97, v33, v179
	v_fma_f32 v34, v98, v34, v180
	v_fma_f32 v35, v99, v35, v181
	v_fma_f32 v36, v100, v36, v182
	v_fma_f32 v37, v101, v37, v183
	v_fma_f32 v38, v102, v38, v184
	v_fma_f32 v39, v103, v39, v185
	v_fma_f32 v40, v104, v40, v186
	v_fma_f32 v41, v105, v41, v187
	v_fma_f32 v42, v106, v42, v188
	v_fma_f32 v43, v107, v43, v189
	v_fma_f32 v44, v108, v44, v190
	v_fma_f32 v45, v109, v45, v191
	v_fma_f32 v46, v110, v46, v192
	v_fma_f32 v47, v111, v47, v193
	v_cvt_pk_f16_f32 v114, v32, v33
	v_cvt_pk_f16_f32 v115, v34, v35
	v_cvt_pk_f16_f32 v116, v36, v37
	v_cvt_pk_f16_f32 v117, v38, v39
	v_cvt_pk_f16_f32 v118, v40, v41
	v_cvt_pk_f16_f32 v119, v42, v43
	v_cvt_pk_f16_f32 v120, v44, v45
	v_cvt_pk_f16_f32 v121, v46, v47
	global_store_dwordx2 v128, v[114:115], s[54:55]
	global_store_dwordx2 v128, v[116:117], s[54:55] offset:512
	global_store_dwordx2 v128, v[118:119], s[54:55] offset:1024
	global_store_dwordx2 v128, v[120:121], s[54:55] offset:1536
	s_add_i32 s40, s40, s4
	s_cmp_lt_i32 s40, s36
	s_cbranch_scc0 .Lrnp_exit
; DI void rows_norm_mod(const P& p, const float* xlat, const float* xctx, int l, const float* gain, int sh_idx, int sc_idx,
;                       h16* dst, int nrows) {
;     ...
;   for (int row = gw; row < nrows; row += nw) {
;     const float* xr = row < TL ? xlat + (size_t)row * 1024 : xctx + (size_t)(row - TL) * 1024;
;     const int mrow = row < TL ? (row >> 12) : 8;
;     const float* mr = mod + ((size_t)l * 9 + mrow) * 6144;
;     f32x4 v[4];
;     float ss = 0.f;
; #pragma unroll
;     for (int i = 0; i < 4; ++i) {
;       v[i] = *(const f32x4*)(xr + lane * 4 + 256 * i);
;       ss += v[i].x * v[i].x + v[i].y * v[i].y + v[i].z * v[i].z + v[i].w * v[i].w;
;     }
;     ss = wave_sum(ss);
;     const float rstd = rsqrtf(ss * (1.f / 1024.f) + EPS);
; #pragma unroll
;     for (int i = 0; i < 4; ++i) {
;       const int c = lane * 4 + 256 * i;
;       f32x4 g = *(const f32x4*)(gain + c), sc = *(const f32x4*)(mr + sc_idx * 1024 + c), sh = *(const f32x4*)(mr + sh_idx * 1024 + c);
;       h16x4 o;
;       o.x = (h16)(v[i].x * rstd * g.x * (1.f + sc.x) + sh.x);
;       o.y = (h16)(v[i].y * rstd * g.y * (1.f + sc.y) + sh.y);
;       o.z = (h16)(v[i].z * rstd * g.z * (1.f + sc.z) + sh.z);
;       o.w = (h16)(v[i].w * rstd * g.w * (1.f + sc.w) + sh.w);
;       *(h16x4*)(dst + (size_t)row * 1024 + c) = o;
;     }
	s_lshr_b32 s41, s40, 12
	s_cmp_lt_u32 s40, 0x8000
	s_cselect_b32 s41, s41, 8
	s_mul_i32 s41, s41, 0x6000
	s_add_u32 s50, s56, s41
	s_addc_u32 s51, s57, 0
	s_add_u32 s52, s50, 0x1000
	s_addc_u32 s53, s51, 0
	s_lshl_b32 s41, s40, 11
	s_add_u32 s54, s58, s41
	s_addc_u32 s55, s59, 0
	global_load_dwordx4 v[96:99], v0, s[52:53]
	global_load_dwordx4 v[100:103], v0, s[52:53] offset:1024
	global_load_dwordx4 v[104:107], v0, s[52:53] offset:2048
	global_load_dwordx4 v[108:111], v0, s[52:53] offset:3072
	global_load_dwordx4 v[178:181], v0, s[50:51]
	global_load_dwordx4 v[182:185], v0, s[50:51] offset:1024
	global_load_dwordx4 v[186:189], v0, s[50:51] offset:2048
	global_load_dwordx4 v[190:193], v0, s[50:51] offset:3072
	s_waitcnt vmcnt(8)
	v_mul_f32_e32 v112, v163, v163
	v_mul_f32_e32 v113, v167, v167
	v_mul_f32_e32 v114, v171, v171
	v_mul_f32_e32 v115, v175, v175
	v_fmac_f32_e32 v112, v162, v162
	v_fmac_f32_e32 v113, v166, v166
	v_fmac_f32_e32 v114, v170, v170
	v_fmac_f32_e32 v115, v174, v174
	v_fmac_f32_e32 v112, v164, v164
	v_fmac_f32_e32 v113, v168, v168
	v_fmac_f32_e32 v114, v172, v172
	v_fmac_f32_e32 v115, v176, v176
	v_fmac_f32_e32 v112, v165, v165
	v_fmac_f32_e32 v113, v169, v169
	v_fmac_f32_e32 v114, v173, v173
	v_fmac_f32_e32 v115, v177, v177
	v_add_f32_e32 v112, v112, v113
	v_add_f32_e32 v112, v112, v114
	v_add_f32_e32 v112, v112, v115
	s_nop 1
	v_add_f32_dpp v112, v112, v112 quad_perm:[1,0,3,2] row_mask:0xf bank_mask:0xf bound_ctrl:1
	s_nop 1
	v_add_f32_dpp v112, v112, v112 quad_perm:[2,3,0,1] row_mask:0xf bank_mask:0xf bound_ctrl:1
	s_nop 1
	v_add_f32_dpp v112, v112, v112 row_half_mirror row_mask:0xf bank_mask:0xf bound_ctrl:1
	s_nop 1
	v_add_f32_dpp v112, v112, v112 row_mirror row_mask:0xf bank_mask:0xf bound_ctrl:1
	s_nop 1
	ds_swizzle_b32 v113, v112 offset:swizzle(SWAP,16)
	s_waitcnt lgkmcnt(0)
	v_add_f32_e32 v112, v112, v113
	v_mov_b32_e32 v113, v112
	s_nop 1
	v_permlane32_swap_b32_e32 v112, v113
	v_add_f32_e32 v112, v112, v113
	v_fmamk_f32 v112, v112, 0x3a800000, v224
	v_rsq_f32_e32 v112, v112
	s_waitcnt vmcnt(0)
	v_mul_f32_e32 v162, v162, v112
	v_mul_f32_e32 v163, v163, v112
	v_mul_f32_e32 v164, v164, v112
	v_mul_f32_e32 v165, v165, v112
	v_mul_f32_e32 v166, v166, v112
	v_mul_f32_e32 v167, v167, v112
	v_mul_f32_e32 v168, v168, v112
	v_mul_f32_e32 v169, v169, v112
	v_mul_f32_e32 v170, v170, v112
	v_mul_f32_e32 v171, v171, v112
	v_mul_f32_e32 v172, v172, v112
	v_mul_f32_e32 v173, v173, v112
	v_mul_f32_e32 v174, v174, v112
	v_mul_f32_e32 v175, v175, v112
	v_mul_f32_e32 v176, v176, v112
	v_mul_f32_e32 v177, v177, v112
	v_mul_f32_e32 v162, v80, v162
	v_mul_f32_e32 v163, v81, v163
	v_mul_f32_e32 v164, v82, v164
	v_mul_f32_e32 v165, v83, v165
	v_mul_f32_e32 v166, v84, v166
	v_mul_f32_e32 v167, v85, v167
	v_mul_f32_e32 v168, v86, v168
	v_mul_f32_e32 v169, v87, v169
	v_mul_f32_e32 v170, v88, v170
	v_mul_f32_e32 v171, v89, v171
	v_mul_f32_e32 v172, v90, v172
	v_mul_f32_e32 v173, v91, v173
	v_mul_f32_e32 v174, v92, v174
	v_mul_f32_e32 v175, v93, v175
	v_mul_f32_e32 v176, v94, v176
	v_mul_f32_e32 v177, v95, v177
	v_add_f32_e32 v96, 1.0, v96
	v_add_f32_e32 v97, 1.0, v97
	v_add_f32_e32 v98, 1.0, v98
	v_add_f32_e32 v99, 1.0, v99
	v_add_f32_e32 v100, 1.0, v100
	v_add_f32_e32 v101, 1.0, v101
	v_add_f32_e32 v102, 1.0, v102
	v_add_f32_e32 v103, 1.0, v103
	v_add_f32_e32 v104, 1.0, v104
	v_add_f32_e32 v105, 1.0, v105
	v_add_f32_e32 v106, 1.0, v106
	v_add_f32_e32 v107, 1.0, v107
	v_add_f32_e32 v108, 1.0, v108
	v_add_f32_e32 v109, 1.0, v109
	v_add_f32_e32 v110, 1.0, v110
	v_add_f32_e32 v111, 1.0, v111
	v_fma_f32 v162, v96, v162, v178
	v_fma_f32 v163, v97, v163, v179
	v_fma_f32 v164, v98, v164, v180
	v_fma_f32 v165, v99, v165, v181
	v_fma_f32 v166, v100, v166, v182
	v_fma_f32 v167, v101, v167, v183
	v_fma_f32 v168, v102, v168, v184
	v_fma_f32 v169, v103, v169, v185
	v_fma_f32 v170, v104, v170, v186
	v_fma_f32 v171, v105, v171, v187
	v_fma_f32 v172, v106, v172, v188
	v_fma_f32 v173, v107, v173, v189
	v_fma_f32 v174, v108, v174, v190
	v_fma_f32 v175, v109, v175, v191
	v_fma_f32 v176, v110, v176, v192
	v_fma_f32 v177, v111, v177, v193
	v_cvt_pk_f16_f32 v114, v162, v163
	v_cvt_pk_f16_f32 v115, v164, v165
	v_cvt_pk_f16_f32 v116, v166, v167
	v_cvt_pk_f16_f32 v117, v168, v169
	v_cvt_pk_f16_f32 v118, v170, v171
	v_cvt_pk_f16_f32 v119, v172, v173
	v_cvt_pk_f16_f32 v120, v174, v175
	v_cvt_pk_f16_f32 v121, v176, v177
	global_store_dwordx2 v128, v[114:115], s[54:55]
	global_store_dwordx2 v128, v[116:117], s[54:55] offset:512
	global_store_dwordx2 v128, v[118:119], s[54:55] offset:1024
	global_store_dwordx2 v128, v[120:121], s[54:55] offset:1536
	s_add_i32 s40, s40, s4
	s_branch .Lrnp_exit
; DI void rows_norm_mod(const P& p, const float* xlat, const float* xctx, int l, const float* gain, int sh_idx, int sc_idx,
;                       h16* dst, int nrows) {
;     ...
;   for (int row = gw; row < nrows; row += nw) {
;     const float* xr = row < TL ? xlat + (size_t)row * 1024 : xctx + (size_t)(row - TL) * 1024;
;     const int mrow = row < TL ? (row >> 12) : 8;
;     const float* mr = mod + ((size_t)l * 9 + mrow) * 6144;
;     f32x4 v[4];
;     float ss = 0.f;
; #pragma unroll
;     for (int i = 0; i < 4; ++i) {
;       v[i] = *(const f32x4*)(xr + lane * 4 + 256 * i);
;       ss += v[i].x * v[i].x + v[i].y * v[i].y + v[i].z * v[i].z + v[i].w * v[i].w;
;     }
;     ss = wave_sum(ss);
;     const float rstd = rsqrtf(ss * (1.f / 1024.f) + EPS);
; #pragma unroll
;     for (int i = 0; i < 4; ++i) {
;       const int c = lane * 4 + 256 * i;
;       f32x4 g = *(const f32x4*)(gain + c), sc = *(const f32x4*)(mr + sc_idx * 1024 + c), sh = *(const f32x4*)(mr + sh_idx * 1024 + c);
;       h16x4 o;
;       o.x = (h16)(v[i].x * rstd * g.x * (1.f + sc.x) + sh.x);
;       o.y = (h16)(v[i].y * rstd * g.y * (1.f + sc.y) + sh.y);
;       o.z = (h16)(v[i].z * rstd * g.z * (1.f + sc.z) + sh.z);
;       o.w = (h16)(v[i].w * rstd * g.w * (1.f + sc.w) + sh.w);
;       *(h16x4*)(dst + (size_t)row * 1024 + c) = o;
;     }
.Lrnp_tail2:
	s_waitcnt vmcnt(8)
	v_mul_f32_e32 v112, v163, v163
	v_mul_f32_e32 v113, v167, v167
	v_mul_f32_e32 v114, v171, v171
	v_mul_f32_e32 v115, v175, v175
	v_fmac_f32_e32 v112, v162, v162
	v_fmac_f32_e32 v113, v166, v166
	v_fmac_f32_e32 v114, v170, v170
	v_fmac_f32_e32 v115, v174, v174
	v_fmac_f32_e32 v112, v164, v164
	v_fmac_f32_e32 v113, v168, v168
	v_fmac_f32_e32 v114, v172, v172
	v_fmac_f32_e32 v115, v176, v176
	v_fmac_f32_e32 v112, v165, v165
	v_fmac_f32_e32 v113, v169, v169
	v_fmac_f32_e32 v114, v173, v173
	v_fmac_f32_e32 v115, v177, v177
	v_add_f32_e32 v112, v112, v113
	v_add_f32_e32 v112, v112, v114
	v_add_f32_e32 v112, v112, v115
	s_nop 1
	v_add_f32_dpp v112, v112, v112 quad_perm:[1,0,3,2] row_mask:0xf bank_mask:0xf bound_ctrl:1
	s_nop 1
	v_add_f32_dpp v112, v112, v112 quad_perm:[2,3,0,1] row_mask:0xf bank_mask:0xf bound_ctrl:1
	s_nop 1
	v_add_f32_dpp v112, v112, v112 row_half_mirror row_mask:0xf bank_mask:0xf bound_ctrl:1
	s_nop 1
	v_add_f32_dpp v112, v112, v112 row_mirror row_mask:0xf bank_mask:0xf bound_ctrl:1
	s_nop 1
	ds_swizzle_b32 v113, v112 offset:swizzle(SWAP,16)
	s_waitcnt lgkmcnt(0)
	v_add_f32_e32 v112, v112, v113
	v_mov_b32_e32 v113, v112
	s_nop 1
	v_permlane32_swap_b32_e32 v112, v113
	v_add_f32_e32 v112, v112, v113
	v_fmamk_f32 v112, v112, 0x3a800000, v224
	v_rsq_f32_e32 v112, v112
	s_waitcnt vmcnt(0)
	v_mul_f32_e32 v162, v162, v112
	v_mul_f32_e32 v163, v163, v112
	v_mul_f32_e32 v164, v164, v112
	v_mul_f32_e32 v165, v165, v112
	v_mul_f32_e32 v166, v166, v112
	v_mul_f32_e32 v167, v167, v112
	v_mul_f32_e32 v168, v168, v112
	v_mul_f32_e32 v169, v169, v112
	v_mul_f32_e32 v170, v170, v112
	v_mul_f32_e32 v171, v171, v112
	v_mul_f32_e32 v172, v172, v112
	v_mul_f32_e32 v173, v173, v112
	v_mul_f32_e32 v174, v174, v112
	v_mul_f32_e32 v175, v175, v112
	v_mul_f32_e32 v176, v176, v112
	v_mul_f32_e32 v177, v177, v112
	v_mul_f32_e32 v162, v80, v162
	v_mul_f32_e32 v163, v81, v163
	v_mul_f32_e32 v164, v82, v164
	v_mul_f32_e32 v165, v83, v165
	v_mul_f32_e32 v166, v84, v166
	v_mul_f32_e32 v167, v85, v167
	v_mul_f32_e32 v168, v86, v168
	v_mul_f32_e32 v169, v87, v169
	v_mul_f32_e32 v170, v88, v170
	v_mul_f32_e32 v171, v89, v171
	v_mul_f32_e32 v172, v90, v172
	v_mul_f32_e32 v173, v91, v173
	v_mul_f32_e32 v174, v92, v174
	v_mul_f32_e32 v175, v93, v175
	v_mul_f32_e32 v176, v94, v176
	v_mul_f32_e32 v177, v95, v177
	v_add_f32_e32 v96, 1.0, v96
	v_add_f32_e32 v97, 1.0, v97
	v_add_f32_e32 v98, 1.0, v98
	v_add_f32_e32 v99, 1.0, v99
	v_add_f32_e32 v100, 1.0, v100
	v_add_f32_e32 v101, 1.0, v101
	v_add_f32_e32 v102, 1.0, v102
	v_add_f32_e32 v103, 1.0, v103
	v_add_f32_e32 v104, 1.0, v104
	v_add_f32_e32 v105, 1.0, v105
	v_add_f32_e32 v106, 1.0, v106
	v_add_f32_e32 v107, 1.0, v107
	v_add_f32_e32 v108, 1.0, v108
	v_add_f32_e32 v109, 1.0, v109
	v_add_f32_e32 v110, 1.0, v110
	v_add_f32_e32 v111, 1.0, v111
	v_fma_f32 v162, v96, v162, v178
	v_fma_f32 v163, v97, v163, v179
	v_fma_f32 v164, v98, v164, v180
	v_fma_f32 v165, v99, v165, v181
	v_fma_f32 v166, v100, v166, v182
	v_fma_f32 v167, v101, v167, v183
	v_fma_f32 v168, v102, v168, v184
	v_fma_f32 v169, v103, v169, v185
	v_fma_f32 v170, v104, v170, v186
	v_fma_f32 v171, v105, v171, v187
	v_fma_f32 v172, v106, v172, v188
	v_fma_f32 v173, v107, v173, v189
	v_fma_f32 v174, v108, v174, v190
	v_fma_f32 v175, v109, v175, v191
	v_fma_f32 v176, v110, v176, v192
	v_fma_f32 v177, v111, v177, v193
	v_cvt_pk_f16_f32 v114, v162, v163
	v_cvt_pk_f16_f32 v115, v164, v165
	v_cvt_pk_f16_f32 v116, v166, v167
	v_cvt_pk_f16_f32 v117, v168, v169
	v_cvt_pk_f16_f32 v118, v170, v171
	v_cvt_pk_f16_f32 v119, v172, v173
	v_cvt_pk_f16_f32 v120, v174, v175
	v_cvt_pk_f16_f32 v121, v176, v177
	global_store_dwordx2 v128, v[114:115], s[54:55]
	global_store_dwordx2 v128, v[116:117], s[54:55] offset:512
	global_store_dwordx2 v128, v[118:119], s[54:55] offset:1024
	global_store_dwordx2 v128, v[120:121], s[54:55] offset:1536
	s_add_i32 s40, s40, s4
	s_cmp_lt_i32 s40, s36
	s_cbranch_scc0 .Lrnp_exit
; DI void rows_norm_mod(const P& p, const float* xlat, const float* xctx, int l, const float* gain, int sh_idx, int sc_idx,
;                       h16* dst, int nrows) {
;     ...
;   for (int row = gw; row < nrows; row += nw) {
;     const float* xr = row < TL ? xlat + (size_t)row * 1024 : xctx + (size_t)(row - TL) * 1024;
;     const int mrow = row < TL ? (row >> 12) : 8;
;     const float* mr = mod + ((size_t)l * 9 + mrow) * 6144;
;     f32x4 v[4];
;     float ss = 0.f;
; #pragma unroll
;     for (int i = 0; i < 4; ++i) {
;       v[i] = *(const f32x4*)(xr + lane * 4 + 256 * i);
;       ss += v[i].x * v[i].x + v[i].y * v[i].y + v[i].z * v[i].z + v[i].w * v[i].w;
;     }
;     ss = wave_sum(ss);
;     const float rstd = rsqrtf(ss * (1.f / 1024.f) + EPS);
; #pragma unroll
;     for (int i = 0; i < 4; ++i) {
;       const int c = lane * 4 + 256 * i;
;       f32x4 g = *(const f32x4*)(gain + c), sc = *(const f32x4*)(mr + sc_idx * 1024 + c), sh = *(const f32x4*)(mr + sh_idx * 1024 + c);
;       h16x4 o;
;       o.x = (h16)(v[i].x * rstd * g.x * (1.f + sc.x) + sh.x);
;       o.y = (h16)(v[i].y * rstd * g.y * (1.f + sc.y) + sh.y);
;       o.z = (h16)(v[i].z * rstd * g.z * (1.f + sc.z) + sh.z);
;       o.w = (h16)(v[i].w * rstd * g.w * (1.f + sc.w) + sh.w);
;       *(h16x4*)(dst + (size_t)row * 1024 + c) = o;
;     }
	s_lshr_b32 s41, s40, 12
	s_cmp_lt_u32 s40, 0x8000
	s_cselect_b32 s41, s41, 8
	s_mul_i32 s41, s41, 0x6000
	s_add_u32 s50, s56, s41
	s_addc_u32 s51, s57, 0
	s_add_u32 s52, s50, 0x1000
	s_addc_u32 s53, s51, 0
	s_lshl_b32 s41, s40, 11
	s_add_u32 s54, s58, s41
	s_addc_u32 s55, s59, 0
	global_load_dwordx4 v[96:99], v0, s[52:53]
	global_load_dwordx4 v[100:103], v0, s[52:53] offset:1024
	global_load_dwordx4 v[104:107], v0, s[52:53] offset:2048
	global_load_dwordx4 v[108:111], v0, s[52:53] offset:3072
	global_load_dwordx4 v[178:181], v0, s[50:51]
	global_load_dwordx4 v[182:185], v0, s[50:51] offset:1024
	global_load_dwordx4 v[186:189], v0, s[50:51] offset:2048
	global_load_dwordx4 v[190:193], v0, s[50:51] offset:3072
	s_waitcnt vmcnt(8)
	v_mul_f32_e32 v112, v3, v3
	v_mul_f32_e32 v113, v7, v7
	v_mul_f32_e32 v114, v11, v11
	v_mul_f32_e32 v115, v15, v15
	v_fmac_f32_e32 v112, v2, v2
	v_fmac_f32_e32 v113, v6, v6
	v_fmac_f32_e32 v114, v10, v10
	v_fmac_f32_e32 v115, v14, v14
	v_fmac_f32_e32 v112, v4, v4
	v_fmac_f32_e32 v113, v8, v8
	v_fmac_f32_e32 v114, v12, v12
	v_fmac_f32_e32 v115, v16, v16
	v_fmac_f32_e32 v112, v5, v5
	v_fmac_f32_e32 v113, v9, v9
	v_fmac_f32_e32 v114, v13, v13
	v_fmac_f32_e32 v115, v17, v17
	v_add_f32_e32 v112, v112, v113
	v_add_f32_e32 v112, v112, v114
	v_add_f32_e32 v112, v112, v115
	s_nop 1
	v_add_f32_dpp v112, v112, v112 quad_perm:[1,0,3,2] row_mask:0xf bank_mask:0xf bound_ctrl:1
	s_nop 1
	v_add_f32_dpp v112, v112, v112 quad_perm:[2,3,0,1] row_mask:0xf bank_mask:0xf bound_ctrl:1
	s_nop 1
	v_add_f32_dpp v112, v112, v112 row_half_mirror row_mask:0xf bank_mask:0xf bound_ctrl:1
	s_nop 1
	v_add_f32_dpp v112, v112, v112 row_mirror row_mask:0xf bank_mask:0xf bound_ctrl:1
	s_nop 1
	ds_swizzle_b32 v113, v112 offset:swizzle(SWAP,16)
	s_waitcnt lgkmcnt(0)
	v_add_f32_e32 v112, v112, v113
	v_mov_b32_e32 v113, v112
	s_nop 1
	v_permlane32_swap_b32_e32 v112, v113
	v_add_f32_e32 v112, v112, v113
	v_fmamk_f32 v112, v112, 0x3a800000, v224
	v_rsq_f32_e32 v112, v112
	s_waitcnt vmcnt(0)
	v_mul_f32_e32 v2, v2, v112
	v_mul_f32_e32 v3, v3, v112
	v_mul_f32_e32 v4, v4, v112
	v_mul_f32_e32 v5, v5, v112
	v_mul_f32_e32 v6, v6, v112
	v_mul_f32_e32 v7, v7, v112
	v_mul_f32_e32 v8, v8, v112
	v_mul_f32_e32 v9, v9, v112
	v_mul_f32_e32 v10, v10, v112
	v_mul_f32_e32 v11, v11, v112
	v_mul_f32_e32 v12, v12, v112
	v_mul_f32_e32 v13, v13, v112
	v_mul_f32_e32 v14, v14, v112
	v_mul_f32_e32 v15, v15, v112
	v_mul_f32_e32 v16, v16, v112
	v_mul_f32_e32 v17, v17, v112
	v_mul_f32_e32 v2, v80, v2
	v_mul_f32_e32 v3, v81, v3
	v_mul_f32_e32 v4, v82, v4
	v_mul_f32_e32 v5, v83, v5
	v_mul_f32_e32 v6, v84, v6
	v_mul_f32_e32 v7, v85, v7
	v_mul_f32_e32 v8, v86, v8
	v_mul_f32_e32 v9, v87, v9
	v_mul_f32_e32 v10, v88, v10
	v_mul_f32_e32 v11, v89, v11
	v_mul_f32_e32 v12, v90, v12
	v_mul_f32_e32 v13, v91, v13
	v_mul_f32_e32 v14, v92, v14
	v_mul_f32_e32 v15, v93, v15
	v_mul_f32_e32 v16, v94, v16
	v_mul_f32_e32 v17, v95, v17
	v_add_f32_e32 v96, 1.0, v96
	v_add_f32_e32 v97, 1.0, v97
	v_add_f32_e32 v98, 1.0, v98
	v_add_f32_e32 v99, 1.0, v99
	v_add_f32_e32 v100, 1.0, v100
	v_add_f32_e32 v101, 1.0, v101
	v_add_f32_e32 v102, 1.0, v102
	v_add_f32_e32 v103, 1.0, v103
	v_add_f32_e32 v104, 1.0, v104
	v_add_f32_e32 v105, 1.0, v105
	v_add_f32_e32 v106, 1.0, v106
	v_add_f32_e32 v107, 1.0, v107
	v_add_f32_e32 v108, 1.0, v108
	v_add_f32_e32 v109, 1.0, v109
	v_add_f32_e32 v110, 1.0, v110
	v_add_f32_e32 v111, 1.0, v111
	v_fma_f32 v2, v96, v2, v178
	v_fma_f32 v3, v97, v3, v179
	v_fma_f32 v4, v98, v4, v180
	v_fma_f32 v5, v99, v5, v181
	v_fma_f32 v6, v100, v6, v182
	v_fma_f32 v7, v101, v7, v183
	v_fma_f32 v8, v102, v8, v184
	v_fma_f32 v9, v103, v9, v185
	v_fma_f32 v10, v104, v10, v186
	v_fma_f32 v11, v105, v11, v187
	v_fma_f32 v12, v106, v12, v188
	v_fma_f32 v13, v107, v13, v189
	v_fma_f32 v14, v108, v14, v190
	v_fma_f32 v15, v109, v15, v191
	v_fma_f32 v16, v110, v16, v192
	v_fma_f32 v17, v111, v17, v193
	v_cvt_pk_f16_f32 v114, v2, v3
	v_cvt_pk_f16_f32 v115, v4, v5
	v_cvt_pk_f16_f32 v116, v6, v7
	v_cvt_pk_f16_f32 v117, v8, v9
	v_cvt_pk_f16_f32 v118, v10, v11
	v_cvt_pk_f16_f32 v119, v12, v13
	v_cvt_pk_f16_f32 v120, v14, v15
	v_cvt_pk_f16_f32 v121, v16, v17
	global_store_dwordx2 v128, v[114:115], s[54:55]
	global_store_dwordx2 v128, v[116:117], s[54:55] offset:512
	global_store_dwordx2 v128, v[118:119], s[54:55] offset:1024
	global_store_dwordx2 v128, v[120:121], s[54:55] offset:1536
	s_add_i32 s40, s40, s4
	s_branch .Lrnp_exit
.Lrnp_exit:
.LBB0_160:
	s_or_b64 exec, exec, s[0:1]

; DI int TIDX() { int t = threadIdx.x; asm volatile("" : "+v"(t)); return t; }
; DI int BIDX() { int b = blockIdx.x; asm volatile("" : "+s"(b)); return b; }
; DI void rows_norm_mod(const P& p, const float* xlat, const float* xctx, int l, const float* gain, int sh_idx, int sc_idx,
;                       h16* dst, int nrows) {
;   const int lane = TIDX() & 63;
;   const int gw = BIDX() * 4 + (TIDX() >> 6), nw = gridDim.x * 4;
;   const float* mod = (const float*)(p.ws + OFF_MOD);
;   for (int row = gw; row < nrows; row += nw) {
;     const float* xr = row < TL ? xlat + (size_t)row * 1024 : xctx + (size_t)(row - TL) * 1024;
;     const int mrow = row < TL ? (row >> 12) : 8;
;     const float* mr = mod + ((size_t)l * 9 + mrow) * 6144;
;     f32x4 v[4];
;     float ss = 0.f;
; #pragma unroll
;     for (int i = 0; i < 4; ++i) {
;       v[i] = *(const f32x4*)(xr + lane * 4 + 256 * i);
;       ss += v[i].x * v[i].x + v[i].y * v[i].y + v[i].z * v[i].z + v[i].w * v[i].w;
;     }
;     ss = wave_sum(ss);
;     const float rstd = rsqrtf(ss * (1.f / 1024.f) + EPS);
; #pragma unroll
;     for (int i = 0; i < 4; ++i) {
;       const int c = lane * 4 + 256 * i;
;       f32x4 g = *(const f32x4*)(gain + c), sc = *(const f32x4*)(mr + sc_idx * 1024 + c), sh = *(const f32x4*)(mr + sh_idx * 1024 + c);
;       h16x4 o;
;       o.x = (h16)(v[i].x * rstd * g.x * (1.f + sc.x) + sh.x);
;       o.y = (h16)(v[i].y * rstd * g.y * (1.f + sc.y) + sh.y);
;       o.z = (h16)(v[i].z * rstd * g.z * (1.f + sc.z) + sh.z);
;       o.w = (h16)(v[i].w * rstd * g.w * (1.f + sc.w) + sh.w);
;       *(h16x4*)(dst + (size_t)row * 1024 + c) = o;
;     }
;   }
; }
.LBB0_1961:
	v_readlane_b32 s12, v254, 53
	v_readlane_b32 s13, v254, 54
	v_readlane_b32 s16, v254, 57
	v_readlane_b32 s17, v254, 58
	v_readlane_b32 s20, v255, 1
	v_readlane_b32 s21, v255, 2
	v_readlane_b32 s2, v255, 5
	s_add_u32 s18, s48, 0x316c000
	s_addc_u32 s19, s49, 0
	v_lshrrev_b32_e32 v128, 1, v0
	global_load_dwordx4 v[80:83], v0, s[20:21]
	global_load_dwordx4 v[84:87], v0, s[20:21] offset:1024
	global_load_dwordx4 v[88:91], v0, s[20:21] offset:2048
	global_load_dwordx4 v[92:95], v0, s[20:21] offset:3072
	v_readfirstlane_b32 s3, v22
	s_nop 3
	s_sub_u32 s7, s3, 0x8000
	s_cmp_lt_u32 s3, 0x8000
	s_cselect_b32 s7, s3, s7
	s_cselect_b32 s8, s12, s16
	s_cselect_b32 s9, s13, s17
	s_lshl_b32 s7, s7, 12
	s_add_u32 s8, s8, s7
	s_addc_u32 s9, s9, 0
	global_load_dwordx4 v[2:5], v0, s[8:9]
	global_load_dwordx4 v[6:9], v0, s[8:9] offset:1024
	global_load_dwordx4 v[10:13], v0, s[8:9] offset:2048
	global_load_dwordx4 v[14:17], v0, s[8:9] offset:3072
	s_add_i32 s14, s3, s2
	s_cmp_lt_i32 s14, 0x8800
	s_cbranch_scc0 .Lrn2_pre0
	s_sub_u32 s7, s14, 0x8000
	s_cmp_lt_u32 s14, 0x8000
	s_cselect_b32 s7, s14, s7
	s_cselect_b32 s8, s12, s16
	s_cselect_b32 s9, s13, s17
	s_lshl_b32 s7, s7, 12
	s_add_u32 s8, s8, s7
	s_addc_u32 s9, s9, 0
	global_load_dwordx4 v[32:35], v0, s[8:9]
	global_load_dwordx4 v[36:39], v0, s[8:9] offset:1024
	global_load_dwordx4 v[40:43], v0, s[8:9] offset:2048
	global_load_dwordx4 v[44:47], v0, s[8:9] offset:3072
.Lrn2_pre0:
	s_lshr_b32 s6, s3, 12
	s_cmp_lt_u32 s3, 0x8000
	s_cselect_b32 s6, s6, 8
	s_mul_i32 s6, s6, 0x6000
	s_add_u32 s22, s4, s6
	s_addc_u32 s23, s5, 0
	s_add_u32 s32, s22, 0x1000
	s_addc_u32 s33, s23, 0
	s_lshl_b32 s6, s3, 11
	s_add_u32 s24, s18, s6
	s_addc_u32 s25, s19, 0
	global_load_dwordx4 v[96:99], v0, s[32:33]
	global_load_dwordx4 v[100:103], v0, s[32:33] offset:1024
	global_load_dwordx4 v[104:107], v0, s[32:33] offset:2048
	global_load_dwordx4 v[108:111], v0, s[32:33] offset:3072
	global_load_dwordx4 v[178:181], v0, s[22:23]
	global_load_dwordx4 v[182:185], v0, s[22:23] offset:1024
	global_load_dwordx4 v[186:189], v0, s[22:23] offset:2048
	global_load_dwordx4 v[190:193], v0, s[22:23] offset:3072
	s_add_i32 s34, s3, s2
	s_add_i32 s34, s34, s2
	s_cmp_lt_i32 s34, 0x8800
	s_cbranch_scc0 .Lrn2_tail0
	s_sub_u32 s7, s34, 0x8000
	s_cmp_lt_u32 s34, 0x8000
	s_cselect_b32 s7, s34, s7
	s_cselect_b32 s8, s12, s16
	s_cselect_b32 s9, s13, s17
	s_lshl_b32 s7, s7, 12
	s_add_u32 s8, s8, s7
	s_addc_u32 s9, s9, 0
	global_load_dwordx4 v[162:165], v0, s[8:9]
	global_load_dwordx4 v[166:169], v0, s[8:9] offset:1024
	global_load_dwordx4 v[170:173], v0, s[8:9] offset:2048
	global_load_dwordx4 v[174:177], v0, s[8:9] offset:3072
	s_waitcnt vmcnt(16)
	v_mul_f32_e32 v112, v3, v3
	v_mul_f32_e32 v113, v7, v7
	v_mul_f32_e32 v114, v11, v11
	v_mul_f32_e32 v115, v15, v15
	v_fmac_f32_e32 v112, v2, v2
	v_fmac_f32_e32 v113, v6, v6
	v_fmac_f32_e32 v114, v10, v10
	v_fmac_f32_e32 v115, v14, v14
	v_fmac_f32_e32 v112, v4, v4
	v_fmac_f32_e32 v113, v8, v8
	v_fmac_f32_e32 v114, v12, v12
	v_fmac_f32_e32 v115, v16, v16
	v_fmac_f32_e32 v112, v5, v5
	v_fmac_f32_e32 v113, v9, v9
	v_fmac_f32_e32 v114, v13, v13
	v_fmac_f32_e32 v115, v17, v17
	v_add_f32_e32 v112, v112, v113
	v_add_f32_e32 v112, v112, v114
	v_add_f32_e32 v112, v112, v115
	s_nop 1
	v_add_f32_dpp v112, v112, v112 quad_perm:[1,0,3,2] row_mask:0xf bank_mask:0xf bound_ctrl:1
	s_nop 1
	v_add_f32_dpp v112, v112, v112 quad_perm:[2,3,0,1] row_mask:0xf bank_mask:0xf bound_ctrl:1
	s_nop 1
	v_add_f32_dpp v112, v112, v112 row_half_mirror row_mask:0xf bank_mask:0xf bound_ctrl:1
	s_nop 1
	v_add_f32_dpp v112, v112, v112 row_mirror row_mask:0xf bank_mask:0xf bound_ctrl:1
	s_nop 1
	ds_swizzle_b32 v113, v112 offset:swizzle(SWAP,16)
	s_waitcnt lgkmcnt(0)
	v_add_f32_e32 v112, v112, v113
	v_mov_b32_e32 v113, v112
	s_nop 1
	v_permlane32_swap_b32_e32 v112, v113
	v_add_f32_e32 v112, v112, v113
	v_fmamk_f32 v112, v112, 0x3a800000, v224
	v_rsq_f32_e32 v112, v112
	s_waitcnt vmcnt(4)
	v_mul_f32_e32 v2, v2, v112
	v_mul_f32_e32 v3, v3, v112
	v_mul_f32_e32 v4, v4, v112
	v_mul_f32_e32 v5, v5, v112
	v_mul_f32_e32 v6, v6, v112
	v_mul_f32_e32 v7, v7, v112
	v_mul_f32_e32 v8, v8, v112
	v_mul_f32_e32 v9, v9, v112
	v_mul_f32_e32 v10, v10, v112
	v_mul_f32_e32 v11, v11, v112
	v_mul_f32_e32 v12, v12, v112
	v_mul_f32_e32 v13, v13, v112
	v_mul_f32_e32 v14, v14, v112
	v_mul_f32_e32 v15, v15, v112
	v_mul_f32_e32 v16, v16, v112
	v_mul_f32_e32 v17, v17, v112
	v_mul_f32_e32 v2, v80, v2
	v_mul_f32_e32 v3, v81, v3
	v_mul_f32_e32 v4, v82, v4
	v_mul_f32_e32 v5, v83, v5
	v_mul_f32_e32 v6, v84, v6
	v_mul_f32_e32 v7, v85, v7
	v_mul_f32_e32 v8, v86, v8
	v_mul_f32_e32 v9, v87, v9
	v_mul_f32_e32 v10, v88, v10
	v_mul_f32_e32 v11, v89, v11
	v_mul_f32_e32 v12, v90, v12
	v_mul_f32_e32 v13, v91, v13
	v_mul_f32_e32 v14, v92, v14
	v_mul_f32_e32 v15, v93, v15
	v_mul_f32_e32 v16, v94, v16
	v_mul_f32_e32 v17, v95, v17
	v_add_f32_e32 v96, 1.0, v96
	v_add_f32_e32 v97, 1.0, v97
	v_add_f32_e32 v98, 1.0, v98
	v_add_f32_e32 v99, 1.0, v99
	v_add_f32_e32 v100, 1.0, v100
	v_add_f32_e32 v101, 1.0, v101
	v_add_f32_e32 v102, 1.0, v102
	v_add_f32_e32 v103, 1.0, v103
	v_add_f32_e32 v104, 1.0, v104
	v_add_f32_e32 v105, 1.0, v105
	v_add_f32_e32 v106, 1.0, v106
	v_add_f32_e32 v107, 1.0, v107
	v_add_f32_e32 v108, 1.0, v108
	v_add_f32_e32 v109, 1.0, v109
	v_add_f32_e32 v110, 1.0, v110
	v_add_f32_e32 v111, 1.0, v111
	v_fma_f32 v2, v96, v2, v178
	v_fma_f32 v3, v97, v3, v179
	v_fma_f32 v4, v98, v4, v180
	v_fma_f32 v5, v99, v5, v181
	v_fma_f32 v6, v100, v6, v182
	v_fma_f32 v7, v101, v7, v183
	v_fma_f32 v8, v102, v8, v184
	v_fma_f32 v9, v103, v9, v185
	v_fma_f32 v10, v104, v10, v186
	v_fma_f32 v11, v105, v11, v187
	v_fma_f32 v12, v106, v12, v188
	v_fma_f32 v13, v107, v13, v189
	v_fma_f32 v14, v108, v14, v190
	v_fma_f32 v15, v109, v15, v191
	v_fma_f32 v16, v110, v16, v192
	v_fma_f32 v17, v111, v17, v193
	v_cvt_pk_f16_f32 v114, v2, v3
	v_cvt_pk_f16_f32 v115, v4, v5
	v_cvt_pk_f16_f32 v116, v6, v7
	v_cvt_pk_f16_f32 v117, v8, v9
	v_cvt_pk_f16_f32 v118, v10, v11
	v_cvt_pk_f16_f32 v119, v12, v13
	v_cvt_pk_f16_f32 v120, v14, v15
	v_cvt_pk_f16_f32 v121, v16, v17
	global_store_dwordx2 v128, v[114:115], s[24:25]
	global_store_dwordx2 v128, v[116:117], s[24:25] offset:512
	global_store_dwordx2 v128, v[118:119], s[24:25] offset:1024
	global_store_dwordx2 v128, v[120:121], s[24:25] offset:1536
	s_add_i32 s3, s3, s2
; DI int TIDX() { int t = threadIdx.x; asm volatile("" : "+v"(t)); return t; }
; DI int BIDX() { int b = blockIdx.x; asm volatile("" : "+s"(b)); return b; }
; DI void rows_norm_mod(const P& p, const float* xlat, const float* xctx, int l, const float* gain, int sh_idx, int sc_idx,
;                       h16* dst, int nrows) {
;   const int lane = TIDX() & 63;
;   const int gw = BIDX() * 4 + (TIDX() >> 6), nw = gridDim.x * 4;
;   const float* mod = (const float*)(p.ws + OFF_MOD);
;   for (int row = gw; row < nrows; row += nw) {
;     const float* xr = row < TL ? xlat + (size_t)row * 1024 : xctx + (size_t)(row - TL) * 1024;
;     const int mrow = row < TL ? (row >> 12) : 8;
;     const float* mr = mod + ((size_t)l * 9 + mrow) * 6144;
;     f32x4 v[4];
;     float ss = 0.f;
; #pragma unroll
;     for (int i = 0; i < 4; ++i) {
;       v[i] = *(const f32x4*)(xr + lane * 4 + 256 * i);
;       ss += v[i].x * v[i].x + v[i].y * v[i].y + v[i].z * v[i].z + v[i].w * v[i].w;
;     }
;     ss = wave_sum(ss);
;     const float rstd = rsqrtf(ss * (1.f / 1024.f) + EPS);
; #pragma unroll
;     for (int i = 0; i < 4; ++i) {
;       const int c = lane * 4 + 256 * i;
;       f32x4 g = *(const f32x4*)(gain + c), sc = *(const f32x4*)(mr + sc_idx * 1024 + c), sh = *(const f32x4*)(mr + sh_idx * 1024 + c);
;       h16x4 o;
;       o.x = (h16)(v[i].x * rstd * g.x * (1.f + sc.x) + sh.x);
;       o.y = (h16)(v[i].y * rstd * g.y * (1.f + sc.y) + sh.y);
;       o.z = (h16)(v[i].z * rstd * g.z * (1.f + sc.z) + sh.z);
;       o.w = (h16)(v[i].w * rstd * g.w * (1.f + sc.w) + sh.w);
;       *(h16x4*)(dst + (size_t)row * 1024 + c) = o;
;     }
;   }
; }
.Lrn2_pre1:
	s_lshr_b32 s6, s3, 12
	s_cmp_lt_u32 s3, 0x8000
	s_cselect_b32 s6, s6, 8
	s_mul_i32 s6, s6, 0x6000
	s_add_u32 s22, s4, s6
	s_addc_u32 s23, s5, 0
	s_add_u32 s32, s22, 0x1000
	s_addc_u32 s33, s23, 0
	s_lshl_b32 s6, s3, 11
	s_add_u32 s24, s18, s6
	s_addc_u32 s25, s19, 0
	global_load_dwordx4 v[96:99], v0, s[32:33]
	global_load_dwordx4 v[100:103], v0, s[32:33] offset:1024
	global_load_dwordx4 v[104:107], v0, s[32:33] offset:2048
	global_load_dwordx4 v[108:111], v0, s[32:33] offset:3072
	global_load_dwordx4 v[178:181], v0, s[22:23]
	global_load_dwordx4 v[182:185], v0, s[22:23] offset:1024
	global_load_dwordx4 v[186:189], v0, s[22:23] offset:2048
	global_load_dwordx4 v[190:193], v0, s[22:23] offset:3072
	s_add_i32 s34, s3, s2
	s_add_i32 s34, s34, s2
	s_cmp_lt_i32 s34, 0x8800
	s_cbranch_scc0 .Lrn2_tail1
	s_sub_u32 s7, s34, 0x8000
	s_cmp_lt_u32 s34, 0x8000
	s_cselect_b32 s7, s34, s7
	s_cselect_b32 s8, s12, s16
	s_cselect_b32 s9, s13, s17
	s_lshl_b32 s7, s7, 12
	s_add_u32 s8, s8, s7
	s_addc_u32 s9, s9, 0
	global_load_dwordx4 v[2:5], v0, s[8:9]
	global_load_dwordx4 v[6:9], v0, s[8:9] offset:1024
	global_load_dwordx4 v[10:13], v0, s[8:9] offset:2048
	global_load_dwordx4 v[14:17], v0, s[8:9] offset:3072
	s_waitcnt vmcnt(16)
	v_mul_f32_e32 v112, v33, v33
	v_mul_f32_e32 v113, v37, v37
	v_mul_f32_e32 v114, v41, v41
	v_mul_f32_e32 v115, v45, v45
	v_fmac_f32_e32 v112, v32, v32
	v_fmac_f32_e32 v113, v36, v36
	v_fmac_f32_e32 v114, v40, v40
	v_fmac_f32_e32 v115, v44, v44
	v_fmac_f32_e32 v112, v34, v34
	v_fmac_f32_e32 v113, v38, v38
	v_fmac_f32_e32 v114, v42, v42
	v_fmac_f32_e32 v115, v46, v46
	v_fmac_f32_e32 v112, v35, v35
	v_fmac_f32_e32 v113, v39, v39
	v_fmac_f32_e32 v114, v43, v43
	v_fmac_f32_e32 v115, v47, v47
	v_add_f32_e32 v112, v112, v113
	v_add_f32_e32 v112, v112, v114
	v_add_f32_e32 v112, v112, v115
	s_nop 1
	v_add_f32_dpp v112, v112, v112 quad_perm:[1,0,3,2] row_mask:0xf bank_mask:0xf bound_ctrl:1
	s_nop 1
	v_add_f32_dpp v112, v112, v112 quad_perm:[2,3,0,1] row_mask:0xf bank_mask:0xf bound_ctrl:1
	s_nop 1
	v_add_f32_dpp v112, v112, v112 row_half_mirror row_mask:0xf bank_mask:0xf bound_ctrl:1
	s_nop 1
	v_add_f32_dpp v112, v112, v112 row_mirror row_mask:0xf bank_mask:0xf bound_ctrl:1
	s_nop 1
	ds_swizzle_b32 v113, v112 offset:swizzle(SWAP,16)
	s_waitcnt lgkmcnt(0)
	v_add_f32_e32 v112, v112, v113
	v_mov_b32_e32 v113, v112
	s_nop 1
	v_permlane32_swap_b32_e32 v112, v113
	v_add_f32_e32 v112, v112, v113
	v_fmamk_f32 v112, v112, 0x3a800000, v224
	v_rsq_f32_e32 v112, v112
	s_waitcnt vmcnt(4)
	v_mul_f32_e32 v32, v32, v112
	v_mul_f32_e32 v33, v33, v112
	v_mul_f32_e32 v34, v34, v112
	v_mul_f32_e32 v35, v35, v112
	v_mul_f32_e32 v36, v36, v112
	v_mul_f32_e32 v37, v37, v112
	v_mul_f32_e32 v38, v38, v112
	v_mul_f32_e32 v39, v39, v112
	v_mul_f32_e32 v40, v40, v112
	v_mul_f32_e32 v41, v41, v112
	v_mul_f32_e32 v42, v42, v112
	v_mul_f32_e32 v43, v43, v112
	v_mul_f32_e32 v44, v44, v112
	v_mul_f32_e32 v45, v45, v112
	v_mul_f32_e32 v46, v46, v112
	v_mul_f32_e32 v47, v47, v112
	v_mul_f32_e32 v32, v80, v32
	v_mul_f32_e32 v33, v81, v33
	v_mul_f32_e32 v34, v82, v34
	v_mul_f32_e32 v35, v83, v35
	v_mul_f32_e32 v36, v84, v36
	v_mul_f32_e32 v37, v85, v37
	v_mul_f32_e32 v38, v86, v38
	v_mul_f32_e32 v39, v87, v39
	v_mul_f32_e32 v40, v88, v40
	v_mul_f32_e32 v41, v89, v41
	v_mul_f32_e32 v42, v90, v42
	v_mul_f32_e32 v43, v91, v43
	v_mul_f32_e32 v44, v92, v44
	v_mul_f32_e32 v45, v93, v45
	v_mul_f32_e32 v46, v94, v46
	v_mul_f32_e32 v47, v95, v47
	v_add_f32_e32 v96, 1.0, v96
	v_add_f32_e32 v97, 1.0, v97
	v_add_f32_e32 v98, 1.0, v98
	v_add_f32_e32 v99, 1.0, v99
	v_add_f32_e32 v100, 1.0, v100
	v_add_f32_e32 v101, 1.0, v101
	v_add_f32_e32 v102, 1.0, v102
	v_add_f32_e32 v103, 1.0, v103
	v_add_f32_e32 v104, 1.0, v104
	v_add_f32_e32 v105, 1.0, v105
	v_add_f32_e32 v106, 1.0, v106
	v_add_f32_e32 v107, 1.0, v107
	v_add_f32_e32 v108, 1.0, v108
	v_add_f32_e32 v109, 1.0, v109
	v_add_f32_e32 v110, 1.0, v110
	v_add_f32_e32 v111, 1.0, v111
	v_fma_f32 v32, v96, v32, v178
	v_fma_f32 v33, v97, v33, v179
	v_fma_f32 v34, v98, v34, v180
	v_fma_f32 v35, v99, v35, v181
	v_fma_f32 v36, v100, v36, v182
	v_fma_f32 v37, v101, v37, v183
	v_fma_f32 v38, v102, v38, v184
	v_fma_f32 v39, v103, v39, v185
	v_fma_f32 v40, v104, v40, v186
	v_fma_f32 v41, v105, v41, v187
	v_fma_f32 v42, v106, v42, v188
	v_fma_f32 v43, v107, v43, v189
	v_fma_f32 v44, v108, v44, v190
	v_fma_f32 v45, v109, v45, v191
	v_fma_f32 v46, v110, v46, v192
	v_fma_f32 v47, v111, v47, v193
	v_cvt_pk_f16_f32 v114, v32, v33
	v_cvt_pk_f16_f32 v115, v34, v35
	v_cvt_pk_f16_f32 v116, v36, v37
	v_cvt_pk_f16_f32 v117, v38, v39
	v_cvt_pk_f16_f32 v118, v40, v41
	v_cvt_pk_f16_f32 v119, v42, v43
	v_cvt_pk_f16_f32 v120, v44, v45
	v_cvt_pk_f16_f32 v121, v46, v47
	global_store_dwordx2 v128, v[114:115], s[24:25]
	global_store_dwordx2 v128, v[116:117], s[24:25] offset:512
	global_store_dwordx2 v128, v[118:119], s[24:25] offset:1024
	global_store_dwordx2 v128, v[120:121], s[24:25] offset:1536
	s_add_i32 s3, s3, s2
; DI int TIDX() { int t = threadIdx.x; asm volatile("" : "+v"(t)); return t; }
; DI int BIDX() { int b = blockIdx.x; asm volatile("" : "+s"(b)); return b; }
; DI void rows_norm_mod(const P& p, const float* xlat, const float* xctx, int l, const float* gain, int sh_idx, int sc_idx,
;                       h16* dst, int nrows) {
;   const int lane = TIDX() & 63;
;   const int gw = BIDX() * 4 + (TIDX() >> 6), nw = gridDim.x * 4;
;   const float* mod = (const float*)(p.ws + OFF_MOD);
;   for (int row = gw; row < nrows; row += nw) {
;     const float* xr = row < TL ? xlat + (size_t)row * 1024 : xctx + (size_t)(row - TL) * 1024;
;     const int mrow = row < TL ? (row >> 12) : 8;
;     const float* mr = mod + ((size_t)l * 9 + mrow) * 6144;
;     f32x4 v[4];
;     float ss = 0.f;
; #pragma unroll
;     for (int i = 0; i < 4; ++i) {
;       v[i] = *(const f32x4*)(xr + lane * 4 + 256 * i);
;       ss += v[i].x * v[i].x + v[i].y * v[i].y + v[i].z * v[i].z + v[i].w * v[i].w;
;     }
;     ss = wave_sum(ss);
;     const float rstd = rsqrtf(ss * (1.f / 1024.f) + EPS);
; #pragma unroll
;     for (int i = 0; i < 4; ++i) {
;       const int c = lane * 4 + 256 * i;
;       f32x4 g = *(const f32x4*)(gain + c), sc = *(const f32x4*)(mr + sc_idx * 1024 + c), sh = *(const f32x4*)(mr + sh_idx * 1024 + c);
;       h16x4 o;
;       o.x = (h16)(v[i].x * rstd * g.x * (1.f + sc.x) + sh.x);
;       o.y = (h16)(v[i].y * rstd * g.y * (1.f + sc.y) + sh.y);
;       o.z = (h16)(v[i].z * rstd * g.z * (1.f + sc.z) + sh.z);
;       o.w = (h16)(v[i].w * rstd * g.w * (1.f + sc.w) + sh.w);
;       *(h16x4*)(dst + (size_t)row * 1024 + c) = o;
;     }
;   }
; }
.Lrn2_l2:
	s_lshr_b32 s6, s3, 12
	s_cmp_lt_u32 s3, 0x8000
	s_cselect_b32 s6, s6, 8
	s_mul_i32 s6, s6, 0x6000
	s_add_u32 s22, s4, s6
	s_addc_u32 s23, s5, 0
	s_add_u32 s32, s22, 0x1000
	s_addc_u32 s33, s23, 0
	s_lshl_b32 s6, s3, 11
	s_add_u32 s24, s18, s6
	s_addc_u32 s25, s19, 0
	global_load_dwordx4 v[96:99], v0, s[32:33]
	global_load_dwordx4 v[100:103], v0, s[32:33] offset:1024
	global_load_dwordx4 v[104:107], v0, s[32:33] offset:2048
	global_load_dwordx4 v[108:111], v0, s[32:33] offset:3072
	global_load_dwordx4 v[178:181], v0, s[22:23]
	global_load_dwordx4 v[182:185], v0, s[22:23] offset:1024
	global_load_dwordx4 v[186:189], v0, s[22:23] offset:2048
	global_load_dwordx4 v[190:193], v0, s[22:23] offset:3072
	s_add_i32 s34, s3, s2
	s_add_i32 s34, s34, s2
	s_cmp_lt_i32 s34, 0x8800
	s_cbranch_scc0 .Lrn2_tail2
	s_sub_u32 s7, s34, 0x8000
	s_cmp_lt_u32 s34, 0x8000
	s_cselect_b32 s7, s34, s7
	s_cselect_b32 s8, s12, s16
	s_cselect_b32 s9, s13, s17
	s_lshl_b32 s7, s7, 12
	s_add_u32 s8, s8, s7
	s_addc_u32 s9, s9, 0
	global_load_dwordx4 v[32:35], v0, s[8:9]
	global_load_dwordx4 v[36:39], v0, s[8:9] offset:1024
	global_load_dwordx4 v[40:43], v0, s[8:9] offset:2048
	global_load_dwordx4 v[44:47], v0, s[8:9] offset:3072
	s_waitcnt vmcnt(32)
	v_mul_f32_e32 v112, v163, v163
	v_mul_f32_e32 v113, v167, v167
	v_mul_f32_e32 v114, v171, v171
	v_mul_f32_e32 v115, v175, v175
	v_fmac_f32_e32 v112, v162, v162
	v_fmac_f32_e32 v113, v166, v166
	v_fmac_f32_e32 v114, v170, v170
	v_fmac_f32_e32 v115, v174, v174
	v_fmac_f32_e32 v112, v164, v164
	v_fmac_f32_e32 v113, v168, v168
	v_fmac_f32_e32 v114, v172, v172
	v_fmac_f32_e32 v115, v176, v176
	v_fmac_f32_e32 v112, v165, v165
	v_fmac_f32_e32 v113, v169, v169
	v_fmac_f32_e32 v114, v173, v173
	v_fmac_f32_e32 v115, v177, v177
	v_add_f32_e32 v112, v112, v113
	v_add_f32_e32 v112, v112, v114
	v_add_f32_e32 v112, v112, v115
	s_nop 1
	v_add_f32_dpp v112, v112, v112 quad_perm:[1,0,3,2] row_mask:0xf bank_mask:0xf bound_ctrl:1
	s_nop 1
	v_add_f32_dpp v112, v112, v112 quad_perm:[2,3,0,1] row_mask:0xf bank_mask:0xf bound_ctrl:1
	s_nop 1
	v_add_f32_dpp v112, v112, v112 row_half_mirror row_mask:0xf bank_mask:0xf bound_ctrl:1
	s_nop 1
	v_add_f32_dpp v112, v112, v112 row_mirror row_mask:0xf bank_mask:0xf bound_ctrl:1
	s_nop 1
	ds_swizzle_b32 v113, v112 offset:swizzle(SWAP,16)
	s_waitcnt lgkmcnt(0)
	v_add_f32_e32 v112, v112, v113
	v_mov_b32_e32 v113, v112
	s_nop 1
	v_permlane32_swap_b32_e32 v112, v113
	v_add_f32_e32 v112, v112, v113
	v_fmamk_f32 v112, v112, 0x3a800000, v224
	v_rsq_f32_e32 v112, v112
	s_waitcnt vmcnt(4)
	v_mul_f32_e32 v162, v162, v112
	v_mul_f32_e32 v163, v163, v112
	v_mul_f32_e32 v164, v164, v112
	v_mul_f32_e32 v165, v165, v112
	v_mul_f32_e32 v166, v166, v112
	v_mul_f32_e32 v167, v167, v112
	v_mul_f32_e32 v168, v168, v112
	v_mul_f32_e32 v169, v169, v112
	v_mul_f32_e32 v170, v170, v112
	v_mul_f32_e32 v171, v171, v112
	v_mul_f32_e32 v172, v172, v112
	v_mul_f32_e32 v173, v173, v112
	v_mul_f32_e32 v174, v174, v112
	v_mul_f32_e32 v175, v175, v112
	v_mul_f32_e32 v176, v176, v112
	v_mul_f32_e32 v177, v177, v112
	v_mul_f32_e32 v162, v80, v162
	v_mul_f32_e32 v163, v81, v163
	v_mul_f32_e32 v164, v82, v164
	v_mul_f32_e32 v165, v83, v165
	v_mul_f32_e32 v166, v84, v166
	v_mul_f32_e32 v167, v85, v167
	v_mul_f32_e32 v168, v86, v168
	v_mul_f32_e32 v169, v87, v169
	v_mul_f32_e32 v170, v88, v170
	v_mul_f32_e32 v171, v89, v171
	v_mul_f32_e32 v172, v90, v172
	v_mul_f32_e32 v173, v91, v173
	v_mul_f32_e32 v174, v92, v174
	v_mul_f32_e32 v175, v93, v175
	v_mul_f32_e32 v176, v94, v176
	v_mul_f32_e32 v177, v95, v177
	v_add_f32_e32 v96, 1.0, v96
	v_add_f32_e32 v97, 1.0, v97
	v_add_f32_e32 v98, 1.0, v98
	v_add_f32_e32 v99, 1.0, v99
	v_add_f32_e32 v100, 1.0, v100
	v_add_f32_e32 v101, 1.0, v101
	v_add_f32_e32 v102, 1.0, v102
	v_add_f32_e32 v103, 1.0, v103
	v_add_f32_e32 v104, 1.0, v104
	v_add_f32_e32 v105, 1.0, v105
	v_add_f32_e32 v106, 1.0, v106
	v_add_f32_e32 v107, 1.0, v107
	v_add_f32_e32 v108, 1.0, v108
	v_add_f32_e32 v109, 1.0, v109
	v_add_f32_e32 v110, 1.0, v110
	v_add_f32_e32 v111, 1.0, v111
	v_fma_f32 v162, v96, v162, v178
	v_fma_f32 v163, v97, v163, v179
	v_fma_f32 v164, v98, v164, v180
	v_fma_f32 v165, v99, v165, v181
	v_fma_f32 v166, v100, v166, v182
	v_fma_f32 v167, v101, v167, v183
	v_fma_f32 v168, v102, v168, v184
	v_fma_f32 v169, v103, v169, v185
	v_fma_f32 v170, v104, v170, v186
	v_fma_f32 v171, v105, v171, v187
	v_fma_f32 v172, v106, v172, v188
	v_fma_f32 v173, v107, v173, v189
	v_fma_f32 v174, v108, v174, v190
	v_fma_f32 v175, v109, v175, v191
	v_fma_f32 v176, v110, v176, v192
	v_fma_f32 v177, v111, v177, v193
	v_cvt_pk_f16_f32 v114, v162, v163
	v_cvt_pk_f16_f32 v115, v164, v165
	v_cvt_pk_f16_f32 v116, v166, v167
	v_cvt_pk_f16_f32 v117, v168, v169
	v_cvt_pk_f16_f32 v118, v170, v171
	v_cvt_pk_f16_f32 v119, v172, v173
	v_cvt_pk_f16_f32 v120, v174, v175
	v_cvt_pk_f16_f32 v121, v176, v177
	global_store_dwordx2 v128, v[114:115], s[24:25]
	global_store_dwordx2 v128, v[116:117], s[24:25] offset:512
	global_store_dwordx2 v128, v[118:119], s[24:25] offset:1024
	global_store_dwordx2 v128, v[120:121], s[24:25] offset:1536
	s_add_i32 s3, s3, s2
; DI int TIDX() { int t = threadIdx.x; asm volatile("" : "+v"(t)); return t; }
; DI int BIDX() { int b = blockIdx.x; asm volatile("" : "+s"(b)); return b; }
; DI void rows_norm_mod(const P& p, const float* xlat, const float* xctx, int l, const float* gain, int sh_idx, int sc_idx,
;                       h16* dst, int nrows) {
;   const int lane = TIDX() & 63;
;   const int gw = BIDX() * 4 + (TIDX() >> 6), nw = gridDim.x * 4;
;   const float* mod = (const float*)(p.ws + OFF_MOD);
;   for (int row = gw; row < nrows; row += nw) {
;     const float* xr = row < TL ? xlat + (size_t)row * 1024 : xctx + (size_t)(row - TL) * 1024;
;     const int mrow = row < TL ? (row >> 12) : 8;
;     const float* mr = mod + ((size_t)l * 9 + mrow) * 6144;
;     f32x4 v[4];
;     float ss = 0.f;
; #pragma unroll
;     for (int i = 0; i < 4; ++i) {
;       v[i] = *(const f32x4*)(xr + lane * 4 + 256 * i);
;       ss += v[i].x * v[i].x + v[i].y * v[i].y + v[i].z * v[i].z + v[i].w * v[i].w;
;     }
;     ss = wave_sum(ss);
;     const float rstd = rsqrtf(ss * (1.f / 1024.f) + EPS);
; #pragma unroll
;     for (int i = 0; i < 4; ++i) {
;       const int c = lane * 4 + 256 * i;
;       f32x4 g = *(const f32x4*)(gain + c), sc = *(const f32x4*)(mr + sc_idx * 1024 + c), sh = *(const f32x4*)(mr + sh_idx * 1024 + c);
;       h16x4 o;
;       o.x = (h16)(v[i].x * rstd * g.x * (1.f + sc.x) + sh.x);
;       o.y = (h16)(v[i].y * rstd * g.y * (1.f + sc.y) + sh.y);
;       o.z = (h16)(v[i].z * rstd * g.z * (1.f + sc.z) + sh.z);
;       o.w = (h16)(v[i].w * rstd * g.w * (1.f + sc.w) + sh.w);
;       *(h16x4*)(dst + (size_t)row * 1024 + c) = o;
;     }
;   }
; }
.Lrn2_l0:
	s_lshr_b32 s6, s3, 12
	s_cmp_lt_u32 s3, 0x8000
	s_cselect_b32 s6, s6, 8
	s_mul_i32 s6, s6, 0x6000
	s_add_u32 s22, s4, s6
	s_addc_u32 s23, s5, 0
	s_add_u32 s32, s22, 0x1000
	s_addc_u32 s33, s23, 0
	s_lshl_b32 s6, s3, 11
	s_add_u32 s24, s18, s6
	s_addc_u32 s25, s19, 0
	global_load_dwordx4 v[96:99], v0, s[32:33]
	global_load_dwordx4 v[100:103], v0, s[32:33] offset:1024
	global_load_dwordx4 v[104:107], v0, s[32:33] offset:2048
	global_load_dwordx4 v[108:111], v0, s[32:33] offset:3072
	global_load_dwordx4 v[178:181], v0, s[22:23]
	global_load_dwordx4 v[182:185], v0, s[22:23] offset:1024
	global_load_dwordx4 v[186:189], v0, s[22:23] offset:2048
	global_load_dwordx4 v[190:193], v0, s[22:23] offset:3072
	s_add_i32 s34, s3, s2
	s_add_i32 s34, s34, s2
	s_cmp_lt_i32 s34, 0x8800
	s_cbranch_scc0 .Lrn2_tail0
	s_sub_u32 s7, s34, 0x8000
	s_cmp_lt_u32 s34, 0x8000
	s_cselect_b32 s7, s34, s7
	s_cselect_b32 s8, s12, s16
	s_cselect_b32 s9, s13, s17
	s_lshl_b32 s7, s7, 12
	s_add_u32 s8, s8, s7
	s_addc_u32 s9, s9, 0
	global_load_dwordx4 v[162:165], v0, s[8:9]
	global_load_dwordx4 v[166:169], v0, s[8:9] offset:1024
	global_load_dwordx4 v[170:173], v0, s[8:9] offset:2048
	global_load_dwordx4 v[174:177], v0, s[8:9] offset:3072
	s_waitcnt vmcnt(32)
	v_mul_f32_e32 v112, v3, v3
	v_mul_f32_e32 v113, v7, v7
	v_mul_f32_e32 v114, v11, v11
	v_mul_f32_e32 v115, v15, v15
	v_fmac_f32_e32 v112, v2, v2
	v_fmac_f32_e32 v113, v6, v6
	v_fmac_f32_e32 v114, v10, v10
	v_fmac_f32_e32 v115, v14, v14
	v_fmac_f32_e32 v112, v4, v4
	v_fmac_f32_e32 v113, v8, v8
	v_fmac_f32_e32 v114, v12, v12
	v_fmac_f32_e32 v115, v16, v16
	v_fmac_f32_e32 v112, v5, v5
	v_fmac_f32_e32 v113, v9, v9
	v_fmac_f32_e32 v114, v13, v13
	v_fmac_f32_e32 v115, v17, v17
	v_add_f32_e32 v112, v112, v113
	v_add_f32_e32 v112, v112, v114
	v_add_f32_e32 v112, v112, v115
	s_nop 1
	v_add_f32_dpp v112, v112, v112 quad_perm:[1,0,3,2] row_mask:0xf bank_mask:0xf bound_ctrl:1
	s_nop 1
	v_add_f32_dpp v112, v112, v112 quad_perm:[2,3,0,1] row_mask:0xf bank_mask:0xf bound_ctrl:1
	s_nop 1
	v_add_f32_dpp v112, v112, v112 row_half_mirror row_mask:0xf bank_mask:0xf bound_ctrl:1
	s_nop 1
	v_add_f32_dpp v112, v112, v112 row_mirror row_mask:0xf bank_mask:0xf bound_ctrl:1
	s_nop 1
	ds_swizzle_b32 v113, v112 offset:swizzle(SWAP,16)
	s_waitcnt lgkmcnt(0)
	v_add_f32_e32 v112, v112, v113
	v_mov_b32_e32 v113, v112
	s_nop 1
	v_permlane32_swap_b32_e32 v112, v113
	v_add_f32_e32 v112, v112, v113
	v_fmamk_f32 v112, v112, 0x3a800000, v224
	v_rsq_f32_e32 v112, v112
	s_waitcnt vmcnt(4)
	v_mul_f32_e32 v2, v2, v112
	v_mul_f32_e32 v3, v3, v112
	v_mul_f32_e32 v4, v4, v112
	v_mul_f32_e32 v5, v5, v112
	v_mul_f32_e32 v6, v6, v112
	v_mul_f32_e32 v7, v7, v112
	v_mul_f32_e32 v8, v8, v112
	v_mul_f32_e32 v9, v9, v112
	v_mul_f32_e32 v10, v10, v112
	v_mul_f32_e32 v11, v11, v112
	v_mul_f32_e32 v12, v12, v112
	v_mul_f32_e32 v13, v13, v112
	v_mul_f32_e32 v14, v14, v112
	v_mul_f32_e32 v15, v15, v112
	v_mul_f32_e32 v16, v16, v112
	v_mul_f32_e32 v17, v17, v112
	v_mul_f32_e32 v2, v80, v2
	v_mul_f32_e32 v3, v81, v3
	v_mul_f32_e32 v4, v82, v4
	v_mul_f32_e32 v5, v83, v5
	v_mul_f32_e32 v6, v84, v6
	v_mul_f32_e32 v7, v85, v7
	v_mul_f32_e32 v8, v86, v8
	v_mul_f32_e32 v9, v87, v9
	v_mul_f32_e32 v10, v88, v10
	v_mul_f32_e32 v11, v89, v11
	v_mul_f32_e32 v12, v90, v12
	v_mul_f32_e32 v13, v91, v13
	v_mul_f32_e32 v14, v92, v14
	v_mul_f32_e32 v15, v93, v15
	v_mul_f32_e32 v16, v94, v16
	v_mul_f32_e32 v17, v95, v17
	v_add_f32_e32 v96, 1.0, v96
	v_add_f32_e32 v97, 1.0, v97
	v_add_f32_e32 v98, 1.0, v98
	v_add_f32_e32 v99, 1.0, v99
	v_add_f32_e32 v100, 1.0, v100
	v_add_f32_e32 v101, 1.0, v101
	v_add_f32_e32 v102, 1.0, v102
	v_add_f32_e32 v103, 1.0, v103
	v_add_f32_e32 v104, 1.0, v104
	v_add_f32_e32 v105, 1.0, v105
	v_add_f32_e32 v106, 1.0, v106
	v_add_f32_e32 v107, 1.0, v107
	v_add_f32_e32 v108, 1.0, v108
	v_add_f32_e32 v109, 1.0, v109
	v_add_f32_e32 v110, 1.0, v110
	v_add_f32_e32 v111, 1.0, v111
	v_fma_f32 v2, v96, v2, v178
	v_fma_f32 v3, v97, v3, v179
	v_fma_f32 v4, v98, v4, v180
	v_fma_f32 v5, v99, v5, v181
	v_fma_f32 v6, v100, v6, v182
	v_fma_f32 v7, v101, v7, v183
	v_fma_f32 v8, v102, v8, v184
	v_fma_f32 v9, v103, v9, v185
	v_fma_f32 v10, v104, v10, v186
	v_fma_f32 v11, v105, v11, v187
	v_fma_f32 v12, v106, v12, v188
	v_fma_f32 v13, v107, v13, v189
	v_fma_f32 v14, v108, v14, v190
	v_fma_f32 v15, v109, v15, v191
	v_fma_f32 v16, v110, v16, v192
	v_fma_f32 v17, v111, v17, v193
	v_cvt_pk_f16_f32 v114, v2, v3
	v_cvt_pk_f16_f32 v115, v4, v5
	v_cvt_pk_f16_f32 v116, v6, v7
	v_cvt_pk_f16_f32 v117, v8, v9
	v_cvt_pk_f16_f32 v118, v10, v11
	v_cvt_pk_f16_f32 v119, v12, v13
	v_cvt_pk_f16_f32 v120, v14, v15
	v_cvt_pk_f16_f32 v121, v16, v17
	global_store_dwordx2 v128, v[114:115], s[24:25]
	global_store_dwordx2 v128, v[116:117], s[24:25] offset:512
	global_store_dwordx2 v128, v[118:119], s[24:25] offset:1024
	global_store_dwordx2 v128, v[120:121], s[24:25] offset:1536
	s_add_i32 s3, s3, s2
; DI int TIDX() { int t = threadIdx.x; asm volatile("" : "+v"(t)); return t; }
; DI int BIDX() { int b = blockIdx.x; asm volatile("" : "+s"(b)); return b; }
; DI void rows_norm_mod(const P& p, const float* xlat, const float* xctx, int l, const float* gain, int sh_idx, int sc_idx,
;                       h16* dst, int nrows) {
;   const int lane = TIDX() & 63;
;   const int gw = BIDX() * 4 + (TIDX() >> 6), nw = gridDim.x * 4;
;   const float* mod = (const float*)(p.ws + OFF_MOD);
;   for (int row = gw; row < nrows; row += nw) {
;     const float* xr = row < TL ? xlat + (size_t)row * 1024 : xctx + (size_t)(row - TL) * 1024;
;     const int mrow = row < TL ? (row >> 12) : 8;
;     const float* mr = mod + ((size_t)l * 9 + mrow) * 6144;
;     f32x4 v[4];
;     float ss = 0.f;
; #pragma unroll
;     for (int i = 0; i < 4; ++i) {
;       v[i] = *(const f32x4*)(xr + lane * 4 + 256 * i);
;       ss += v[i].x * v[i].x + v[i].y * v[i].y + v[i].z * v[i].z + v[i].w * v[i].w;
;     }
;     ss = wave_sum(ss);
;     const float rstd = rsqrtf(ss * (1.f / 1024.f) + EPS);
; #pragma unroll
;     for (int i = 0; i < 4; ++i) {
;       const int c = lane * 4 + 256 * i;
;       f32x4 g = *(const f32x4*)(gain + c), sc = *(const f32x4*)(mr + sc_idx * 1024 + c), sh = *(const f32x4*)(mr + sh_idx * 1024 + c);
;       h16x4 o;
;       o.x = (h16)(v[i].x * rstd * g.x * (1.f + sc.x) + sh.x);
;       o.y = (h16)(v[i].y * rstd * g.y * (1.f + sc.y) + sh.y);
;       o.z = (h16)(v[i].z * rstd * g.z * (1.f + sc.z) + sh.z);
;       o.w = (h16)(v[i].w * rstd * g.w * (1.f + sc.w) + sh.w);
;       *(h16x4*)(dst + (size_t)row * 1024 + c) = o;
;     }
;   }
; }
.Lrn2_l1:
	s_lshr_b32 s6, s3, 12
	s_cmp_lt_u32 s3, 0x8000
	s_cselect_b32 s6, s6, 8
	s_mul_i32 s6, s6, 0x6000
	s_add_u32 s22, s4, s6
	s_addc_u32 s23, s5, 0
	s_add_u32 s32, s22, 0x1000
	s_addc_u32 s33, s23, 0
	s_lshl_b32 s6, s3, 11
	s_add_u32 s24, s18, s6
	s_addc_u32 s25, s19, 0
	global_load_dwordx4 v[96:99], v0, s[32:33]
	global_load_dwordx4 v[100:103], v0, s[32:33] offset:1024
	global_load_dwordx4 v[104:107], v0, s[32:33] offset:2048
	global_load_dwordx4 v[108:111], v0, s[32:33] offset:3072
	global_load_dwordx4 v[178:181], v0, s[22:23]
	global_load_dwordx4 v[182:185], v0, s[22:23] offset:1024
	global_load_dwordx4 v[186:189], v0, s[22:23] offset:2048
	global_load_dwordx4 v[190:193], v0, s[22:23] offset:3072
	s_add_i32 s34, s3, s2
	s_add_i32 s34, s34, s2
	s_cmp_lt_i32 s34, 0x8800
	s_cbranch_scc0 .Lrn2_tail1
	s_sub_u32 s7, s34, 0x8000
	s_cmp_lt_u32 s34, 0x8000
	s_cselect_b32 s7, s34, s7
	s_cselect_b32 s8, s12, s16
	s_cselect_b32 s9, s13, s17
	s_lshl_b32 s7, s7, 12
	s_add_u32 s8, s8, s7
	s_addc_u32 s9, s9, 0
	global_load_dwordx4 v[2:5], v0, s[8:9]
	global_load_dwordx4 v[6:9], v0, s[8:9] offset:1024
	global_load_dwordx4 v[10:13], v0, s[8:9] offset:2048
	global_load_dwordx4 v[14:17], v0, s[8:9] offset:3072
	s_waitcnt vmcnt(32)
	v_mul_f32_e32 v112, v33, v33
	v_mul_f32_e32 v113, v37, v37
	v_mul_f32_e32 v114, v41, v41
	v_mul_f32_e32 v115, v45, v45
	v_fmac_f32_e32 v112, v32, v32
	v_fmac_f32_e32 v113, v36, v36
	v_fmac_f32_e32 v114, v40, v40
	v_fmac_f32_e32 v115, v44, v44
	v_fmac_f32_e32 v112, v34, v34
	v_fmac_f32_e32 v113, v38, v38
	v_fmac_f32_e32 v114, v42, v42
	v_fmac_f32_e32 v115, v46, v46
	v_fmac_f32_e32 v112, v35, v35
	v_fmac_f32_e32 v113, v39, v39
	v_fmac_f32_e32 v114, v43, v43
	v_fmac_f32_e32 v115, v47, v47
	v_add_f32_e32 v112, v112, v113
	v_add_f32_e32 v112, v112, v114
	v_add_f32_e32 v112, v112, v115
	s_nop 1
	v_add_f32_dpp v112, v112, v112 quad_perm:[1,0,3,2] row_mask:0xf bank_mask:0xf bound_ctrl:1
	s_nop 1
	v_add_f32_dpp v112, v112, v112 quad_perm:[2,3,0,1] row_mask:0xf bank_mask:0xf bound_ctrl:1
	s_nop 1
	v_add_f32_dpp v112, v112, v112 row_half_mirror row_mask:0xf bank_mask:0xf bound_ctrl:1
	s_nop 1
	v_add_f32_dpp v112, v112, v112 row_mirror row_mask:0xf bank_mask:0xf bound_ctrl:1
	s_nop 1
	ds_swizzle_b32 v113, v112 offset:swizzle(SWAP,16)
	s_waitcnt lgkmcnt(0)
	v_add_f32_e32 v112, v112, v113
	v_mov_b32_e32 v113, v112
	s_nop 1
	v_permlane32_swap_b32_e32 v112, v113
	v_add_f32_e32 v112, v112, v113
	v_fmamk_f32 v112, v112, 0x3a800000, v224
	v_rsq_f32_e32 v112, v112
	s_waitcnt vmcnt(4)
	v_mul_f32_e32 v32, v32, v112
	v_mul_f32_e32 v33, v33, v112
	v_mul_f32_e32 v34, v34, v112
	v_mul_f32_e32 v35, v35, v112
	v_mul_f32_e32 v36, v36, v112
	v_mul_f32_e32 v37, v37, v112
	v_mul_f32_e32 v38, v38, v112
	v_mul_f32_e32 v39, v39, v112
	v_mul_f32_e32 v40, v40, v112
	v_mul_f32_e32 v41, v41, v112
	v_mul_f32_e32 v42, v42, v112
	v_mul_f32_e32 v43, v43, v112
	v_mul_f32_e32 v44, v44, v112
	v_mul_f32_e32 v45, v45, v112
	v_mul_f32_e32 v46, v46, v112
	v_mul_f32_e32 v47, v47, v112
	v_mul_f32_e32 v32, v80, v32
	v_mul_f32_e32 v33, v81, v33
	v_mul_f32_e32 v34, v82, v34
	v_mul_f32_e32 v35, v83, v35
	v_mul_f32_e32 v36, v84, v36
	v_mul_f32_e32 v37, v85, v37
	v_mul_f32_e32 v38, v86, v38
	v_mul_f32_e32 v39, v87, v39
	v_mul_f32_e32 v40, v88, v40
	v_mul_f32_e32 v41, v89, v41
	v_mul_f32_e32 v42, v90, v42
	v_mul_f32_e32 v43, v91, v43
	v_mul_f32_e32 v44, v92, v44
	v_mul_f32_e32 v45, v93, v45
	v_mul_f32_e32 v46, v94, v46
	v_mul_f32_e32 v47, v95, v47
	v_add_f32_e32 v96, 1.0, v96
	v_add_f32_e32 v97, 1.0, v97
	v_add_f32_e32 v98, 1.0, v98
	v_add_f32_e32 v99, 1.0, v99
	v_add_f32_e32 v100, 1.0, v100
	v_add_f32_e32 v101, 1.0, v101
	v_add_f32_e32 v102, 1.0, v102
	v_add_f32_e32 v103, 1.0, v103
	v_add_f32_e32 v104, 1.0, v104
	v_add_f32_e32 v105, 1.0, v105
	v_add_f32_e32 v106, 1.0, v106
	v_add_f32_e32 v107, 1.0, v107
	v_add_f32_e32 v108, 1.0, v108
	v_add_f32_e32 v109, 1.0, v109
	v_add_f32_e32 v110, 1.0, v110
	v_add_f32_e32 v111, 1.0, v111
	v_fma_f32 v32, v96, v32, v178
	v_fma_f32 v33, v97, v33, v179
	v_fma_f32 v34, v98, v34, v180
	v_fma_f32 v35, v99, v35, v181
	v_fma_f32 v36, v100, v36, v182
	v_fma_f32 v37, v101, v37, v183
	v_fma_f32 v38, v102, v38, v184
	v_fma_f32 v39, v103, v39, v185
	v_fma_f32 v40, v104, v40, v186
	v_fma_f32 v41, v105, v41, v187
	v_fma_f32 v42, v106, v42, v188
	v_fma_f32 v43, v107, v43, v189
	v_fma_f32 v44, v108, v44, v190
	v_fma_f32 v45, v109, v45, v191
	v_fma_f32 v46, v110, v46, v192
	v_fma_f32 v47, v111, v47, v193
	v_cvt_pk_f16_f32 v114, v32, v33
	v_cvt_pk_f16_f32 v115, v34, v35
	v_cvt_pk_f16_f32 v116, v36, v37
	v_cvt_pk_f16_f32 v117, v38, v39
	v_cvt_pk_f16_f32 v118, v40, v41
	v_cvt_pk_f16_f32 v119, v42, v43
	v_cvt_pk_f16_f32 v120, v44, v45
	v_cvt_pk_f16_f32 v121, v46, v47
	global_store_dwordx2 v128, v[114:115], s[24:25]
	global_store_dwordx2 v128, v[116:117], s[24:25] offset:512
	global_store_dwordx2 v128, v[118:119], s[24:25] offset:1024
	global_store_dwordx2 v128, v[120:121], s[24:25] offset:1536
	s_add_i32 s3, s3, s2
	s_branch .Lrn2_l2
; DI int TIDX() { int t = threadIdx.x; asm volatile("" : "+v"(t)); return t; }
; DI int BIDX() { int b = blockIdx.x; asm volatile("" : "+s"(b)); return b; }
; DI void rows_norm_mod(const P& p, const float* xlat, const float* xctx, int l, const float* gain, int sh_idx, int sc_idx,
;                       h16* dst, int nrows) {
;   const int lane = TIDX() & 63;
;   const int gw = BIDX() * 4 + (TIDX() >> 6), nw = gridDim.x * 4;
;   const float* mod = (const float*)(p.ws + OFF_MOD);
;   for (int row = gw; row < nrows; row += nw) {
;     const float* xr = row < TL ? xlat + (size_t)row * 1024 : xctx + (size_t)(row - TL) * 1024;
;     const int mrow = row < TL ? (row >> 12) : 8;
;     const float* mr = mod + ((size_t)l * 9 + mrow) * 6144;
;     f32x4 v[4];
;     float ss = 0.f;
; #pragma unroll
;     for (int i = 0; i < 4; ++i) {
;       v[i] = *(const f32x4*)(xr + lane * 4 + 256 * i);
;       ss += v[i].x * v[i].x + v[i].y * v[i].y + v[i].z * v[i].z + v[i].w * v[i].w;
;     }
;     ss = wave_sum(ss);
;     const float rstd = rsqrtf(ss * (1.f / 1024.f) + EPS);
; #pragma unroll
;     for (int i = 0; i < 4; ++i) {
;       const int c = lane * 4 + 256 * i;
;       f32x4 g = *(const f32x4*)(gain + c), sc = *(const f32x4*)(mr + sc_idx * 1024 + c), sh = *(const f32x4*)(mr + sh_idx * 1024 + c);
;       h16x4 o;
;       o.x = (h16)(v[i].x * rstd * g.x * (1.f + sc.x) + sh.x);
;       o.y = (h16)(v[i].y * rstd * g.y * (1.f + sc.y) + sh.y);
;       o.z = (h16)(v[i].z * rstd * g.z * (1.f + sc.z) + sh.z);
;       o.w = (h16)(v[i].w * rstd * g.w * (1.f + sc.w) + sh.w);
;       *(h16x4*)(dst + (size_t)row * 1024 + c) = o;
;     }
;   }
; }
.Lrn2_tail0:
	s_waitcnt vmcnt(8)
	v_mul_f32_e32 v112, v3, v3
	v_mul_f32_e32 v113, v7, v7
	v_mul_f32_e32 v114, v11, v11
	v_mul_f32_e32 v115, v15, v15
	v_fmac_f32_e32 v112, v2, v2
	v_fmac_f32_e32 v113, v6, v6
	v_fmac_f32_e32 v114, v10, v10
	v_fmac_f32_e32 v115, v14, v14
	v_fmac_f32_e32 v112, v4, v4
	v_fmac_f32_e32 v113, v8, v8
	v_fmac_f32_e32 v114, v12, v12
	v_fmac_f32_e32 v115, v16, v16
	v_fmac_f32_e32 v112, v5, v5
	v_fmac_f32_e32 v113, v9, v9
	v_fmac_f32_e32 v114, v13, v13
	v_fmac_f32_e32 v115, v17, v17
	v_add_f32_e32 v112, v112, v113
	v_add_f32_e32 v112, v112, v114
	v_add_f32_e32 v112, v112, v115
	s_nop 1
	v_add_f32_dpp v112, v112, v112 quad_perm:[1,0,3,2] row_mask:0xf bank_mask:0xf bound_ctrl:1
	s_nop 1
	v_add_f32_dpp v112, v112, v112 quad_perm:[2,3,0,1] row_mask:0xf bank_mask:0xf bound_ctrl:1
	s_nop 1
	v_add_f32_dpp v112, v112, v112 row_half_mirror row_mask:0xf bank_mask:0xf bound_ctrl:1
	s_nop 1
	v_add_f32_dpp v112, v112, v112 row_mirror row_mask:0xf bank_mask:0xf bound_ctrl:1
	s_nop 1
	ds_swizzle_b32 v113, v112 offset:swizzle(SWAP,16)
	s_waitcnt lgkmcnt(0)
	v_add_f32_e32 v112, v112, v113
	v_mov_b32_e32 v113, v112
	s_nop 1
	v_permlane32_swap_b32_e32 v112, v113
	v_add_f32_e32 v112, v112, v113
	v_fmamk_f32 v112, v112, 0x3a800000, v224
	v_rsq_f32_e32 v112, v112
	s_waitcnt vmcnt(0)
	v_mul_f32_e32 v2, v2, v112
	v_mul_f32_e32 v3, v3, v112
	v_mul_f32_e32 v4, v4, v112
	v_mul_f32_e32 v5, v5, v112
	v_mul_f32_e32 v6, v6, v112
	v_mul_f32_e32 v7, v7, v112
	v_mul_f32_e32 v8, v8, v112
	v_mul_f32_e32 v9, v9, v112
	v_mul_f32_e32 v10, v10, v112
	v_mul_f32_e32 v11, v11, v112
	v_mul_f32_e32 v12, v12, v112
	v_mul_f32_e32 v13, v13, v112
	v_mul_f32_e32 v14, v14, v112
	v_mul_f32_e32 v15, v15, v112
	v_mul_f32_e32 v16, v16, v112
	v_mul_f32_e32 v17, v17, v112
	v_mul_f32_e32 v2, v80, v2
	v_mul_f32_e32 v3, v81, v3
	v_mul_f32_e32 v4, v82, v4
	v_mul_f32_e32 v5, v83, v5
	v_mul_f32_e32 v6, v84, v6
	v_mul_f32_e32 v7, v85, v7
	v_mul_f32_e32 v8, v86, v8
	v_mul_f32_e32 v9, v87, v9
	v_mul_f32_e32 v10, v88, v10
	v_mul_f32_e32 v11, v89, v11
	v_mul_f32_e32 v12, v90, v12
	v_mul_f32_e32 v13, v91, v13
	v_mul_f32_e32 v14, v92, v14
	v_mul_f32_e32 v15, v93, v15
	v_mul_f32_e32 v16, v94, v16
	v_mul_f32_e32 v17, v95, v17
	v_add_f32_e32 v96, 1.0, v96
	v_add_f32_e32 v97, 1.0, v97
	v_add_f32_e32 v98, 1.0, v98
	v_add_f32_e32 v99, 1.0, v99
	v_add_f32_e32 v100, 1.0, v100
	v_add_f32_e32 v101, 1.0, v101
	v_add_f32_e32 v102, 1.0, v102
	v_add_f32_e32 v103, 1.0, v103
	v_add_f32_e32 v104, 1.0, v104
	v_add_f32_e32 v105, 1.0, v105
	v_add_f32_e32 v106, 1.0, v106
	v_add_f32_e32 v107, 1.0, v107
	v_add_f32_e32 v108, 1.0, v108
	v_add_f32_e32 v109, 1.0, v109
	v_add_f32_e32 v110, 1.0, v110
	v_add_f32_e32 v111, 1.0, v111
	v_fma_f32 v2, v96, v2, v178
	v_fma_f32 v3, v97, v3, v179
	v_fma_f32 v4, v98, v4, v180
	v_fma_f32 v5, v99, v5, v181
	v_fma_f32 v6, v100, v6, v182
	v_fma_f32 v7, v101, v7, v183
	v_fma_f32 v8, v102, v8, v184
	v_fma_f32 v9, v103, v9, v185
	v_fma_f32 v10, v104, v10, v186
	v_fma_f32 v11, v105, v11, v187
	v_fma_f32 v12, v106, v12, v188
	v_fma_f32 v13, v107, v13, v189
	v_fma_f32 v14, v108, v14, v190
	v_fma_f32 v15, v109, v15, v191
	v_fma_f32 v16, v110, v16, v192
	v_fma_f32 v17, v111, v17, v193
	v_cvt_pk_f16_f32 v114, v2, v3
	v_cvt_pk_f16_f32 v115, v4, v5
	v_cvt_pk_f16_f32 v116, v6, v7
	v_cvt_pk_f16_f32 v117, v8, v9
	v_cvt_pk_f16_f32 v118, v10, v11
	v_cvt_pk_f16_f32 v119, v12, v13
	v_cvt_pk_f16_f32 v120, v14, v15
	v_cvt_pk_f16_f32 v121, v16, v17
	global_store_dwordx2 v128, v[114:115], s[24:25]
	global_store_dwordx2 v128, v[116:117], s[24:25] offset:512
	global_store_dwordx2 v128, v[118:119], s[24:25] offset:1024
	global_store_dwordx2 v128, v[120:121], s[24:25] offset:1536
	s_add_i32 s3, s3, s2
	s_cmp_lt_i32 s3, 0x8800
	s_cbranch_scc0 .Lrn2_exit
	s_lshr_b32 s6, s3, 12
	s_cmp_lt_u32 s3, 0x8000
	s_cselect_b32 s6, s6, 8
	s_mul_i32 s6, s6, 0x6000
	s_add_u32 s22, s4, s6
	s_addc_u32 s23, s5, 0
	s_add_u32 s32, s22, 0x1000
	s_addc_u32 s33, s23, 0
	s_lshl_b32 s6, s3, 11
	s_add_u32 s24, s18, s6
	s_addc_u32 s25, s19, 0
	global_load_dwordx4 v[96:99], v0, s[32:33]
	global_load_dwordx4 v[100:103], v0, s[32:33] offset:1024
	global_load_dwordx4 v[104:107], v0, s[32:33] offset:2048
	global_load_dwordx4 v[108:111], v0, s[32:33] offset:3072
	global_load_dwordx4 v[178:181], v0, s[22:23]
	global_load_dwordx4 v[182:185], v0, s[22:23] offset:1024
	global_load_dwordx4 v[186:189], v0, s[22:23] offset:2048
	global_load_dwordx4 v[190:193], v0, s[22:23] offset:3072
	s_waitcnt vmcnt(8)
	v_mul_f32_e32 v112, v33, v33
	v_mul_f32_e32 v113, v37, v37
	v_mul_f32_e32 v114, v41, v41
	v_mul_f32_e32 v115, v45, v45
	v_fmac_f32_e32 v112, v32, v32
	v_fmac_f32_e32 v113, v36, v36
	v_fmac_f32_e32 v114, v40, v40
	v_fmac_f32_e32 v115, v44, v44
	v_fmac_f32_e32 v112, v34, v34
	v_fmac_f32_e32 v113, v38, v38
	v_fmac_f32_e32 v114, v42, v42
	v_fmac_f32_e32 v115, v46, v46
	v_fmac_f32_e32 v112, v35, v35
	v_fmac_f32_e32 v113, v39, v39
	v_fmac_f32_e32 v114, v43, v43
	v_fmac_f32_e32 v115, v47, v47
	v_add_f32_e32 v112, v112, v113
	v_add_f32_e32 v112, v112, v114
	v_add_f32_e32 v112, v112, v115
	s_nop 1
	v_add_f32_dpp v112, v112, v112 quad_perm:[1,0,3,2] row_mask:0xf bank_mask:0xf bound_ctrl:1
	s_nop 1
	v_add_f32_dpp v112, v112, v112 quad_perm:[2,3,0,1] row_mask:0xf bank_mask:0xf bound_ctrl:1
	s_nop 1
	v_add_f32_dpp v112, v112, v112 row_half_mirror row_mask:0xf bank_mask:0xf bound_ctrl:1
	s_nop 1
	v_add_f32_dpp v112, v112, v112 row_mirror row_mask:0xf bank_mask:0xf bound_ctrl:1
	s_nop 1
	ds_swizzle_b32 v113, v112 offset:swizzle(SWAP,16)
	s_waitcnt lgkmcnt(0)
; DI int TIDX() { int t = threadIdx.x; asm volatile("" : "+v"(t)); return t; }
; DI int BIDX() { int b = blockIdx.x; asm volatile("" : "+s"(b)); return b; }
; DI void rows_norm_mod(const P& p, const float* xlat, const float* xctx, int l, const float* gain, int sh_idx, int sc_idx,
;                       h16* dst, int nrows) {
;   const int lane = TIDX() & 63;
;   const int gw = BIDX() * 4 + (TIDX() >> 6), nw = gridDim.x * 4;
;   const float* mod = (const float*)(p.ws + OFF_MOD);
;   for (int row = gw; row < nrows; row += nw) {
;     const float* xr = row < TL ? xlat + (size_t)row * 1024 : xctx + (size_t)(row - TL) * 1024;
;     const int mrow = row < TL ? (row >> 12) : 8;
;     const float* mr = mod + ((size_t)l * 9 + mrow) * 6144;
;     f32x4 v[4];
;     float ss = 0.f;
; #pragma unroll
;     for (int i = 0; i < 4; ++i) {
;       v[i] = *(const f32x4*)(xr + lane * 4 + 256 * i);
;       ss += v[i].x * v[i].x + v[i].y * v[i].y + v[i].z * v[i].z + v[i].w * v[i].w;
;     }
;     ss = wave_sum(ss);
;     const float rstd = rsqrtf(ss * (1.f / 1024.f) + EPS);
; #pragma unroll
;     for (int i = 0; i < 4; ++i) {
;       const int c = lane * 4 + 256 * i;
;       f32x4 g = *(const f32x4*)(gain + c), sc = *(const f32x4*)(mr + sc_idx * 1024 + c), sh = *(const f32x4*)(mr + sh_idx * 1024 + c);
;       h16x4 o;
;       o.x = (h16)(v[i].x * rstd * g.x * (1.f + sc.x) + sh.x);
;       o.y = (h16)(v[i].y * rstd * g.y * (1.f + sc.y) + sh.y);
;       o.z = (h16)(v[i].z * rstd * g.z * (1.f + sc.z) + sh.z);
;       o.w = (h16)(v[i].w * rstd * g.w * (1.f + sc.w) + sh.w);
;       *(h16x4*)(dst + (size_t)row * 1024 + c) = o;
;     }
;   }
; }
	v_add_f32_e32 v112, v112, v113
	v_mov_b32_e32 v113, v112
	s_nop 1
	v_permlane32_swap_b32_e32 v112, v113
	v_add_f32_e32 v112, v112, v113
	v_fmamk_f32 v112, v112, 0x3a800000, v224
	v_rsq_f32_e32 v112, v112
	s_waitcnt vmcnt(0)
	v_mul_f32_e32 v32, v32, v112
	v_mul_f32_e32 v33, v33, v112
	v_mul_f32_e32 v34, v34, v112
	v_mul_f32_e32 v35, v35, v112
	v_mul_f32_e32 v36, v36, v112
	v_mul_f32_e32 v37, v37, v112
	v_mul_f32_e32 v38, v38, v112
	v_mul_f32_e32 v39, v39, v112
	v_mul_f32_e32 v40, v40, v112
	v_mul_f32_e32 v41, v41, v112
	v_mul_f32_e32 v42, v42, v112
	v_mul_f32_e32 v43, v43, v112
	v_mul_f32_e32 v44, v44, v112
	v_mul_f32_e32 v45, v45, v112
	v_mul_f32_e32 v46, v46, v112
	v_mul_f32_e32 v47, v47, v112
	v_mul_f32_e32 v32, v80, v32
	v_mul_f32_e32 v33, v81, v33
	v_mul_f32_e32 v34, v82, v34
	v_mul_f32_e32 v35, v83, v35
	v_mul_f32_e32 v36, v84, v36
	v_mul_f32_e32 v37, v85, v37
	v_mul_f32_e32 v38, v86, v38
	v_mul_f32_e32 v39, v87, v39
	v_mul_f32_e32 v40, v88, v40
	v_mul_f32_e32 v41, v89, v41
	v_mul_f32_e32 v42, v90, v42
	v_mul_f32_e32 v43, v91, v43
	v_mul_f32_e32 v44, v92, v44
	v_mul_f32_e32 v45, v93, v45
	v_mul_f32_e32 v46, v94, v46
	v_mul_f32_e32 v47, v95, v47
	v_add_f32_e32 v96, 1.0, v96
	v_add_f32_e32 v97, 1.0, v97
	v_add_f32_e32 v98, 1.0, v98
	v_add_f32_e32 v99, 1.0, v99
	v_add_f32_e32 v100, 1.0, v100
	v_add_f32_e32 v101, 1.0, v101
	v_add_f32_e32 v102, 1.0, v102
	v_add_f32_e32 v103, 1.0, v103
	v_add_f32_e32 v104, 1.0, v104
	v_add_f32_e32 v105, 1.0, v105
	v_add_f32_e32 v106, 1.0, v106
	v_add_f32_e32 v107, 1.0, v107
	v_add_f32_e32 v108, 1.0, v108
	v_add_f32_e32 v109, 1.0, v109
	v_add_f32_e32 v110, 1.0, v110
	v_add_f32_e32 v111, 1.0, v111
	v_fma_f32 v32, v96, v32, v178
	v_fma_f32 v33, v97, v33, v179
	v_fma_f32 v34, v98, v34, v180
	v_fma_f32 v35, v99, v35, v181
	v_fma_f32 v36, v100, v36, v182
	v_fma_f32 v37, v101, v37, v183
	v_fma_f32 v38, v102, v38, v184
	v_fma_f32 v39, v103, v39, v185
	v_fma_f32 v40, v104, v40, v186
	v_fma_f32 v41, v105, v41, v187
	v_fma_f32 v42, v106, v42, v188
	v_fma_f32 v43, v107, v43, v189
	v_fma_f32 v44, v108, v44, v190
	v_fma_f32 v45, v109, v45, v191
	v_fma_f32 v46, v110, v46, v192
	v_fma_f32 v47, v111, v47, v193
	v_cvt_pk_f16_f32 v114, v32, v33
	v_cvt_pk_f16_f32 v115, v34, v35
	v_cvt_pk_f16_f32 v116, v36, v37
	v_cvt_pk_f16_f32 v117, v38, v39
	v_cvt_pk_f16_f32 v118, v40, v41
	v_cvt_pk_f16_f32 v119, v42, v43
	v_cvt_pk_f16_f32 v120, v44, v45
	v_cvt_pk_f16_f32 v121, v46, v47
	global_store_dwordx2 v128, v[114:115], s[24:25]
	global_store_dwordx2 v128, v[116:117], s[24:25] offset:512
	global_store_dwordx2 v128, v[118:119], s[24:25] offset:1024
	global_store_dwordx2 v128, v[120:121], s[24:25] offset:1536
	s_add_i32 s3, s3, s2
	s_branch .Lrn2_exit
.Lrn2_tail1:
	s_waitcnt vmcnt(8)
	v_mul_f32_e32 v112, v33, v33
	v_mul_f32_e32 v113, v37, v37
	v_mul_f32_e32 v114, v41, v41
	v_mul_f32_e32 v115, v45, v45
	v_fmac_f32_e32 v112, v32, v32
	v_fmac_f32_e32 v113, v36, v36
	v_fmac_f32_e32 v114, v40, v40
	v_fmac_f32_e32 v115, v44, v44
	v_fmac_f32_e32 v112, v34, v34
	v_fmac_f32_e32 v113, v38, v38
	v_fmac_f32_e32 v114, v42, v42
	v_fmac_f32_e32 v115, v46, v46
	v_fmac_f32_e32 v112, v35, v35
	v_fmac_f32_e32 v113, v39, v39
	v_fmac_f32_e32 v114, v43, v43
	v_fmac_f32_e32 v115, v47, v47
	v_add_f32_e32 v112, v112, v113
	v_add_f32_e32 v112, v112, v114
	v_add_f32_e32 v112, v112, v115
	s_nop 1
	v_add_f32_dpp v112, v112, v112 quad_perm:[1,0,3,2] row_mask:0xf bank_mask:0xf bound_ctrl:1
	s_nop 1
	v_add_f32_dpp v112, v112, v112 quad_perm:[2,3,0,1] row_mask:0xf bank_mask:0xf bound_ctrl:1
	s_nop 1
	v_add_f32_dpp v112, v112, v112 row_half_mirror row_mask:0xf bank_mask:0xf bound_ctrl:1
	s_nop 1
	v_add_f32_dpp v112, v112, v112 row_mirror row_mask:0xf bank_mask:0xf bound_ctrl:1
	s_nop 1
	ds_swizzle_b32 v113, v112 offset:swizzle(SWAP,16)
	s_waitcnt lgkmcnt(0)
	v_add_f32_e32 v112, v112, v113
	v_mov_b32_e32 v113, v112
	s_nop 1
	v_permlane32_swap_b32_e32 v112, v113
	v_add_f32_e32 v112, v112, v113
	v_fmamk_f32 v112, v112, 0x3a800000, v224
	v_rsq_f32_e32 v112, v112
	s_waitcnt vmcnt(0)
	v_mul_f32_e32 v32, v32, v112
	v_mul_f32_e32 v33, v33, v112
	v_mul_f32_e32 v34, v34, v112
	v_mul_f32_e32 v35, v35, v112
	v_mul_f32_e32 v36, v36, v112
	v_mul_f32_e32 v37, v37, v112
	v_mul_f32_e32 v38, v38, v112
	v_mul_f32_e32 v39, v39, v112
	v_mul_f32_e32 v40, v40, v112
	v_mul_f32_e32 v41, v41, v112
	v_mul_f32_e32 v42, v42, v112
	v_mul_f32_e32 v43, v43, v112
	v_mul_f32_e32 v44, v44, v112
	v_mul_f32_e32 v45, v45, v112
	v_mul_f32_e32 v46, v46, v112
	v_mul_f32_e32 v47, v47, v112
	v_mul_f32_e32 v32, v80, v32
	v_mul_f32_e32 v33, v81, v33
	v_mul_f32_e32 v34, v82, v34
	v_mul_f32_e32 v35, v83, v35
	v_mul_f32_e32 v36, v84, v36
	v_mul_f32_e32 v37, v85, v37
	v_mul_f32_e32 v38, v86, v38
	v_mul_f32_e32 v39, v87, v39
	v_mul_f32_e32 v40, v88, v40
	v_mul_f32_e32 v41, v89, v41
	v_mul_f32_e32 v42, v90, v42
	v_mul_f32_e32 v43, v91, v43
	v_mul_f32_e32 v44, v92, v44
	v_mul_f32_e32 v45, v93, v45
	v_mul_f32_e32 v46, v94, v46
	v_mul_f32_e32 v47, v95, v47
	v_add_f32_e32 v96, 1.0, v96
	v_add_f32_e32 v97, 1.0, v97
	v_add_f32_e32 v98, 1.0, v98
	v_add_f32_e32 v99, 1.0, v99
	v_add_f32_e32 v100, 1.0, v100
	v_add_f32_e32 v101, 1.0, v101
	v_add_f32_e32 v102, 1.0, v102
	v_add_f32_e32 v103, 1.0, v103
	v_add_f32_e32 v104, 1.0, v104
	v_add_f32_e32 v105, 1.0, v105
	v_add_f32_e32 v106, 1.0, v106
	v_add_f32_e32 v107, 1.0, v107
	v_add_f32_e32 v108, 1.0, v108
	v_add_f32_e32 v109, 1.0, v109
	v_add_f32_e32 v110, 1.0, v110
	v_add_f32_e32 v111, 1.0, v111
	v_fma_f32 v32, v96, v32, v178
	v_fma_f32 v33, v97, v33, v179
	v_fma_f32 v34, v98, v34, v180
	v_fma_f32 v35, v99, v35, v181
	v_fma_f32 v36, v100, v36, v182
	v_fma_f32 v37, v101, v37, v183
	v_fma_f32 v38, v102, v38, v184
	v_fma_f32 v39, v103, v39, v185
	v_fma_f32 v40, v104, v40, v186
	v_fma_f32 v41, v105, v41, v187
	v_fma_f32 v42, v106, v42, v188
	v_fma_f32 v43, v107, v43, v189
	v_fma_f32 v44, v108, v44, v190
	v_fma_f32 v45, v109, v45, v191
	v_fma_f32 v46, v110, v46, v192
	v_fma_f32 v47, v111, v47, v193
	v_cvt_pk_f16_f32 v114, v32, v33
	v_cvt_pk_f16_f32 v115, v34, v35
	v_cvt_pk_f16_f32 v116, v36, v37
	v_cvt_pk_f16_f32 v117, v38, v39
	v_cvt_pk_f16_f32 v118, v40, v41
	v_cvt_pk_f16_f32 v119, v42, v43
	v_cvt_pk_f16_f32 v120, v44, v45
	v_cvt_pk_f16_f32 v121, v46, v47
	global_store_dwordx2 v128, v[114:115], s[24:25]
	global_store_dwordx2 v128, v[116:117], s[24:25] offset:512
	global_store_dwordx2 v128, v[118:119], s[24:25] offset:1024
	global_store_dwordx2 v128, v[120:121], s[24:25] offset:1536
	s_add_i32 s3, s3, s2
	s_cmp_lt_i32 s3, 0x8800
	s_cbranch_scc0 .Lrn2_exit
; DI int TIDX() { int t = threadIdx.x; asm volatile("" : "+v"(t)); return t; }
; DI int BIDX() { int b = blockIdx.x; asm volatile("" : "+s"(b)); return b; }
; DI void rows_norm_mod(const P& p, const float* xlat, const float* xctx, int l, const float* gain, int sh_idx, int sc_idx,
;                       h16* dst, int nrows) {
;   const int lane = TIDX() & 63;
;   const int gw = BIDX() * 4 + (TIDX() >> 6), nw = gridDim.x * 4;
;   const float* mod = (const float*)(p.ws + OFF_MOD);
;   for (int row = gw; row < nrows; row += nw) {
;     const float* xr = row < TL ? xlat + (size_t)row * 1024 : xctx + (size_t)(row - TL) * 1024;
;     const int mrow = row < TL ? (row >> 12) : 8;
;     const float* mr = mod + ((size_t)l * 9 + mrow) * 6144;
;     f32x4 v[4];
;     float ss = 0.f;
; #pragma unroll
;     for (int i = 0; i < 4; ++i) {
;       v[i] = *(const f32x4*)(xr + lane * 4 + 256 * i);
;       ss += v[i].x * v[i].x + v[i].y * v[i].y + v[i].z * v[i].z + v[i].w * v[i].w;
;     }
;     ss = wave_sum(ss);
;     const float rstd = rsqrtf(ss * (1.f / 1024.f) + EPS);
; #pragma unroll
;     for (int i = 0; i < 4; ++i) {
;       const int c = lane * 4 + 256 * i;
;       f32x4 g = *(const f32x4*)(gain + c), sc = *(const f32x4*)(mr + sc_idx * 1024 + c), sh = *(const f32x4*)(mr + sh_idx * 1024 + c);
;       h16x4 o;
;       o.x = (h16)(v[i].x * rstd * g.x * (1.f + sc.x) + sh.x);
;       o.y = (h16)(v[i].y * rstd * g.y * (1.f + sc.y) + sh.y);
;       o.z = (h16)(v[i].z * rstd * g.z * (1.f + sc.z) + sh.z);
;       o.w = (h16)(v[i].w * rstd * g.w * (1.f + sc.w) + sh.w);
;       *(h16x4*)(dst + (size_t)row * 1024 + c) = o;
;     }
;   }
; }
	s_lshr_b32 s6, s3, 12
	s_cmp_lt_u32 s3, 0x8000
	s_cselect_b32 s6, s6, 8
	s_mul_i32 s6, s6, 0x6000
	s_add_u32 s22, s4, s6
	s_addc_u32 s23, s5, 0
	s_add_u32 s32, s22, 0x1000
	s_addc_u32 s33, s23, 0
	s_lshl_b32 s6, s3, 11
	s_add_u32 s24, s18, s6
	s_addc_u32 s25, s19, 0
	global_load_dwordx4 v[96:99], v0, s[32:33]
	global_load_dwordx4 v[100:103], v0, s[32:33] offset:1024
	global_load_dwordx4 v[104:107], v0, s[32:33] offset:2048
	global_load_dwordx4 v[108:111], v0, s[32:33] offset:3072
	global_load_dwordx4 v[178:181], v0, s[22:23]
	global_load_dwordx4 v[182:185], v0, s[22:23] offset:1024
	global_load_dwordx4 v[186:189], v0, s[22:23] offset:2048
	global_load_dwordx4 v[190:193], v0, s[22:23] offset:3072
	s_waitcnt vmcnt(8)
	v_mul_f32_e32 v112, v163, v163
	v_mul_f32_e32 v113, v167, v167
	v_mul_f32_e32 v114, v171, v171
	v_mul_f32_e32 v115, v175, v175
	v_fmac_f32_e32 v112, v162, v162
	v_fmac_f32_e32 v113, v166, v166
	v_fmac_f32_e32 v114, v170, v170
	v_fmac_f32_e32 v115, v174, v174
	v_fmac_f32_e32 v112, v164, v164
	v_fmac_f32_e32 v113, v168, v168
	v_fmac_f32_e32 v114, v172, v172
	v_fmac_f32_e32 v115, v176, v176
	v_fmac_f32_e32 v112, v165, v165
	v_fmac_f32_e32 v113, v169, v169
	v_fmac_f32_e32 v114, v173, v173
	v_fmac_f32_e32 v115, v177, v177
	v_add_f32_e32 v112, v112, v113
	v_add_f32_e32 v112, v112, v114
	v_add_f32_e32 v112, v112, v115
	s_nop 1
	v_add_f32_dpp v112, v112, v112 quad_perm:[1,0,3,2] row_mask:0xf bank_mask:0xf bound_ctrl:1
	s_nop 1
	v_add_f32_dpp v112, v112, v112 quad_perm:[2,3,0,1] row_mask:0xf bank_mask:0xf bound_ctrl:1
	s_nop 1
	v_add_f32_dpp v112, v112, v112 row_half_mirror row_mask:0xf bank_mask:0xf bound_ctrl:1
	s_nop 1
	v_add_f32_dpp v112, v112, v112 row_mirror row_mask:0xf bank_mask:0xf bound_ctrl:1
	s_nop 1
	ds_swizzle_b32 v113, v112 offset:swizzle(SWAP,16)
	s_waitcnt lgkmcnt(0)
	v_add_f32_e32 v112, v112, v113
	v_mov_b32_e32 v113, v112
	s_nop 1
	v_permlane32_swap_b32_e32 v112, v113
	v_add_f32_e32 v112, v112, v113
	v_fmamk_f32 v112, v112, 0x3a800000, v224
	v_rsq_f32_e32 v112, v112
	s_waitcnt vmcnt(0)
	v_mul_f32_e32 v162, v162, v112
	v_mul_f32_e32 v163, v163, v112
	v_mul_f32_e32 v164, v164, v112
	v_mul_f32_e32 v165, v165, v112
	v_mul_f32_e32 v166, v166, v112
	v_mul_f32_e32 v167, v167, v112
	v_mul_f32_e32 v168, v168, v112
	v_mul_f32_e32 v169, v169, v112
	v_mul_f32_e32 v170, v170, v112
	v_mul_f32_e32 v171, v171, v112
	v_mul_f32_e32 v172, v172, v112
	v_mul_f32_e32 v173, v173, v112
	v_mul_f32_e32 v174, v174, v112
	v_mul_f32_e32 v175, v175, v112
	v_mul_f32_e32 v176, v176, v112
	v_mul_f32_e32 v177, v177, v112
	v_mul_f32_e32 v162, v80, v162
	v_mul_f32_e32 v163, v81, v163
	v_mul_f32_e32 v164, v82, v164
	v_mul_f32_e32 v165, v83, v165
	v_mul_f32_e32 v166, v84, v166
	v_mul_f32_e32 v167, v85, v167
	v_mul_f32_e32 v168, v86, v168
	v_mul_f32_e32 v169, v87, v169
	v_mul_f32_e32 v170, v88, v170
	v_mul_f32_e32 v171, v89, v171
	v_mul_f32_e32 v172, v90, v172
	v_mul_f32_e32 v173, v91, v173
	v_mul_f32_e32 v174, v92, v174
	v_mul_f32_e32 v175, v93, v175
	v_mul_f32_e32 v176, v94, v176
	v_mul_f32_e32 v177, v95, v177
	v_add_f32_e32 v96, 1.0, v96
	v_add_f32_e32 v97, 1.0, v97
	v_add_f32_e32 v98, 1.0, v98
	v_add_f32_e32 v99, 1.0, v99
	v_add_f32_e32 v100, 1.0, v100
	v_add_f32_e32 v101, 1.0, v101
	v_add_f32_e32 v102, 1.0, v102
	v_add_f32_e32 v103, 1.0, v103
	v_add_f32_e32 v104, 1.0, v104
	v_add_f32_e32 v105, 1.0, v105
	v_add_f32_e32 v106, 1.0, v106
	v_add_f32_e32 v107, 1.0, v107
	v_add_f32_e32 v108, 1.0, v108
	v_add_f32_e32 v109, 1.0, v109
	v_add_f32_e32 v110, 1.0, v110
	v_add_f32_e32 v111, 1.0, v111
	v_fma_f32 v162, v96, v162, v178
	v_fma_f32 v163, v97, v163, v179
	v_fma_f32 v164, v98, v164, v180
	v_fma_f32 v165, v99, v165, v181
	v_fma_f32 v166, v100, v166, v182
	v_fma_f32 v167, v101, v167, v183
	v_fma_f32 v168, v102, v168, v184
	v_fma_f32 v169, v103, v169, v185
	v_fma_f32 v170, v104, v170, v186
	v_fma_f32 v171, v105, v171, v187
	v_fma_f32 v172, v106, v172, v188
	v_fma_f32 v173, v107, v173, v189
	v_fma_f32 v174, v108, v174, v190
	v_fma_f32 v175, v109, v175, v191
	v_fma_f32 v176, v110, v176, v192
	v_fma_f32 v177, v111, v177, v193
	v_cvt_pk_f16_f32 v114, v162, v163
	v_cvt_pk_f16_f32 v115, v164, v165
	v_cvt_pk_f16_f32 v116, v166, v167
	v_cvt_pk_f16_f32 v117, v168, v169
	v_cvt_pk_f16_f32 v118, v170, v171
	v_cvt_pk_f16_f32 v119, v172, v173
	v_cvt_pk_f16_f32 v120, v174, v175
	v_cvt_pk_f16_f32 v121, v176, v177
	global_store_dwordx2 v128, v[114:115], s[24:25]
	global_store_dwordx2 v128, v[116:117], s[24:25] offset:512
	global_store_dwordx2 v128, v[118:119], s[24:25] offset:1024
	global_store_dwordx2 v128, v[120:121], s[24:25] offset:1536
	s_add_i32 s3, s3, s2
	s_branch .Lrn2_exit
; DI int TIDX() { int t = threadIdx.x; asm volatile("" : "+v"(t)); return t; }
; DI int BIDX() { int b = blockIdx.x; asm volatile("" : "+s"(b)); return b; }
; DI void rows_norm_mod(const P& p, const float* xlat, const float* xctx, int l, const float* gain, int sh_idx, int sc_idx,
;                       h16* dst, int nrows) {
;   const int lane = TIDX() & 63;
;   const int gw = BIDX() * 4 + (TIDX() >> 6), nw = gridDim.x * 4;
;   const float* mod = (const float*)(p.ws + OFF_MOD);
;   for (int row = gw; row < nrows; row += nw) {
;     const float* xr = row < TL ? xlat + (size_t)row * 1024 : xctx + (size_t)(row - TL) * 1024;
;     const int mrow = row < TL ? (row >> 12) : 8;
;     const float* mr = mod + ((size_t)l * 9 + mrow) * 6144;
;     f32x4 v[4];
;     float ss = 0.f;
; #pragma unroll
;     for (int i = 0; i < 4; ++i) {
;       v[i] = *(const f32x4*)(xr + lane * 4 + 256 * i);
;       ss += v[i].x * v[i].x + v[i].y * v[i].y + v[i].z * v[i].z + v[i].w * v[i].w;
;     }
;     ss = wave_sum(ss);
;     const float rstd = rsqrtf(ss * (1.f / 1024.f) + EPS);
; #pragma unroll
;     for (int i = 0; i < 4; ++i) {
;       const int c = lane * 4 + 256 * i;
;       f32x4 g = *(const f32x4*)(gain + c), sc = *(const f32x4*)(mr + sc_idx * 1024 + c), sh = *(const f32x4*)(mr + sh_idx * 1024 + c);
;       h16x4 o;
;       o.x = (h16)(v[i].x * rstd * g.x * (1.f + sc.x) + sh.x);
;       o.y = (h16)(v[i].y * rstd * g.y * (1.f + sc.y) + sh.y);
;       o.z = (h16)(v[i].z * rstd * g.z * (1.f + sc.z) + sh.z);
;       o.w = (h16)(v[i].w * rstd * g.w * (1.f + sc.w) + sh.w);
;       *(h16x4*)(dst + (size_t)row * 1024 + c) = o;
;     }
;   }
; }
.Lrn2_tail2:
	s_waitcnt vmcnt(8)
	v_mul_f32_e32 v112, v163, v163
	v_mul_f32_e32 v113, v167, v167
	v_mul_f32_e32 v114, v171, v171
	v_mul_f32_e32 v115, v175, v175
	v_fmac_f32_e32 v112, v162, v162
	v_fmac_f32_e32 v113, v166, v166
	v_fmac_f32_e32 v114, v170, v170
	v_fmac_f32_e32 v115, v174, v174
	v_fmac_f32_e32 v112, v164, v164
	v_fmac_f32_e32 v113, v168, v168
	v_fmac_f32_e32 v114, v172, v172
	v_fmac_f32_e32 v115, v176, v176
	v_fmac_f32_e32 v112, v165, v165
	v_fmac_f32_e32 v113, v169, v169
	v_fmac_f32_e32 v114, v173, v173
	v_fmac_f32_e32 v115, v177, v177
	v_add_f32_e32 v112, v112, v113
	v_add_f32_e32 v112, v112, v114
	v_add_f32_e32 v112, v112, v115
	s_nop 1
	v_add_f32_dpp v112, v112, v112 quad_perm:[1,0,3,2] row_mask:0xf bank_mask:0xf bound_ctrl:1
	s_nop 1
	v_add_f32_dpp v112, v112, v112 quad_perm:[2,3,0,1] row_mask:0xf bank_mask:0xf bound_ctrl:1
	s_nop 1
	v_add_f32_dpp v112, v112, v112 row_half_mirror row_mask:0xf bank_mask:0xf bound_ctrl:1
	s_nop 1
	v_add_f32_dpp v112, v112, v112 row_mirror row_mask:0xf bank_mask:0xf bound_ctrl:1
	s_nop 1
	ds_swizzle_b32 v113, v112 offset:swizzle(SWAP,16)
	s_waitcnt lgkmcnt(0)
	v_add_f32_e32 v112, v112, v113
	v_mov_b32_e32 v113, v112
	s_nop 1
	v_permlane32_swap_b32_e32 v112, v113
	v_add_f32_e32 v112, v112, v113
	v_fmamk_f32 v112, v112, 0x3a800000, v224
	v_rsq_f32_e32 v112, v112
	s_waitcnt vmcnt(0)
	v_mul_f32_e32 v162, v162, v112
	v_mul_f32_e32 v163, v163, v112
	v_mul_f32_e32 v164, v164, v112
	v_mul_f32_e32 v165, v165, v112
	v_mul_f32_e32 v166, v166, v112
	v_mul_f32_e32 v167, v167, v112
	v_mul_f32_e32 v168, v168, v112
	v_mul_f32_e32 v169, v169, v112
	v_mul_f32_e32 v170, v170, v112
	v_mul_f32_e32 v171, v171, v112
	v_mul_f32_e32 v172, v172, v112
	v_mul_f32_e32 v173, v173, v112
	v_mul_f32_e32 v174, v174, v112
	v_mul_f32_e32 v175, v175, v112
	v_mul_f32_e32 v176, v176, v112
	v_mul_f32_e32 v177, v177, v112
	v_mul_f32_e32 v162, v80, v162
	v_mul_f32_e32 v163, v81, v163
	v_mul_f32_e32 v164, v82, v164
	v_mul_f32_e32 v165, v83, v165
	v_mul_f32_e32 v166, v84, v166
	v_mul_f32_e32 v167, v85, v167
	v_mul_f32_e32 v168, v86, v168
	v_mul_f32_e32 v169, v87, v169
	v_mul_f32_e32 v170, v88, v170
	v_mul_f32_e32 v171, v89, v171
	v_mul_f32_e32 v172, v90, v172
	v_mul_f32_e32 v173, v91, v173
	v_mul_f32_e32 v174, v92, v174
	v_mul_f32_e32 v175, v93, v175
	v_mul_f32_e32 v176, v94, v176
	v_mul_f32_e32 v177, v95, v177
	v_add_f32_e32 v96, 1.0, v96
	v_add_f32_e32 v97, 1.0, v97
	v_add_f32_e32 v98, 1.0, v98
	v_add_f32_e32 v99, 1.0, v99
	v_add_f32_e32 v100, 1.0, v100
	v_add_f32_e32 v101, 1.0, v101
	v_add_f32_e32 v102, 1.0, v102
	v_add_f32_e32 v103, 1.0, v103
	v_add_f32_e32 v104, 1.0, v104
	v_add_f32_e32 v105, 1.0, v105
	v_add_f32_e32 v106, 1.0, v106
	v_add_f32_e32 v107, 1.0, v107
	v_add_f32_e32 v108, 1.0, v108
	v_add_f32_e32 v109, 1.0, v109
	v_add_f32_e32 v110, 1.0, v110
	v_add_f32_e32 v111, 1.0, v111
	v_fma_f32 v162, v96, v162, v178
	v_fma_f32 v163, v97, v163, v179
	v_fma_f32 v164, v98, v164, v180
	v_fma_f32 v165, v99, v165, v181
	v_fma_f32 v166, v100, v166, v182
	v_fma_f32 v167, v101, v167, v183
	v_fma_f32 v168, v102, v168, v184
	v_fma_f32 v169, v103, v169, v185
	v_fma_f32 v170, v104, v170, v186
	v_fma_f32 v171, v105, v171, v187
	v_fma_f32 v172, v106, v172, v188
	v_fma_f32 v173, v107, v173, v189
	v_fma_f32 v174, v108, v174, v190
	v_fma_f32 v175, v109, v175, v191
	v_fma_f32 v176, v110, v176, v192
	v_fma_f32 v177, v111, v177, v193
	v_cvt_pk_f16_f32 v114, v162, v163
	v_cvt_pk_f16_f32 v115, v164, v165
	v_cvt_pk_f16_f32 v116, v166, v167
	v_cvt_pk_f16_f32 v117, v168, v169
	v_cvt_pk_f16_f32 v118, v170, v171
	v_cvt_pk_f16_f32 v119, v172, v173
	v_cvt_pk_f16_f32 v120, v174, v175
	v_cvt_pk_f16_f32 v121, v176, v177
	global_store_dwordx2 v128, v[114:115], s[24:25]
	global_store_dwordx2 v128, v[116:117], s[24:25] offset:512
	global_store_dwordx2 v128, v[118:119], s[24:25] offset:1024
	global_store_dwordx2 v128, v[120:121], s[24:25] offset:1536
	s_add_i32 s3, s3, s2
	s_cmp_lt_i32 s3, 0x8800
	s_cbranch_scc0 .Lrn2_exit
; DI int TIDX() { int t = threadIdx.x; asm volatile("" : "+v"(t)); return t; }
; DI int BIDX() { int b = blockIdx.x; asm volatile("" : "+s"(b)); return b; }
; DI void rows_norm_mod(const P& p, const float* xlat, const float* xctx, int l, const float* gain, int sh_idx, int sc_idx,
;                       h16* dst, int nrows) {
;   const int lane = TIDX() & 63;
;   const int gw = BIDX() * 4 + (TIDX() >> 6), nw = gridDim.x * 4;
;   const float* mod = (const float*)(p.ws + OFF_MOD);
;   for (int row = gw; row < nrows; row += nw) {
;     const float* xr = row < TL ? xlat + (size_t)row * 1024 : xctx + (size_t)(row - TL) * 1024;
;     const int mrow = row < TL ? (row >> 12) : 8;
;     const float* mr = mod + ((size_t)l * 9 + mrow) * 6144;
;     f32x4 v[4];
;     float ss = 0.f;
; #pragma unroll
;     for (int i = 0; i < 4; ++i) {
;       v[i] = *(const f32x4*)(xr + lane * 4 + 256 * i);
;       ss += v[i].x * v[i].x + v[i].y * v[i].y + v[i].z * v[i].z + v[i].w * v[i].w;
;     }
;     ss = wave_sum(ss);
;     const float rstd = rsqrtf(ss * (1.f / 1024.f) + EPS);
; #pragma unroll
;     for (int i = 0; i < 4; ++i) {
;       const int c = lane * 4 + 256 * i;
;       f32x4 g = *(const f32x4*)(gain + c), sc = *(const f32x4*)(mr + sc_idx * 1024 + c), sh = *(const f32x4*)(mr + sh_idx * 1024 + c);
;       h16x4 o;
;       o.x = (h16)(v[i].x * rstd * g.x * (1.f + sc.x) + sh.x);
;       o.y = (h16)(v[i].y * rstd * g.y * (1.f + sc.y) + sh.y);
;       o.z = (h16)(v[i].z * rstd * g.z * (1.f + sc.z) + sh.z);
;       o.w = (h16)(v[i].w * rstd * g.w * (1.f + sc.w) + sh.w);
;       *(h16x4*)(dst + (size_t)row * 1024 + c) = o;
;     }
;   }
; }
	s_lshr_b32 s6, s3, 12
	s_cmp_lt_u32 s3, 0x8000
	s_cselect_b32 s6, s6, 8
	s_mul_i32 s6, s6, 0x6000
	s_add_u32 s22, s4, s6
	s_addc_u32 s23, s5, 0
	s_add_u32 s32, s22, 0x1000
	s_addc_u32 s33, s23, 0
	s_lshl_b32 s6, s3, 11
	s_add_u32 s24, s18, s6
	s_addc_u32 s25, s19, 0
	global_load_dwordx4 v[96:99], v0, s[32:33]
	global_load_dwordx4 v[100:103], v0, s[32:33] offset:1024
	global_load_dwordx4 v[104:107], v0, s[32:33] offset:2048
	global_load_dwordx4 v[108:111], v0, s[32:33] offset:3072
	global_load_dwordx4 v[178:181], v0, s[22:23]
	global_load_dwordx4 v[182:185], v0, s[22:23] offset:1024
	global_load_dwordx4 v[186:189], v0, s[22:23] offset:2048
	global_load_dwordx4 v[190:193], v0, s[22:23] offset:3072
	s_waitcnt vmcnt(8)
	v_mul_f32_e32 v112, v3, v3
	v_mul_f32_e32 v113, v7, v7
	v_mul_f32_e32 v114, v11, v11
	v_mul_f32_e32 v115, v15, v15
	v_fmac_f32_e32 v112, v2, v2
	v_fmac_f32_e32 v113, v6, v6
	v_fmac_f32_e32 v114, v10, v10
	v_fmac_f32_e32 v115, v14, v14
	v_fmac_f32_e32 v112, v4, v4
	v_fmac_f32_e32 v113, v8, v8
	v_fmac_f32_e32 v114, v12, v12
	v_fmac_f32_e32 v115, v16, v16
	v_fmac_f32_e32 v112, v5, v5
	v_fmac_f32_e32 v113, v9, v9
	v_fmac_f32_e32 v114, v13, v13
	v_fmac_f32_e32 v115, v17, v17
	v_add_f32_e32 v112, v112, v113
	v_add_f32_e32 v112, v112, v114
	v_add_f32_e32 v112, v112, v115
	s_nop 1
	v_add_f32_dpp v112, v112, v112 quad_perm:[1,0,3,2] row_mask:0xf bank_mask:0xf bound_ctrl:1
	s_nop 1
	v_add_f32_dpp v112, v112, v112 quad_perm:[2,3,0,1] row_mask:0xf bank_mask:0xf bound_ctrl:1
	s_nop 1
	v_add_f32_dpp v112, v112, v112 row_half_mirror row_mask:0xf bank_mask:0xf bound_ctrl:1
	s_nop 1
	v_add_f32_dpp v112, v112, v112 row_mirror row_mask:0xf bank_mask:0xf bound_ctrl:1
	s_nop 1
	ds_swizzle_b32 v113, v112 offset:swizzle(SWAP,16)
	s_waitcnt lgkmcnt(0)
	v_add_f32_e32 v112, v112, v113
	v_mov_b32_e32 v113, v112
	s_nop 1
	v_permlane32_swap_b32_e32 v112, v113
	v_add_f32_e32 v112, v112, v113
	v_fmamk_f32 v112, v112, 0x3a800000, v224
	v_rsq_f32_e32 v112, v112
	s_waitcnt vmcnt(0)
	v_mul_f32_e32 v2, v2, v112
	v_mul_f32_e32 v3, v3, v112
	v_mul_f32_e32 v4, v4, v112
	v_mul_f32_e32 v5, v5, v112
	v_mul_f32_e32 v6, v6, v112
	v_mul_f32_e32 v7, v7, v112
	v_mul_f32_e32 v8, v8, v112
	v_mul_f32_e32 v9, v9, v112
	v_mul_f32_e32 v10, v10, v112
	v_mul_f32_e32 v11, v11, v112
	v_mul_f32_e32 v12, v12, v112
	v_mul_f32_e32 v13, v13, v112
	v_mul_f32_e32 v14, v14, v112
	v_mul_f32_e32 v15, v15, v112
	v_mul_f32_e32 v16, v16, v112
	v_mul_f32_e32 v17, v17, v112
	v_mul_f32_e32 v2, v80, v2
	v_mul_f32_e32 v3, v81, v3
	v_mul_f32_e32 v4, v82, v4
	v_mul_f32_e32 v5, v83, v5
	v_mul_f32_e32 v6, v84, v6
	v_mul_f32_e32 v7, v85, v7
	v_mul_f32_e32 v8, v86, v8
	v_mul_f32_e32 v9, v87, v9
	v_mul_f32_e32 v10, v88, v10
	v_mul_f32_e32 v11, v89, v11
	v_mul_f32_e32 v12, v90, v12
	v_mul_f32_e32 v13, v91, v13
	v_mul_f32_e32 v14, v92, v14
	v_mul_f32_e32 v15, v93, v15
	v_mul_f32_e32 v16, v94, v16
	v_mul_f32_e32 v17, v95, v17
	v_add_f32_e32 v96, 1.0, v96
	v_add_f32_e32 v97, 1.0, v97
	v_add_f32_e32 v98, 1.0, v98
	v_add_f32_e32 v99, 1.0, v99
	v_add_f32_e32 v100, 1.0, v100
	v_add_f32_e32 v101, 1.0, v101
	v_add_f32_e32 v102, 1.0, v102
	v_add_f32_e32 v103, 1.0, v103
	v_add_f32_e32 v104, 1.0, v104
	v_add_f32_e32 v105, 1.0, v105
	v_add_f32_e32 v106, 1.0, v106
	v_add_f32_e32 v107, 1.0, v107
	v_add_f32_e32 v108, 1.0, v108
	v_add_f32_e32 v109, 1.0, v109
	v_add_f32_e32 v110, 1.0, v110
	v_add_f32_e32 v111, 1.0, v111
	v_fma_f32 v2, v96, v2, v178
	v_fma_f32 v3, v97, v3, v179
	v_fma_f32 v4, v98, v4, v180
	v_fma_f32 v5, v99, v5, v181
	v_fma_f32 v6, v100, v6, v182
	v_fma_f32 v7, v101, v7, v183
	v_fma_f32 v8, v102, v8, v184
	v_fma_f32 v9, v103, v9, v185
	v_fma_f32 v10, v104, v10, v186
	v_fma_f32 v11, v105, v11, v187
	v_fma_f32 v12, v106, v12, v188
	v_fma_f32 v13, v107, v13, v189
	v_fma_f32 v14, v108, v14, v190
	v_fma_f32 v15, v109, v15, v191
	v_fma_f32 v16, v110, v16, v192
	v_fma_f32 v17, v111, v17, v193
	v_cvt_pk_f16_f32 v114, v2, v3
	v_cvt_pk_f16_f32 v115, v4, v5
	v_cvt_pk_f16_f32 v116, v6, v7
	v_cvt_pk_f16_f32 v117, v8, v9
	v_cvt_pk_f16_f32 v118, v10, v11
	v_cvt_pk_f16_f32 v119, v12, v13
	v_cvt_pk_f16_f32 v120, v14, v15
	v_cvt_pk_f16_f32 v121, v16, v17
	global_store_dwordx2 v128, v[114:115], s[24:25]
	global_store_dwordx2 v128, v[116:117], s[24:25] offset:512
	global_store_dwordx2 v128, v[118:119], s[24:25] offset:1024
	global_store_dwordx2 v128, v[120:121], s[24:25] offset:1536
	s_add_i32 s3, s3, s2
	s_branch .Lrn2_exit
